# K-loop LDS-DMA loads issued in SGPR-base + VGPR-offset form in 8 GEMM loops (16 v_lshl_add_u64 per iteration removed from the load segments)
# baseline (speedup 1.0000x reference)
; #define PG8_STAGE(bufoff, gbase, voff) do { _Pragma("unroll") for (int _i = 0; _i < 2; ++_i) \
;         __builtin_amdgcn_global_load_lds((const unsigned*)((const char*)(gbase) + (voff)[_i]), (PG8_LAS unsigned*)(lds + (bufoff) + ldsw + _i * 8192), 16, 0, 0); } while (0)
; #define PG8_LDA(dst, b, h) do { _Pragma("unroll") for (int m = 0; m < 4; ++m) _Pragma("unroll") for (int k = 0; k < 2; ++k) dst[m][k] = *(const PG8_LAS bf16x8*)(lds + PG8_SA(b, h) + aoff + m * 2048 + k * 1024); } while (0)
; #define PG8_LDB(dst, b, h) do { _Pragma("unroll") for (int n = 0; n < 2; ++n) _Pragma("unroll") for (int k = 0; k < 2; ++k) dst[n][k] = *(const PG8_LAS bf16x8*)(lds + PG8_SB(b, h) + boff + n * 2048 + k * 1024); } while (0)
; #define PG8_MMA(ai, bj, At, Bt) do { __builtin_amdgcn_s_setprio(1); _Pragma("unroll") for (int m = 0; m < 4; ++m) _Pragma("unroll") for (int n = 0; n < 2; ++n) _Pragma("unroll") for (int k = 0; k < 2; ++k) \
;         acc[ai][bj][m][n] = __builtin_amdgcn_mfma_f32_16x16x32_bf16(Bt[n][k], At[m][k], acc[ai][bj][m][n], 0, 0, 0); __builtin_amdgcn_s_setprio(0); } while (0)
; #define PG8_WAIT_V(n) asm volatile("s_waitcnt vmcnt(" #n ")" ::: "memory")
; #define PG8_WAIT_L(n) asm volatile("s_waitcnt lgkmcnt(" #n ")" ::: "memory")
; template <class Epi, class Sched, bool ALIGN_EPI = false, bool SP2 = false>
; __device__ __forceinline__ void gemm_phase(PG8_LAS unsigned char* lds, const Gemm g, const Sched& S, const Epi& E) {
;     ...
;             const bool last = (t == nt - 2);
;             const char* a1 = cA + (size_t)(t + 1) * kstep;
;             const char* a2 = last ? nA : cA + (size_t)(t + 2) * kstep; const char* b2 = last ? nB : cB + (size_t)(t + 2) * kstep;
;             const char* a3 = a2 + kstep; const char* b3 = b2 + kstep;
;             if (last && has_next) S.a_ready(nxt);
;             if constexpr (SP2) {
;             PG8_LDB(B0, 0, 0); PG8_LDB(B1, 0, 1); PG8_SCHED; PG8_LDA(At, 0, 0); PG8_STAGE(PG8_SA(1, 1), a1 + hstep, voffA);
;             PG8_WAIT_V(8); PG8_WAIT_L(0); PG8_BAR; PG8_MMA(0, 0, At, B0); PG8_MMA(0, 1, At, B1); PG8_BAR; PG8_SCHED;
;             PG8_LDA(At, 0, 1); PG8_STAGE(PG8_SB(0, 0), b2, voffB); PG8_STAGE(PG8_SB(0, 1), b2 + hstep, voffB); PG8_STAGE(PG8_SA(0, 0), a2, voffA);
;             PG8_WAIT_V(8); PG8_WAIT_L(0); PG8_BAR; PG8_MMA(1, 0, At, B0); PG8_MMA(1, 1, At, B1); PG8_BAR; PG8_SCHED;
.LBB0_204:
	ds_read_b128 v[152:155], v147
	ds_read_b128 v[156:159], v147 offset:1024
	ds_read_b128 v[160:163], v147 offset:2048
	ds_read_b128 v[164:167], v147 offset:3072
	ds_read_b128 v[168:171], v148
	ds_read_b128 v[172:175], v148 offset:1024
	ds_read_b128 v[176:179], v148 offset:2048
	ds_read_b128 v[180:183], v148 offset:3072
	s_add_u32 s24, s22, 0xfff80080
	s_addc_u32 s25, s23, -1
	s_cmp_eq_u32 s51, 28
	s_cselect_b32 s27, s17, s25
	s_cselect_b32 s26, s47, s24
	s_cselect_b32 s25, s15, s50
	s_cselect_b32 s24, s48, s49
	s_add_i32 m0, s29, 0xc000
	ds_read_b128 v[184:187], v149
	ds_read_b128 v[188:191], v149 offset:1024
	ds_read_b128 v[192:195], v149 offset:2048
	ds_read_b128 v[196:199], v149 offset:3072
	ds_read_b128 v[200:203], v149 offset:4096
	ds_read_b128 v[206:209], v149 offset:5120
	ds_read_b128 v[210:213], v149 offset:6144
	ds_read_b128 v[214:217], v149 offset:7168
	s_cmp_lg_u32 s100, 0
	s_cbranch_scc1 .Lgr_p1_0
	global_load_lds_dwordx4 v136, s[22:23]
	s_add_i32 m0, s29, 0xe000
	s_nop 0
	global_load_lds_dwordx4 v138, s[22:23]
	s_waitcnt vmcnt(8)
.Lgr_p1_0:
	s_waitcnt lgkmcnt(0)
	s_barrier
	s_setprio 1
	s_waitcnt lgkmcnt(0)
	v_mfma_f32_16x16x32_bf16 v[116:119], v[152:155], v[184:187], v[116:119]
	v_mfma_f32_16x16x32_bf16 v[112:115], v[160:163], v[184:187], v[112:115]
	v_mfma_f32_16x16x32_bf16 v[108:111], v[152:155], v[192:195], v[108:111]
	v_mfma_f32_16x16x32_bf16 v[100:103], v[160:163], v[192:195], v[100:103]
	v_mfma_f32_16x16x32_bf16 v[92:95], v[152:155], v[200:203], v[92:95]
	v_mfma_f32_16x16x32_bf16 v[84:87], v[160:163], v[200:203], v[84:87]
	v_mfma_f32_16x16x32_bf16 v[76:79], v[152:155], v[210:213], v[76:79]
	v_mfma_f32_16x16x32_bf16 v[68:71], v[160:163], v[210:213], v[68:71]
	v_mfma_f32_16x16x32_bf16 v[116:119], v[156:159], v[188:191], v[116:119]
	v_mfma_f32_16x16x32_bf16 v[112:115], v[164:167], v[188:191], v[112:115]
	v_mfma_f32_16x16x32_bf16 v[108:111], v[156:159], v[196:199], v[108:111]
	v_mfma_f32_16x16x32_bf16 v[100:103], v[164:167], v[196:199], v[100:103]
	v_mfma_f32_16x16x32_bf16 v[92:95], v[156:159], v[206:209], v[92:95]
	v_mfma_f32_16x16x32_bf16 v[84:87], v[164:167], v[206:209], v[84:87]
	v_mfma_f32_16x16x32_bf16 v[76:79], v[156:159], v[214:217], v[76:79]
	v_mfma_f32_16x16x32_bf16 v[68:71], v[164:167], v[214:217], v[68:71]
	s_setprio 0
	s_setprio 1
	v_mfma_f32_16x16x32_bf16 v[124:127], v[168:171], v[184:187], v[124:127]
	v_mfma_f32_16x16x32_bf16 v[120:123], v[176:179], v[184:187], v[120:123]
	v_mfma_f32_16x16x32_bf16 v[104:107], v[168:171], v[192:195], v[104:107]
	v_mfma_f32_16x16x32_bf16 v[96:99], v[176:179], v[192:195], v[96:99]
	v_mfma_f32_16x16x32_bf16 v[88:91], v[168:171], v[200:203], v[88:91]
	v_mfma_f32_16x16x32_bf16 v[80:83], v[176:179], v[200:203], v[80:83]
	v_mfma_f32_16x16x32_bf16 v[72:75], v[168:171], v[210:213], v[72:75]
	v_mfma_f32_16x16x32_bf16 v[64:67], v[176:179], v[210:213], v[64:67]
	v_mfma_f32_16x16x32_bf16 v[124:127], v[172:175], v[188:191], v[124:127]
	v_mfma_f32_16x16x32_bf16 v[120:123], v[180:183], v[188:191], v[120:123]
	v_mfma_f32_16x16x32_bf16 v[104:107], v[172:175], v[196:199], v[104:107]
	v_mfma_f32_16x16x32_bf16 v[96:99], v[180:183], v[196:199], v[96:99]
	v_mfma_f32_16x16x32_bf16 v[88:91], v[172:175], v[206:209], v[88:91]
	v_mfma_f32_16x16x32_bf16 v[80:83], v[180:183], v[206:209], v[80:83]
	v_mfma_f32_16x16x32_bf16 v[72:75], v[172:175], v[214:217], v[72:75]
	v_mfma_f32_16x16x32_bf16 v[64:67], v[180:183], v[214:217], v[64:67]
	s_setprio 0
	s_barrier
	s_add_i32 s52, s43, s0
	s_add_u32 vcc_lo, s24, 0x80
	s_addc_u32 vcc_hi, s25, 0
	s_mov_b32 m0, s52
	ds_read_b128 v[184:187], v149 offset:16384
	ds_read_b128 v[188:191], v149 offset:17408
	ds_read_b128 v[192:195], v149 offset:18432
	ds_read_b128 v[196:199], v149 offset:19456
	ds_read_b128 v[200:203], v149 offset:20480
	ds_read_b128 v[206:209], v149 offset:21504
	ds_read_b128 v[210:213], v149 offset:22528
	ds_read_b128 v[214:217], v149 offset:23552
	global_load_lds_dwordx4 v132, s[24:25]
	s_add_i32 m0, s52, 0x2000
	s_add_u32 s52, s24, 0x80000
	s_addc_u32 s53, s25, 0
	s_add_i32 s54, s44, s0
	global_load_lds_dwordx4 v128, s[24:25]
	s_mov_b32 m0, s54
	s_nop 0
	global_load_lds_dwordx4 v132, s[52:53]
	s_add_i32 m0, s54, 0x2000
	s_nop 0
	global_load_lds_dwordx4 v128, s[52:53]
	s_add_u32 s98, s26, 0x80
	s_addc_u32 s99, s27, 0
	s_mov_b32 m0, s29
	s_nop 0
	global_load_lds_dwordx4 v134, s[26:27]
	s_mov_b32 m0, s30
	s_nop 0
	global_load_lds_dwordx4 v130, s[26:27]
	s_cmp_lg_u32 s100, 0
	s_cbranch_scc1 .Lgr_p1_1
	s_waitcnt vmcnt(8)
; #define PG8_STAGE(bufoff, gbase, voff) do { _Pragma("unroll") for (int _i = 0; _i < 2; ++_i) \
;         __builtin_amdgcn_global_load_lds((const unsigned*)((const char*)(gbase) + (voff)[_i]), (PG8_LAS unsigned*)(lds + (bufoff) + ldsw + _i * 8192), 16, 0, 0); } while (0)
; #define PG8_LDA(dst, b, h) do { _Pragma("unroll") for (int m = 0; m < 4; ++m) _Pragma("unroll") for (int k = 0; k < 2; ++k) dst[m][k] = *(const PG8_LAS bf16x8*)(lds + PG8_SA(b, h) + aoff + m * 2048 + k * 1024); } while (0)
; #define PG8_LDB(dst, b, h) do { _Pragma("unroll") for (int n = 0; n < 2; ++n) _Pragma("unroll") for (int k = 0; k < 2; ++k) dst[n][k] = *(const PG8_LAS bf16x8*)(lds + PG8_SB(b, h) + boff + n * 2048 + k * 1024); } while (0)
; #define PG8_MMA(ai, bj, At, Bt) do { __builtin_amdgcn_s_setprio(1); _Pragma("unroll") for (int m = 0; m < 4; ++m) _Pragma("unroll") for (int n = 0; n < 2; ++n) _Pragma("unroll") for (int k = 0; k < 2; ++k) \
;         acc[ai][bj][m][n] = __builtin_amdgcn_mfma_f32_16x16x32_bf16(Bt[n][k], At[m][k], acc[ai][bj][m][n], 0, 0, 0); __builtin_amdgcn_s_setprio(0); } while (0)
; #define PG8_WAIT_V(n) asm volatile("s_waitcnt vmcnt(" #n ")" ::: "memory")
; #define PG8_WAIT_L(n) asm volatile("s_waitcnt lgkmcnt(" #n ")" ::: "memory")
; #define PG8_BAR __builtin_amdgcn_s_barrier()
; #define PG8_SCHED __builtin_amdgcn_sched_barrier(0)
; template <class Epi, class Sched, bool ALIGN_EPI = false, bool SP2 = false>
; __device__ __forceinline__ void gemm_phase(PG8_LAS unsigned char* lds, const Gemm g, const Sched& S, const Epi& E) {
;     ...
;             PG8_WAIT_V(8); PG8_WAIT_L(0); PG8_BAR; PG8_MMA(1, 0, At, B0); PG8_MMA(1, 1, At, B1); PG8_BAR; PG8_SCHED;
;             PG8_LDB(B0, 1, 0); PG8_LDB(B1, 1, 1); PG8_SCHED; PG8_LDA(At, 1, 0); PG8_STAGE(PG8_SA(0, 1), a2 + hstep, voffA);
;             PG8_WAIT_V(8); PG8_WAIT_L(0); PG8_BAR; PG8_MMA(0, 0, At, B0); PG8_MMA(0, 1, At, B1); PG8_BAR; PG8_SCHED;
.Lgr_p1_1:
	s_waitcnt lgkmcnt(0)
	s_barrier
	s_setprio 1
	s_waitcnt lgkmcnt(0)
	v_mfma_f32_16x16x32_bf16 v[60:63], v[152:155], v[184:187], v[60:63]
	v_mfma_f32_16x16x32_bf16 v[52:55], v[160:163], v[184:187], v[52:55]
	v_mfma_f32_16x16x32_bf16 v[44:47], v[152:155], v[192:195], v[44:47]
	v_mfma_f32_16x16x32_bf16 v[36:39], v[160:163], v[192:195], v[36:39]
	v_mfma_f32_16x16x32_bf16 v[28:31], v[152:155], v[200:203], v[28:31]
	v_mfma_f32_16x16x32_bf16 v[20:23], v[160:163], v[200:203], v[20:23]
	v_mfma_f32_16x16x32_bf16 v[12:15], v[152:155], v[210:213], v[12:15]
	v_mfma_f32_16x16x32_bf16 v[4:7], v[160:163], v[210:213], v[4:7]
	v_mfma_f32_16x16x32_bf16 v[60:63], v[156:159], v[188:191], v[60:63]
	v_mfma_f32_16x16x32_bf16 v[52:55], v[164:167], v[188:191], v[52:55]
	v_mfma_f32_16x16x32_bf16 v[44:47], v[156:159], v[196:199], v[44:47]
	v_mfma_f32_16x16x32_bf16 v[36:39], v[164:167], v[196:199], v[36:39]
	v_mfma_f32_16x16x32_bf16 v[28:31], v[156:159], v[206:209], v[28:31]
	v_mfma_f32_16x16x32_bf16 v[20:23], v[164:167], v[206:209], v[20:23]
	v_mfma_f32_16x16x32_bf16 v[12:15], v[156:159], v[214:217], v[12:15]
	v_mfma_f32_16x16x32_bf16 v[4:7], v[164:167], v[214:217], v[4:7]
	s_setprio 0
	s_setprio 1
	v_mfma_f32_16x16x32_bf16 v[56:59], v[168:171], v[184:187], v[56:59]
	v_mfma_f32_16x16x32_bf16 v[48:51], v[176:179], v[184:187], v[48:51]
	v_mfma_f32_16x16x32_bf16 v[40:43], v[168:171], v[192:195], v[40:43]
	v_mfma_f32_16x16x32_bf16 v[32:35], v[176:179], v[192:195], v[32:35]
	v_mfma_f32_16x16x32_bf16 v[24:27], v[168:171], v[200:203], v[24:27]
	v_mfma_f32_16x16x32_bf16 v[16:19], v[176:179], v[200:203], v[16:19]
	v_mfma_f32_16x16x32_bf16 v[8:11], v[168:171], v[210:213], v[8:11]
	v_mfma_f32_16x16x32_bf16 v[0:3], v[176:179], v[210:213], v[0:3]
	v_mfma_f32_16x16x32_bf16 v[56:59], v[172:175], v[188:191], v[56:59]
	v_mfma_f32_16x16x32_bf16 v[48:51], v[180:183], v[188:191], v[48:51]
	v_mfma_f32_16x16x32_bf16 v[40:43], v[172:175], v[196:199], v[40:43]
	v_mfma_f32_16x16x32_bf16 v[32:35], v[180:183], v[196:199], v[32:35]
	v_mfma_f32_16x16x32_bf16 v[24:27], v[172:175], v[206:209], v[24:27]
	v_mfma_f32_16x16x32_bf16 v[16:19], v[180:183], v[206:209], v[16:19]
	v_mfma_f32_16x16x32_bf16 v[8:11], v[172:175], v[214:217], v[8:11]
	v_mfma_f32_16x16x32_bf16 v[0:3], v[180:183], v[214:217], v[0:3]
	s_setprio 0
	s_barrier
	s_add_i32 s52, 0, 0x18000
	v_add_u32_e32 v151, s52, v145
	s_add_i32 s53, 0, 0x1c000
	ds_read_b128 v[152:155], v151
	ds_read_b128 v[156:159], v151 offset:1024
	ds_read_b128 v[160:163], v151 offset:2048
	ds_read_b128 v[164:167], v151 offset:3072
	v_add_u32_e32 v151, s53, v145
	ds_read_b128 v[168:171], v151
	ds_read_b128 v[172:175], v151 offset:1024
	ds_read_b128 v[176:179], v151 offset:2048
	ds_read_b128 v[180:183], v151 offset:3072
	s_add_u32 s26, s26, 0x80000
	s_addc_u32 s27, s27, 0
	s_mov_b32 m0, s31
	ds_read_b128 v[184:187], v149 offset:32768
	ds_read_b128 v[188:191], v149 offset:33792
	ds_read_b128 v[192:195], v149 offset:34816
	ds_read_b128 v[196:199], v149 offset:35840
	ds_read_b128 v[200:203], v149 offset:36864
	ds_read_b128 v[206:209], v149 offset:37888
	ds_read_b128 v[210:213], v149 offset:38912
	ds_read_b128 v[214:217], v149 offset:39936
	global_load_lds_dwordx4 v134, s[26:27]
	s_mov_b32 m0, s33
	s_nop 0
	global_load_lds_dwordx4 v130, s[26:27]
	s_cmp_lg_u32 s100, 0
	s_cbranch_scc1 .Lgr_p1_2
	s_waitcnt vmcnt(8)
; #define PG8_STAGE(bufoff, gbase, voff) do { _Pragma("unroll") for (int _i = 0; _i < 2; ++_i) \
;         __builtin_amdgcn_global_load_lds((const unsigned*)((const char*)(gbase) + (voff)[_i]), (PG8_LAS unsigned*)(lds + (bufoff) + ldsw + _i * 8192), 16, 0, 0); } while (0)
; #define PG8_LDA(dst, b, h) do { _Pragma("unroll") for (int m = 0; m < 4; ++m) _Pragma("unroll") for (int k = 0; k < 2; ++k) dst[m][k] = *(const PG8_LAS bf16x8*)(lds + PG8_SA(b, h) + aoff + m * 2048 + k * 1024); } while (0)
; #define PG8_MMA(ai, bj, At, Bt) do { __builtin_amdgcn_s_setprio(1); _Pragma("unroll") for (int m = 0; m < 4; ++m) _Pragma("unroll") for (int n = 0; n < 2; ++n) _Pragma("unroll") for (int k = 0; k < 2; ++k) \
;         acc[ai][bj][m][n] = __builtin_amdgcn_mfma_f32_16x16x32_bf16(Bt[n][k], At[m][k], acc[ai][bj][m][n], 0, 0, 0); __builtin_amdgcn_s_setprio(0); } while (0)
; #define PG8_WAIT_V(n) asm volatile("s_waitcnt vmcnt(" #n ")" ::: "memory")
; #define PG8_WAIT_L(n) asm volatile("s_waitcnt lgkmcnt(" #n ")" ::: "memory")
; #define PG8_BAR __builtin_amdgcn_s_barrier()
; #define PG8_SCHED __builtin_amdgcn_sched_barrier(0)
; template <class Epi, class Sched, bool ALIGN_EPI = false, bool SP2 = false>
; __device__ __forceinline__ void gemm_phase(PG8_LAS unsigned char* lds, const Gemm g, const Sched& S, const Epi& E) {
;     ...
;             PG8_WAIT_V(8); PG8_WAIT_L(0); PG8_BAR; PG8_MMA(0, 0, At, B0); PG8_MMA(0, 1, At, B1); PG8_BAR; PG8_SCHED;
;             PG8_LDA(At, 1, 1); PG8_STAGE(PG8_SB(1, 0), b3, voffB); PG8_STAGE(PG8_SB(1, 1), b3 + hstep, voffB); PG8_STAGE(PG8_SA(1, 0), a3, voffA);
;             PG8_WAIT_V(8); PG8_WAIT_L(0); PG8_BAR; PG8_MMA(1, 0, At, B0); PG8_MMA(1, 1, At, B1); PG8_BAR; PG8_SCHED;
.Lgr_p1_2:
	s_waitcnt lgkmcnt(0)
	s_barrier
	s_setprio 1
	s_waitcnt lgkmcnt(0)
	v_mfma_f32_16x16x32_bf16 v[116:119], v[152:155], v[184:187], v[116:119]
	v_mfma_f32_16x16x32_bf16 v[112:115], v[160:163], v[184:187], v[112:115]
	v_mfma_f32_16x16x32_bf16 v[108:111], v[152:155], v[192:195], v[108:111]
	v_mfma_f32_16x16x32_bf16 v[100:103], v[160:163], v[192:195], v[100:103]
	v_mfma_f32_16x16x32_bf16 v[92:95], v[152:155], v[200:203], v[92:95]
	v_mfma_f32_16x16x32_bf16 v[84:87], v[160:163], v[200:203], v[84:87]
	v_mfma_f32_16x16x32_bf16 v[76:79], v[152:155], v[210:213], v[76:79]
	v_mfma_f32_16x16x32_bf16 v[68:71], v[160:163], v[210:213], v[68:71]
	v_mfma_f32_16x16x32_bf16 v[116:119], v[156:159], v[188:191], v[116:119]
	v_mfma_f32_16x16x32_bf16 v[112:115], v[164:167], v[188:191], v[112:115]
	v_mfma_f32_16x16x32_bf16 v[108:111], v[156:159], v[196:199], v[108:111]
	v_mfma_f32_16x16x32_bf16 v[100:103], v[164:167], v[196:199], v[100:103]
	v_mfma_f32_16x16x32_bf16 v[92:95], v[156:159], v[206:209], v[92:95]
	v_mfma_f32_16x16x32_bf16 v[84:87], v[164:167], v[206:209], v[84:87]
	v_mfma_f32_16x16x32_bf16 v[76:79], v[156:159], v[214:217], v[76:79]
	v_mfma_f32_16x16x32_bf16 v[68:71], v[164:167], v[214:217], v[68:71]
	s_setprio 0
	s_setprio 1
	v_mfma_f32_16x16x32_bf16 v[124:127], v[168:171], v[184:187], v[124:127]
	v_mfma_f32_16x16x32_bf16 v[120:123], v[176:179], v[184:187], v[120:123]
	v_mfma_f32_16x16x32_bf16 v[104:107], v[168:171], v[192:195], v[104:107]
	v_mfma_f32_16x16x32_bf16 v[96:99], v[176:179], v[192:195], v[96:99]
	v_mfma_f32_16x16x32_bf16 v[88:91], v[168:171], v[200:203], v[88:91]
	v_mfma_f32_16x16x32_bf16 v[80:83], v[176:179], v[200:203], v[80:83]
	v_mfma_f32_16x16x32_bf16 v[72:75], v[168:171], v[210:213], v[72:75]
	v_mfma_f32_16x16x32_bf16 v[64:67], v[176:179], v[210:213], v[64:67]
	v_mfma_f32_16x16x32_bf16 v[124:127], v[172:175], v[188:191], v[124:127]
	v_mfma_f32_16x16x32_bf16 v[120:123], v[180:183], v[188:191], v[120:123]
	v_mfma_f32_16x16x32_bf16 v[104:107], v[172:175], v[196:199], v[104:107]
	v_mfma_f32_16x16x32_bf16 v[96:99], v[180:183], v[196:199], v[96:99]
	v_mfma_f32_16x16x32_bf16 v[88:91], v[172:175], v[206:209], v[88:91]
	v_mfma_f32_16x16x32_bf16 v[80:83], v[180:183], v[206:209], v[80:83]
	v_mfma_f32_16x16x32_bf16 v[72:75], v[172:175], v[214:217], v[72:75]
	v_mfma_f32_16x16x32_bf16 v[64:67], v[180:183], v[214:217], v[64:67]
	s_setprio 0
	s_barrier
	s_add_i32 s26, s52, s0
	s_mov_b32 m0, s26
	ds_read_b128 v[184:187], v149 offset:49152
	ds_read_b128 v[188:191], v149 offset:50176
	ds_read_b128 v[192:195], v149 offset:51200
	ds_read_b128 v[196:199], v149 offset:52224
	ds_read_b128 v[200:203], v149 offset:53248
	ds_read_b128 v[206:209], v149 offset:54272
	ds_read_b128 v[210:213], v149 offset:55296
	ds_read_b128 v[214:217], v149 offset:56320
	global_load_lds_dwordx4 v132, vcc
	s_add_i32 m0, s26, 0x2000
	s_add_u32 s24, s24, 0x80080
	s_addc_u32 s25, s25, 0
	s_add_i32 s26, s53, s0
	global_load_lds_dwordx4 v128, vcc
	s_mov_b32 m0, s26
	s_nop 0
	global_load_lds_dwordx4 v132, s[24:25]
	s_add_i32 m0, s26, 0x2000
	s_nop 0
	global_load_lds_dwordx4 v128, s[24:25]
	s_mov_b32 m0, s35
	s_nop 0
	global_load_lds_dwordx4 v134, s[98:99]
	s_mov_b32 m0, s40
	s_nop 0
	global_load_lds_dwordx4 v130, s[98:99]
	s_waitcnt vmcnt(8)
	s_waitcnt lgkmcnt(0)
	s_barrier
	s_setprio 1
	s_waitcnt lgkmcnt(0)
	v_mfma_f32_16x16x32_bf16 v[60:63], v[152:155], v[184:187], v[60:63]
	v_mfma_f32_16x16x32_bf16 v[52:55], v[160:163], v[184:187], v[52:55]
	v_mfma_f32_16x16x32_bf16 v[44:47], v[152:155], v[192:195], v[44:47]
	v_mfma_f32_16x16x32_bf16 v[36:39], v[160:163], v[192:195], v[36:39]
	v_mfma_f32_16x16x32_bf16 v[28:31], v[152:155], v[200:203], v[28:31]
	v_mfma_f32_16x16x32_bf16 v[20:23], v[160:163], v[200:203], v[20:23]
	v_mfma_f32_16x16x32_bf16 v[12:15], v[152:155], v[210:213], v[12:15]
	v_mfma_f32_16x16x32_bf16 v[4:7], v[160:163], v[210:213], v[4:7]
	v_mfma_f32_16x16x32_bf16 v[60:63], v[156:159], v[188:191], v[60:63]
	v_mfma_f32_16x16x32_bf16 v[52:55], v[164:167], v[188:191], v[52:55]
	v_mfma_f32_16x16x32_bf16 v[44:47], v[156:159], v[196:199], v[44:47]
	v_mfma_f32_16x16x32_bf16 v[36:39], v[164:167], v[196:199], v[36:39]
	v_mfma_f32_16x16x32_bf16 v[28:31], v[156:159], v[206:209], v[28:31]
	v_mfma_f32_16x16x32_bf16 v[20:23], v[164:167], v[206:209], v[20:23]
	v_mfma_f32_16x16x32_bf16 v[12:15], v[156:159], v[214:217], v[12:15]
	v_mfma_f32_16x16x32_bf16 v[4:7], v[164:167], v[214:217], v[4:7]
	s_setprio 0
	s_setprio 1
	v_mfma_f32_16x16x32_bf16 v[56:59], v[168:171], v[184:187], v[56:59]
	v_mfma_f32_16x16x32_bf16 v[48:51], v[176:179], v[184:187], v[48:51]
	v_mfma_f32_16x16x32_bf16 v[40:43], v[168:171], v[192:195], v[40:43]
	v_mfma_f32_16x16x32_bf16 v[32:35], v[176:179], v[192:195], v[32:35]
	v_mfma_f32_16x16x32_bf16 v[24:27], v[168:171], v[200:203], v[24:27]
	v_mfma_f32_16x16x32_bf16 v[16:19], v[176:179], v[200:203], v[16:19]
	v_mfma_f32_16x16x32_bf16 v[8:11], v[168:171], v[210:213], v[8:11]
	v_mfma_f32_16x16x32_bf16 v[0:3], v[176:179], v[210:213], v[0:3]
	v_mfma_f32_16x16x32_bf16 v[56:59], v[172:175], v[188:191], v[56:59]
	v_mfma_f32_16x16x32_bf16 v[48:51], v[180:183], v[188:191], v[48:51]
	v_mfma_f32_16x16x32_bf16 v[40:43], v[172:175], v[196:199], v[40:43]
	v_mfma_f32_16x16x32_bf16 v[32:35], v[180:183], v[196:199], v[32:35]
	v_mfma_f32_16x16x32_bf16 v[24:27], v[172:175], v[206:209], v[24:27]
	v_mfma_f32_16x16x32_bf16 v[16:19], v[180:183], v[206:209], v[16:19]
	v_mfma_f32_16x16x32_bf16 v[8:11], v[172:175], v[214:217], v[8:11]
	v_mfma_f32_16x16x32_bf16 v[0:3], v[180:183], v[214:217], v[0:3]
	s_setprio 0
	s_barrier
	s_mov_b32 s100, 0
	s_add_i32 s51, s51, 2
	s_add_u32 s22, s22, 0x100
	s_addc_u32 s23, s23, 0
	s_add_u32 s49, s49, 0x100
	s_addc_u32 s50, s50, 0
	s_cmp_gt_u32 s51, 29
	s_cbranch_scc0 .LBB0_204
	s_and_b64 vcc, exec, s[12:13]
	s_cbranch_vccz .LBB0_207
	s_barrier

; #define PG8_STAGE(bufoff, gbase, voff) do { _Pragma("unroll") for (int _i = 0; _i < 2; ++_i) \
;         __builtin_amdgcn_global_load_lds((const unsigned*)((const char*)(gbase) + (voff)[_i]), (PG8_LAS unsigned*)(lds + (bufoff) + ldsw + _i * 8192), 16, 0, 0); } while (0)
; #define PG8_LDA(dst, b, h) do { _Pragma("unroll") for (int m = 0; m < 4; ++m) _Pragma("unroll") for (int k = 0; k < 2; ++k) dst[m][k] = *(const PG8_LAS bf16x8*)(lds + PG8_SA(b, h) + aoff + m * 2048 + k * 1024); } while (0)
; #define PG8_LDB(dst, b, h) do { _Pragma("unroll") for (int n = 0; n < 2; ++n) _Pragma("unroll") for (int k = 0; k < 2; ++k) dst[n][k] = *(const PG8_LAS bf16x8*)(lds + PG8_SB(b, h) + boff + n * 2048 + k * 1024); } while (0)
; #define PG8_MMA(ai, bj, At, Bt) do { __builtin_amdgcn_s_setprio(1); _Pragma("unroll") for (int m = 0; m < 4; ++m) _Pragma("unroll") for (int n = 0; n < 2; ++n) _Pragma("unroll") for (int k = 0; k < 2; ++k) \
;         acc[ai][bj][m][n] = __builtin_amdgcn_mfma_f32_16x16x32_bf16(Bt[n][k], At[m][k], acc[ai][bj][m][n], 0, 0, 0); __builtin_amdgcn_s_setprio(0); } while (0)
; #define PG8_WAIT_V(n) asm volatile("s_waitcnt vmcnt(" #n ")" ::: "memory")
; #define PG8_WAIT_L(n) asm volatile("s_waitcnt lgkmcnt(" #n ")" ::: "memory")
; template <class Epi, class Sched, bool ALIGN_EPI = false, bool SP2 = false>
; __device__ __forceinline__ void gemm_phase(PG8_LAS unsigned char* lds, const Gemm g, const Sched& S, const Epi& E) {
;     ...
;             const bool last = (t == nt - 2);
;             const char* a1 = cA + (size_t)(t + 1) * kstep;
;             const char* a2 = last ? nA : cA + (size_t)(t + 2) * kstep; const char* b2 = last ? nB : cB + (size_t)(t + 2) * kstep;
;             const char* a3 = a2 + kstep; const char* b3 = b2 + kstep;
;             if (last && has_next) S.a_ready(nxt);
;             if constexpr (SP2) {
;             PG8_LDB(B0, 0, 0); PG8_LDB(B1, 0, 1); PG8_SCHED; PG8_LDA(At, 0, 0); PG8_STAGE(PG8_SA(1, 1), a1 + hstep, voffA);
;             PG8_WAIT_V(8); PG8_WAIT_L(0); PG8_BAR; PG8_MMA(0, 0, At, B0); PG8_MMA(0, 1, At, B1); PG8_BAR; PG8_SCHED;
;             PG8_LDA(At, 0, 1); PG8_STAGE(PG8_SB(0, 0), b2, voffB); PG8_STAGE(PG8_SB(0, 1), b2 + hstep, voffB); PG8_STAGE(PG8_SA(0, 0), a2, voffA);
;             PG8_WAIT_V(8); PG8_WAIT_L(0); PG8_BAR; PG8_MMA(1, 0, At, B0); PG8_MMA(1, 1, At, B1); PG8_BAR; PG8_SCHED;
.LBB0_285:
	ds_read_b128 v[128:131], v208
	ds_read_b128 v[132:135], v208 offset:1024
	ds_read_b128 v[136:139], v208 offset:2048
	ds_read_b128 v[140:143], v208 offset:3072
	ds_read_b128 v[144:147], v209
	ds_read_b128 v[148:151], v209 offset:1024
	ds_read_b128 v[152:155], v209 offset:2048
	ds_read_b128 v[156:159], v209 offset:3072
	s_add_u32 s22, s20, 0xffea0080
	s_addc_u32 s23, s21, -1
	s_cmpk_eq_i32 s48, 0x54
	s_cselect_b32 s25, s7, s23
	s_cselect_b32 s24, s6, s22
	s_cselect_b32 s23, s19, s47
	s_cselect_b32 s22, s18, s46
	s_add_i32 m0, s1, 0xc000
	ds_read_b128 v[160:163], v210
	ds_read_b128 v[164:167], v210 offset:1024
	ds_read_b128 v[168:171], v210 offset:2048
	ds_read_b128 v[172:175], v210 offset:3072
	ds_read_b128 v[192:195], v210 offset:4096
	ds_read_b128 v[196:199], v210 offset:5120
	ds_read_b128 v[200:203], v210 offset:6144
	ds_read_b128 v[212:215], v210 offset:7168
	global_load_lds_dwordx4 v184, s[20:21]
	s_add_i32 m0, s1, 0xe000
	s_nop 0
	global_load_lds_dwordx4 v186, s[20:21]
	s_waitcnt vmcnt(8)
	s_waitcnt lgkmcnt(0)
	s_barrier
	s_setprio 1
	s_waitcnt lgkmcnt(0)
	v_mfma_f32_16x16x32_bf16 v[124:127], v[128:131], v[160:163], v[124:127]
	v_mfma_f32_16x16x32_bf16 v[120:123], v[136:139], v[160:163], v[120:123]
	v_mfma_f32_16x16x32_bf16 v[108:111], v[128:131], v[168:171], v[108:111]
	v_mfma_f32_16x16x32_bf16 v[104:107], v[136:139], v[168:171], v[104:107]
	v_mfma_f32_16x16x32_bf16 v[92:95], v[128:131], v[192:195], v[92:95]
	v_mfma_f32_16x16x32_bf16 v[88:91], v[136:139], v[192:195], v[88:91]
	v_mfma_f32_16x16x32_bf16 v[76:79], v[128:131], v[200:203], v[76:79]
	v_mfma_f32_16x16x32_bf16 v[72:75], v[136:139], v[200:203], v[72:75]
	v_mfma_f32_16x16x32_bf16 v[124:127], v[132:135], v[164:167], v[124:127]
	v_mfma_f32_16x16x32_bf16 v[120:123], v[140:143], v[164:167], v[120:123]
	v_mfma_f32_16x16x32_bf16 v[108:111], v[132:135], v[172:175], v[108:111]
	v_mfma_f32_16x16x32_bf16 v[104:107], v[140:143], v[172:175], v[104:107]
	v_mfma_f32_16x16x32_bf16 v[92:95], v[132:135], v[196:199], v[92:95]
	v_mfma_f32_16x16x32_bf16 v[88:91], v[140:143], v[196:199], v[88:91]
	v_mfma_f32_16x16x32_bf16 v[76:79], v[132:135], v[212:215], v[76:79]
	v_mfma_f32_16x16x32_bf16 v[72:75], v[140:143], v[212:215], v[72:75]
	s_setprio 0
	s_setprio 1
	v_mfma_f32_16x16x32_bf16 v[116:119], v[144:147], v[160:163], v[116:119]
	v_mfma_f32_16x16x32_bf16 v[112:115], v[152:155], v[160:163], v[112:115]
	v_mfma_f32_16x16x32_bf16 v[100:103], v[144:147], v[168:171], v[100:103]
	v_mfma_f32_16x16x32_bf16 v[96:99], v[152:155], v[168:171], v[96:99]
	v_mfma_f32_16x16x32_bf16 v[84:87], v[144:147], v[192:195], v[84:87]
	v_mfma_f32_16x16x32_bf16 v[80:83], v[152:155], v[192:195], v[80:83]
	v_mfma_f32_16x16x32_bf16 v[68:71], v[144:147], v[200:203], v[68:71]
	v_mfma_f32_16x16x32_bf16 v[64:67], v[152:155], v[200:203], v[64:67]
	v_mfma_f32_16x16x32_bf16 v[116:119], v[148:151], v[164:167], v[116:119]
	v_mfma_f32_16x16x32_bf16 v[112:115], v[156:159], v[164:167], v[112:115]
	v_mfma_f32_16x16x32_bf16 v[100:103], v[148:151], v[172:175], v[100:103]
	v_mfma_f32_16x16x32_bf16 v[96:99], v[156:159], v[172:175], v[96:99]
	v_mfma_f32_16x16x32_bf16 v[84:87], v[148:151], v[196:199], v[84:87]
	v_mfma_f32_16x16x32_bf16 v[80:83], v[156:159], v[196:199], v[80:83]
	v_mfma_f32_16x16x32_bf16 v[68:71], v[148:151], v[212:215], v[68:71]
	v_mfma_f32_16x16x32_bf16 v[64:67], v[156:159], v[212:215], v[64:67]
	s_setprio 0
	s_barrier
	s_add_i32 s49, s40, s0
	s_add_u32 vcc_lo, s22, 0x80
	s_addc_u32 vcc_hi, s23, 0
	s_mov_b32 m0, s49
	ds_read_b128 v[160:163], v210 offset:16384
	ds_read_b128 v[164:167], v210 offset:17408
	ds_read_b128 v[168:171], v210 offset:18432
	ds_read_b128 v[172:175], v210 offset:19456
	ds_read_b128 v[192:195], v210 offset:20480
	ds_read_b128 v[196:199], v210 offset:21504
	ds_read_b128 v[200:203], v210 offset:22528
	ds_read_b128 v[212:215], v210 offset:23552
	global_load_lds_dwordx4 v178, s[22:23]
	s_add_i32 m0, s49, 0x2000
	s_add_u32 s50, s22, 0x160000
	s_addc_u32 s51, s23, 0
	s_add_i32 s49, s41, s0
	global_load_lds_dwordx4 v182, s[22:23]
	s_mov_b32 m0, s49
	s_nop 0
	global_load_lds_dwordx4 v178, s[50:51]
	s_add_i32 m0, s49, 0x2000
	s_nop 0
	global_load_lds_dwordx4 v182, s[50:51]
	s_add_u32 s98, s24, 0x80
	s_addc_u32 s99, s25, 0
	s_mov_b32 m0, s1
	s_nop 0
	global_load_lds_dwordx4 v176, s[24:25]
	s_mov_b32 m0, s26
	s_nop 0
	global_load_lds_dwordx4 v180, s[24:25]
	s_waitcnt vmcnt(8)
	s_waitcnt lgkmcnt(0)
	s_barrier
	s_setprio 1
	s_waitcnt lgkmcnt(0)
	v_mfma_f32_16x16x32_bf16 v[60:63], v[128:131], v[160:163], v[60:63]
	v_mfma_f32_16x16x32_bf16 v[56:59], v[136:139], v[160:163], v[56:59]
	v_mfma_f32_16x16x32_bf16 v[44:47], v[128:131], v[168:171], v[44:47]
	v_mfma_f32_16x16x32_bf16 v[40:43], v[136:139], v[168:171], v[40:43]
	v_mfma_f32_16x16x32_bf16 v[28:31], v[128:131], v[192:195], v[28:31]
	v_mfma_f32_16x16x32_bf16 v[24:27], v[136:139], v[192:195], v[24:27]
	v_mfma_f32_16x16x32_bf16 v[12:15], v[128:131], v[200:203], v[12:15]
	v_mfma_f32_16x16x32_bf16 v[8:11], v[136:139], v[200:203], v[8:11]
	v_mfma_f32_16x16x32_bf16 v[60:63], v[132:135], v[164:167], v[60:63]
	v_mfma_f32_16x16x32_bf16 v[56:59], v[140:143], v[164:167], v[56:59]
	v_mfma_f32_16x16x32_bf16 v[44:47], v[132:135], v[172:175], v[44:47]
	v_mfma_f32_16x16x32_bf16 v[40:43], v[140:143], v[172:175], v[40:43]
	v_mfma_f32_16x16x32_bf16 v[28:31], v[132:135], v[196:199], v[28:31]
	v_mfma_f32_16x16x32_bf16 v[24:27], v[140:143], v[196:199], v[24:27]
	v_mfma_f32_16x16x32_bf16 v[12:15], v[132:135], v[212:215], v[12:15]
	v_mfma_f32_16x16x32_bf16 v[8:11], v[140:143], v[212:215], v[8:11]
	s_setprio 0
	s_setprio 1
	v_mfma_f32_16x16x32_bf16 v[52:55], v[144:147], v[160:163], v[52:55]
	v_mfma_f32_16x16x32_bf16 v[48:51], v[152:155], v[160:163], v[48:51]
	v_mfma_f32_16x16x32_bf16 v[36:39], v[144:147], v[168:171], v[36:39]
	v_mfma_f32_16x16x32_bf16 v[32:35], v[152:155], v[168:171], v[32:35]
	v_mfma_f32_16x16x32_bf16 v[20:23], v[144:147], v[192:195], v[20:23]
	v_mfma_f32_16x16x32_bf16 v[16:19], v[152:155], v[192:195], v[16:19]
	v_mfma_f32_16x16x32_bf16 v[4:7], v[144:147], v[200:203], v[4:7]
	v_mfma_f32_16x16x32_bf16 v[0:3], v[152:155], v[200:203], v[0:3]
	v_mfma_f32_16x16x32_bf16 v[52:55], v[148:151], v[164:167], v[52:55]
	v_mfma_f32_16x16x32_bf16 v[48:51], v[156:159], v[164:167], v[48:51]
	v_mfma_f32_16x16x32_bf16 v[36:39], v[148:151], v[172:175], v[36:39]
	v_mfma_f32_16x16x32_bf16 v[32:35], v[156:159], v[172:175], v[32:35]
	v_mfma_f32_16x16x32_bf16 v[20:23], v[148:151], v[196:199], v[20:23]
	v_mfma_f32_16x16x32_bf16 v[16:19], v[156:159], v[196:199], v[16:19]
	v_mfma_f32_16x16x32_bf16 v[4:7], v[148:151], v[212:215], v[4:7]
	v_mfma_f32_16x16x32_bf16 v[0:3], v[156:159], v[212:215], v[0:3]
	s_setprio 0
	s_barrier
; #define PG8_STAGE(bufoff, gbase, voff) do { _Pragma("unroll") for (int _i = 0; _i < 2; ++_i) \
;         __builtin_amdgcn_global_load_lds((const unsigned*)((const char*)(gbase) + (voff)[_i]), (PG8_LAS unsigned*)(lds + (bufoff) + ldsw + _i * 8192), 16, 0, 0); } while (0)
; #define PG8_LDA(dst, b, h) do { _Pragma("unroll") for (int m = 0; m < 4; ++m) _Pragma("unroll") for (int k = 0; k < 2; ++k) dst[m][k] = *(const PG8_LAS bf16x8*)(lds + PG8_SA(b, h) + aoff + m * 2048 + k * 1024); } while (0)
; #define PG8_LDB(dst, b, h) do { _Pragma("unroll") for (int n = 0; n < 2; ++n) _Pragma("unroll") for (int k = 0; k < 2; ++k) dst[n][k] = *(const PG8_LAS bf16x8*)(lds + PG8_SB(b, h) + boff + n * 2048 + k * 1024); } while (0)
; #define PG8_MMA(ai, bj, At, Bt) do { __builtin_amdgcn_s_setprio(1); _Pragma("unroll") for (int m = 0; m < 4; ++m) _Pragma("unroll") for (int n = 0; n < 2; ++n) _Pragma("unroll") for (int k = 0; k < 2; ++k) \
;         acc[ai][bj][m][n] = __builtin_amdgcn_mfma_f32_16x16x32_bf16(Bt[n][k], At[m][k], acc[ai][bj][m][n], 0, 0, 0); __builtin_amdgcn_s_setprio(0); } while (0)
; #define PG8_WAIT_V(n) asm volatile("s_waitcnt vmcnt(" #n ")" ::: "memory")
; #define PG8_WAIT_L(n) asm volatile("s_waitcnt lgkmcnt(" #n ")" ::: "memory")
; #define PG8_BAR __builtin_amdgcn_s_barrier()
; #define PG8_SCHED __builtin_amdgcn_sched_barrier(0)
; template <class Epi, class Sched, bool ALIGN_EPI = false, bool SP2 = false>
; __device__ __forceinline__ void gemm_phase(PG8_LAS unsigned char* lds, const Gemm g, const Sched& S, const Epi& E) {
;     ...
;             PG8_LDB(B0, 1, 0); PG8_LDB(B1, 1, 1); PG8_SCHED; PG8_LDA(At, 1, 0); PG8_STAGE(PG8_SA(0, 1), a2 + hstep, voffA);
;             PG8_WAIT_V(8); PG8_WAIT_L(0); PG8_BAR; PG8_MMA(0, 0, At, B0); PG8_MMA(0, 1, At, B1); PG8_BAR; PG8_SCHED;
;             PG8_LDA(At, 1, 1); PG8_STAGE(PG8_SB(1, 0), b3, voffB); PG8_STAGE(PG8_SB(1, 1), b3 + hstep, voffB); PG8_STAGE(PG8_SA(1, 0), a3, voffA);
;             PG8_WAIT_V(8); PG8_WAIT_L(0); PG8_BAR; PG8_MMA(1, 0, At, B0); PG8_MMA(1, 1, At, B1); PG8_BAR; PG8_SCHED;
	s_add_i32 s49, 0, 0x18000
	s_add_i32 s50, 0, 0x1c000
	v_add_u32_e32 v140, s49, v206
	v_add_u32_e32 v156, s50, v206
	ds_read_b128 v[128:131], v140
	ds_read_b128 v[132:135], v140 offset:1024
	ds_read_b128 v[136:139], v140 offset:2048
	ds_read_b128 v[140:143], v140 offset:3072
	ds_read_b128 v[144:147], v156
	ds_read_b128 v[148:151], v156 offset:1024
	ds_read_b128 v[152:155], v156 offset:2048
	ds_read_b128 v[156:159], v156 offset:3072
	s_add_u32 s24, s24, 0x160000
	s_addc_u32 s25, s25, 0
	s_mov_b32 m0, s27
	ds_read_b128 v[160:163], v210 offset:32768
	ds_read_b128 v[164:167], v210 offset:33792
	ds_read_b128 v[168:171], v210 offset:34816
	ds_read_b128 v[172:175], v210 offset:35840
	ds_read_b128 v[192:195], v210 offset:36864
	ds_read_b128 v[196:199], v210 offset:37888
	ds_read_b128 v[200:203], v210 offset:38912
	ds_read_b128 v[212:215], v210 offset:39936
	global_load_lds_dwordx4 v176, s[24:25]
	s_mov_b32 m0, s28
	s_nop 0
	global_load_lds_dwordx4 v180, s[24:25]
	s_waitcnt vmcnt(8)
	s_waitcnt lgkmcnt(0)
	s_barrier
	s_setprio 1
	s_waitcnt lgkmcnt(0)
	v_mfma_f32_16x16x32_bf16 v[124:127], v[128:131], v[160:163], v[124:127]
	v_mfma_f32_16x16x32_bf16 v[120:123], v[136:139], v[160:163], v[120:123]
	v_mfma_f32_16x16x32_bf16 v[108:111], v[128:131], v[168:171], v[108:111]
	v_mfma_f32_16x16x32_bf16 v[104:107], v[136:139], v[168:171], v[104:107]
	v_mfma_f32_16x16x32_bf16 v[92:95], v[128:131], v[192:195], v[92:95]
	v_mfma_f32_16x16x32_bf16 v[88:91], v[136:139], v[192:195], v[88:91]
	v_mfma_f32_16x16x32_bf16 v[76:79], v[128:131], v[200:203], v[76:79]
	v_mfma_f32_16x16x32_bf16 v[72:75], v[136:139], v[200:203], v[72:75]
	v_mfma_f32_16x16x32_bf16 v[124:127], v[132:135], v[164:167], v[124:127]
	v_mfma_f32_16x16x32_bf16 v[120:123], v[140:143], v[164:167], v[120:123]
	v_mfma_f32_16x16x32_bf16 v[108:111], v[132:135], v[172:175], v[108:111]
	v_mfma_f32_16x16x32_bf16 v[104:107], v[140:143], v[172:175], v[104:107]
	v_mfma_f32_16x16x32_bf16 v[92:95], v[132:135], v[196:199], v[92:95]
	v_mfma_f32_16x16x32_bf16 v[88:91], v[140:143], v[196:199], v[88:91]
	v_mfma_f32_16x16x32_bf16 v[76:79], v[132:135], v[212:215], v[76:79]
	v_mfma_f32_16x16x32_bf16 v[72:75], v[140:143], v[212:215], v[72:75]
	s_setprio 0
	s_setprio 1
	v_mfma_f32_16x16x32_bf16 v[116:119], v[144:147], v[160:163], v[116:119]
	v_mfma_f32_16x16x32_bf16 v[112:115], v[152:155], v[160:163], v[112:115]
	v_mfma_f32_16x16x32_bf16 v[100:103], v[144:147], v[168:171], v[100:103]
	v_mfma_f32_16x16x32_bf16 v[96:99], v[152:155], v[168:171], v[96:99]
	v_mfma_f32_16x16x32_bf16 v[84:87], v[144:147], v[192:195], v[84:87]
	v_mfma_f32_16x16x32_bf16 v[80:83], v[152:155], v[192:195], v[80:83]
	v_mfma_f32_16x16x32_bf16 v[68:71], v[144:147], v[200:203], v[68:71]
	v_mfma_f32_16x16x32_bf16 v[64:67], v[152:155], v[200:203], v[64:67]
	v_mfma_f32_16x16x32_bf16 v[116:119], v[148:151], v[164:167], v[116:119]
	v_mfma_f32_16x16x32_bf16 v[112:115], v[156:159], v[164:167], v[112:115]
	v_mfma_f32_16x16x32_bf16 v[100:103], v[148:151], v[172:175], v[100:103]
	v_mfma_f32_16x16x32_bf16 v[96:99], v[156:159], v[172:175], v[96:99]
	v_mfma_f32_16x16x32_bf16 v[84:87], v[148:151], v[196:199], v[84:87]
	v_mfma_f32_16x16x32_bf16 v[80:83], v[156:159], v[196:199], v[80:83]
	v_mfma_f32_16x16x32_bf16 v[68:71], v[148:151], v[212:215], v[68:71]
	v_mfma_f32_16x16x32_bf16 v[64:67], v[156:159], v[212:215], v[64:67]
	s_setprio 0
	s_barrier
	s_add_i32 s24, s49, s0
	s_mov_b32 m0, s24
	ds_read_b128 v[160:163], v210 offset:49152
	ds_read_b128 v[164:167], v210 offset:50176
	ds_read_b128 v[168:171], v210 offset:51200
	ds_read_b128 v[172:175], v210 offset:52224
	ds_read_b128 v[192:195], v210 offset:53248
	ds_read_b128 v[196:199], v210 offset:54272
	ds_read_b128 v[200:203], v210 offset:55296
	ds_read_b128 v[212:215], v210 offset:56320
	global_load_lds_dwordx4 v178, vcc
	s_add_i32 m0, s24, 0x2000
	s_add_u32 s22, s22, 0x160080
	s_addc_u32 s23, s23, 0
	s_add_i32 s24, s50, s0
	global_load_lds_dwordx4 v182, vcc
	s_mov_b32 m0, s24
	s_nop 0
	global_load_lds_dwordx4 v178, s[22:23]
	s_add_i32 m0, s24, 0x2000
	s_nop 0
	global_load_lds_dwordx4 v182, s[22:23]
	s_mov_b32 m0, s30
	s_nop 0
	global_load_lds_dwordx4 v176, s[98:99]
	s_mov_b32 m0, s31
	s_nop 0
	global_load_lds_dwordx4 v180, s[98:99]
	s_waitcnt vmcnt(8)
	s_waitcnt lgkmcnt(0)
	s_barrier
	s_setprio 1
	s_waitcnt lgkmcnt(0)
	v_mfma_f32_16x16x32_bf16 v[60:63], v[128:131], v[160:163], v[60:63]
	v_mfma_f32_16x16x32_bf16 v[56:59], v[136:139], v[160:163], v[56:59]
	v_mfma_f32_16x16x32_bf16 v[44:47], v[128:131], v[168:171], v[44:47]
	v_mfma_f32_16x16x32_bf16 v[40:43], v[136:139], v[168:171], v[40:43]
	v_mfma_f32_16x16x32_bf16 v[28:31], v[128:131], v[192:195], v[28:31]
	v_mfma_f32_16x16x32_bf16 v[24:27], v[136:139], v[192:195], v[24:27]
	v_mfma_f32_16x16x32_bf16 v[12:15], v[128:131], v[200:203], v[12:15]
	v_mfma_f32_16x16x32_bf16 v[8:11], v[136:139], v[200:203], v[8:11]
	v_mfma_f32_16x16x32_bf16 v[60:63], v[132:135], v[164:167], v[60:63]
	v_mfma_f32_16x16x32_bf16 v[56:59], v[140:143], v[164:167], v[56:59]
	v_mfma_f32_16x16x32_bf16 v[44:47], v[132:135], v[172:175], v[44:47]
	v_mfma_f32_16x16x32_bf16 v[40:43], v[140:143], v[172:175], v[40:43]
	v_mfma_f32_16x16x32_bf16 v[28:31], v[132:135], v[196:199], v[28:31]
	v_mfma_f32_16x16x32_bf16 v[24:27], v[140:143], v[196:199], v[24:27]
	v_mfma_f32_16x16x32_bf16 v[12:15], v[132:135], v[212:215], v[12:15]
	v_mfma_f32_16x16x32_bf16 v[8:11], v[140:143], v[212:215], v[8:11]
	s_setprio 0
	s_setprio 1
	v_mfma_f32_16x16x32_bf16 v[52:55], v[144:147], v[160:163], v[52:55]
	v_mfma_f32_16x16x32_bf16 v[48:51], v[152:155], v[160:163], v[48:51]
	v_mfma_f32_16x16x32_bf16 v[36:39], v[144:147], v[168:171], v[36:39]
	v_mfma_f32_16x16x32_bf16 v[32:35], v[152:155], v[168:171], v[32:35]
	v_mfma_f32_16x16x32_bf16 v[20:23], v[144:147], v[192:195], v[20:23]
	v_mfma_f32_16x16x32_bf16 v[16:19], v[152:155], v[192:195], v[16:19]
	v_mfma_f32_16x16x32_bf16 v[4:7], v[144:147], v[200:203], v[4:7]
	v_mfma_f32_16x16x32_bf16 v[0:3], v[152:155], v[200:203], v[0:3]
	v_mfma_f32_16x16x32_bf16 v[52:55], v[148:151], v[164:167], v[52:55]
	v_mfma_f32_16x16x32_bf16 v[48:51], v[156:159], v[164:167], v[48:51]
	v_mfma_f32_16x16x32_bf16 v[36:39], v[148:151], v[172:175], v[36:39]
	v_mfma_f32_16x16x32_bf16 v[32:35], v[156:159], v[172:175], v[32:35]
	v_mfma_f32_16x16x32_bf16 v[20:23], v[148:151], v[196:199], v[20:23]
	v_mfma_f32_16x16x32_bf16 v[16:19], v[156:159], v[196:199], v[16:19]
	v_mfma_f32_16x16x32_bf16 v[4:7], v[148:151], v[212:215], v[4:7]
	v_mfma_f32_16x16x32_bf16 v[0:3], v[156:159], v[212:215], v[0:3]
	s_setprio 0
	s_barrier
	s_add_i32 s48, s48, 2
	s_add_u32 s20, s20, 0x100
	s_addc_u32 s21, s21, 0
	s_add_u32 s46, s46, 0x100
	s_addc_u32 s47, s47, 0
	s_cmpk_gt_u32 s48, 0x55
	s_cbranch_scc0 .LBB0_285
	s_and_b64 vcc, exec, s[16:17]
	s_cbranch_vccz .LBB0_288
	s_barrier

; #define PG8_STAGE(bufoff, gbase, voff) do { _Pragma("unroll") for (int _i = 0; _i < 2; ++_i) \
;         __builtin_amdgcn_global_load_lds((const unsigned*)((const char*)(gbase) + (voff)[_i]), (PG8_LAS unsigned*)(lds + (bufoff) + ldsw + _i * 8192), 16, 0, 0); } while (0)
; #define PG8_LDA(dst, b, h) do { _Pragma("unroll") for (int m = 0; m < 4; ++m) _Pragma("unroll") for (int k = 0; k < 2; ++k) dst[m][k] = *(const PG8_LAS bf16x8*)(lds + PG8_SA(b, h) + aoff + m * 2048 + k * 1024); } while (0)
; #define PG8_LDB(dst, b, h) do { _Pragma("unroll") for (int n = 0; n < 2; ++n) _Pragma("unroll") for (int k = 0; k < 2; ++k) dst[n][k] = *(const PG8_LAS bf16x8*)(lds + PG8_SB(b, h) + boff + n * 2048 + k * 1024); } while (0)
; #define PG8_MMA(ai, bj, At, Bt) do { __builtin_amdgcn_s_setprio(1); _Pragma("unroll") for (int m = 0; m < 4; ++m) _Pragma("unroll") for (int n = 0; n < 2; ++n) _Pragma("unroll") for (int k = 0; k < 2; ++k) \
;         acc[ai][bj][m][n] = __builtin_amdgcn_mfma_f32_16x16x32_bf16(Bt[n][k], At[m][k], acc[ai][bj][m][n], 0, 0, 0); __builtin_amdgcn_s_setprio(0); } while (0)
; #define PG8_WAIT_V(n) asm volatile("s_waitcnt vmcnt(" #n ")" ::: "memory")
; #define PG8_WAIT_L(n) asm volatile("s_waitcnt lgkmcnt(" #n ")" ::: "memory")
; template <class Epi, class Sched, bool ALIGN_EPI = false, bool SP2 = false>
; __device__ __forceinline__ void gemm_phase(PG8_LAS unsigned char* lds, const Gemm g, const Sched& S, const Epi& E) {
;     ...
;             const bool last = (t == nt - 2);
;             const char* a1 = cA + (size_t)(t + 1) * kstep;
;             const char* a2 = last ? nA : cA + (size_t)(t + 2) * kstep; const char* b2 = last ? nB : cB + (size_t)(t + 2) * kstep;
;             const char* a3 = a2 + kstep; const char* b3 = b2 + kstep;
;             if (last && has_next) S.a_ready(nxt);
;             if constexpr (SP2) {
;             PG8_LDB(B0, 0, 0); PG8_LDB(B1, 0, 1); PG8_SCHED; PG8_LDA(At, 0, 0); PG8_STAGE(PG8_SA(1, 1), a1 + hstep, voffA);
;             PG8_WAIT_V(8); PG8_WAIT_L(0); PG8_BAR; PG8_MMA(0, 0, At, B0); PG8_MMA(0, 1, At, B1); PG8_BAR; PG8_SCHED;
;             PG8_LDA(At, 0, 1); PG8_STAGE(PG8_SB(0, 0), b2, voffB); PG8_STAGE(PG8_SB(0, 1), b2 + hstep, voffB); PG8_STAGE(PG8_SA(0, 0), a2, voffA);
;             PG8_WAIT_V(8); PG8_WAIT_L(0); PG8_BAR; PG8_MMA(1, 0, At, B0); PG8_MMA(1, 1, At, B1); PG8_BAR; PG8_SCHED;
.LBB0_370:
	ds_read_b128 v[128:131], v173
	ds_read_b128 v[132:135], v173 offset:1024
	ds_read_b128 v[156:159], v173 offset:2048
	ds_read_b128 v[160:163], v173 offset:3072
	ds_read_b128 v[164:167], v174
	ds_read_b128 v[178:181], v174 offset:1024
	ds_read_b128 v[182:185], v174 offset:2048
	ds_read_b128 v[186:189], v174 offset:3072
	s_add_u32 s6, s4, 0xfff80080
	s_addc_u32 s7, s5, -1
	s_cmp_eq_u32 s47, 28
	s_cselect_b32 s43, s10, s7
	s_cselect_b32 s42, s29, s6
	s_cselect_b32 s7, s27, s46
	s_cselect_b32 s6, s44, s45
	s_add_i32 m0, s1, 0xc000
	ds_read_b128 v[190:193], v175
	ds_read_b128 v[194:197], v175 offset:1024
	ds_read_b128 v[198:201], v175 offset:2048
	ds_read_b128 v[206:209], v175 offset:3072
	ds_read_b128 v[210:213], v175 offset:4096
	ds_read_b128 v[214:217], v175 offset:5120
	ds_read_b128 v[222:225], v175 offset:6144
	ds_read_b128 v[226:229], v175 offset:7168
	s_cmp_lg_u32 s100, 0
	s_cbranch_scc1 .Lgr_p3_0
	global_load_lds_dwordx4 v146, s[4:5]
	s_add_i32 m0, s1, 0xe000
	s_nop 0
	global_load_lds_dwordx4 v148, s[4:5]
	s_waitcnt vmcnt(8)
.Lgr_p3_0:
	s_waitcnt lgkmcnt(0)
	s_barrier
	s_setprio 1
	s_waitcnt lgkmcnt(0)
	v_mfma_f32_16x16x32_bf16 v[124:127], v[128:131], v[190:193], v[124:127]
	v_mfma_f32_16x16x32_bf16 v[120:123], v[156:159], v[190:193], v[120:123]
	v_mfma_f32_16x16x32_bf16 v[108:111], v[128:131], v[198:201], v[108:111]
	v_mfma_f32_16x16x32_bf16 v[104:107], v[156:159], v[198:201], v[104:107]
	v_mfma_f32_16x16x32_bf16 v[92:95], v[128:131], v[210:213], v[92:95]
	v_mfma_f32_16x16x32_bf16 v[88:91], v[156:159], v[210:213], v[88:91]
	v_mfma_f32_16x16x32_bf16 v[76:79], v[128:131], v[222:225], v[76:79]
	v_mfma_f32_16x16x32_bf16 v[72:75], v[156:159], v[222:225], v[72:75]
	v_mfma_f32_16x16x32_bf16 v[124:127], v[132:135], v[194:197], v[124:127]
	v_mfma_f32_16x16x32_bf16 v[120:123], v[160:163], v[194:197], v[120:123]
	v_mfma_f32_16x16x32_bf16 v[108:111], v[132:135], v[206:209], v[108:111]
	v_mfma_f32_16x16x32_bf16 v[104:107], v[160:163], v[206:209], v[104:107]
	v_mfma_f32_16x16x32_bf16 v[92:95], v[132:135], v[214:217], v[92:95]
	v_mfma_f32_16x16x32_bf16 v[88:91], v[160:163], v[214:217], v[88:91]
	v_mfma_f32_16x16x32_bf16 v[76:79], v[132:135], v[226:229], v[76:79]
	v_mfma_f32_16x16x32_bf16 v[72:75], v[160:163], v[226:229], v[72:75]
	s_setprio 0
	s_setprio 1
	v_mfma_f32_16x16x32_bf16 v[116:119], v[164:167], v[190:193], v[116:119]
	v_mfma_f32_16x16x32_bf16 v[112:115], v[182:185], v[190:193], v[112:115]
	v_mfma_f32_16x16x32_bf16 v[100:103], v[164:167], v[198:201], v[100:103]
	v_mfma_f32_16x16x32_bf16 v[96:99], v[182:185], v[198:201], v[96:99]
	v_mfma_f32_16x16x32_bf16 v[84:87], v[164:167], v[210:213], v[84:87]
	v_mfma_f32_16x16x32_bf16 v[80:83], v[182:185], v[210:213], v[80:83]
	v_mfma_f32_16x16x32_bf16 v[68:71], v[164:167], v[222:225], v[68:71]
	v_mfma_f32_16x16x32_bf16 v[64:67], v[182:185], v[222:225], v[64:67]
	v_mfma_f32_16x16x32_bf16 v[116:119], v[178:181], v[194:197], v[116:119]
	v_mfma_f32_16x16x32_bf16 v[112:115], v[186:189], v[194:197], v[112:115]
	v_mfma_f32_16x16x32_bf16 v[100:103], v[178:181], v[206:209], v[100:103]
	v_mfma_f32_16x16x32_bf16 v[96:99], v[186:189], v[206:209], v[96:99]
	v_mfma_f32_16x16x32_bf16 v[84:87], v[178:181], v[214:217], v[84:87]
	v_mfma_f32_16x16x32_bf16 v[80:83], v[186:189], v[214:217], v[80:83]
	v_mfma_f32_16x16x32_bf16 v[68:71], v[178:181], v[226:229], v[68:71]
	v_mfma_f32_16x16x32_bf16 v[64:67], v[186:189], v[226:229], v[64:67]
	s_setprio 0
	s_barrier
	s_add_i32 s69, s53, s0
	s_add_u32 vcc_lo, s6, 0x80
	s_addc_u32 vcc_hi, s7, 0
	s_mov_b32 m0, s69
	ds_read_b128 v[190:193], v175 offset:16384
	ds_read_b128 v[194:197], v175 offset:17408
	ds_read_b128 v[198:201], v175 offset:18432
	ds_read_b128 v[206:209], v175 offset:19456
	ds_read_b128 v[210:213], v175 offset:20480
	ds_read_b128 v[214:217], v175 offset:21504
	ds_read_b128 v[222:225], v175 offset:22528
	ds_read_b128 v[226:229], v175 offset:23552
	global_load_lds_dwordx4 v138, s[6:7]
	s_add_i32 m0, s69, 0x2000
	s_add_u32 s70, s6, 0x80000
	s_addc_u32 s71, s7, 0
	s_add_i32 s69, s54, s0
	global_load_lds_dwordx4 v142, s[6:7]
	s_mov_b32 m0, s69
	s_nop 0
	global_load_lds_dwordx4 v138, s[70:71]
	s_add_i32 m0, s69, 0x2000
	s_nop 0
	global_load_lds_dwordx4 v142, s[70:71]
	s_add_u32 s98, s42, 0x80
	s_addc_u32 s99, s43, 0
	s_mov_b32 m0, s1
	s_nop 0
	global_load_lds_dwordx4 v136, s[42:43]
	s_mov_b32 m0, s33
	s_nop 0
	global_load_lds_dwordx4 v140, s[42:43]
	s_cmp_lg_u32 s100, 0
	s_cbranch_scc1 .Lgr_p3_1
	s_waitcnt vmcnt(8)
; #define PG8_STAGE(bufoff, gbase, voff) do { _Pragma("unroll") for (int _i = 0; _i < 2; ++_i) \
;         __builtin_amdgcn_global_load_lds((const unsigned*)((const char*)(gbase) + (voff)[_i]), (PG8_LAS unsigned*)(lds + (bufoff) + ldsw + _i * 8192), 16, 0, 0); } while (0)
; #define PG8_LDA(dst, b, h) do { _Pragma("unroll") for (int m = 0; m < 4; ++m) _Pragma("unroll") for (int k = 0; k < 2; ++k) dst[m][k] = *(const PG8_LAS bf16x8*)(lds + PG8_SA(b, h) + aoff + m * 2048 + k * 1024); } while (0)
; #define PG8_LDB(dst, b, h) do { _Pragma("unroll") for (int n = 0; n < 2; ++n) _Pragma("unroll") for (int k = 0; k < 2; ++k) dst[n][k] = *(const PG8_LAS bf16x8*)(lds + PG8_SB(b, h) + boff + n * 2048 + k * 1024); } while (0)
; #define PG8_MMA(ai, bj, At, Bt) do { __builtin_amdgcn_s_setprio(1); _Pragma("unroll") for (int m = 0; m < 4; ++m) _Pragma("unroll") for (int n = 0; n < 2; ++n) _Pragma("unroll") for (int k = 0; k < 2; ++k) \
;         acc[ai][bj][m][n] = __builtin_amdgcn_mfma_f32_16x16x32_bf16(Bt[n][k], At[m][k], acc[ai][bj][m][n], 0, 0, 0); __builtin_amdgcn_s_setprio(0); } while (0)
; #define PG8_WAIT_V(n) asm volatile("s_waitcnt vmcnt(" #n ")" ::: "memory")
; #define PG8_WAIT_L(n) asm volatile("s_waitcnt lgkmcnt(" #n ")" ::: "memory")
; #define PG8_BAR __builtin_amdgcn_s_barrier()
; #define PG8_SCHED __builtin_amdgcn_sched_barrier(0)
; template <class Epi, class Sched, bool ALIGN_EPI = false, bool SP2 = false>
; __device__ __forceinline__ void gemm_phase(PG8_LAS unsigned char* lds, const Gemm g, const Sched& S, const Epi& E) {
;     ...
;             PG8_WAIT_V(8); PG8_WAIT_L(0); PG8_BAR; PG8_MMA(1, 0, At, B0); PG8_MMA(1, 1, At, B1); PG8_BAR; PG8_SCHED;
;             PG8_LDB(B0, 1, 0); PG8_LDB(B1, 1, 1); PG8_SCHED; PG8_LDA(At, 1, 0); PG8_STAGE(PG8_SA(0, 1), a2 + hstep, voffA);
;             PG8_WAIT_V(8); PG8_WAIT_L(0); PG8_BAR; PG8_MMA(0, 0, At, B0); PG8_MMA(0, 1, At, B1); PG8_BAR; PG8_SCHED;
.Lgr_p3_1:
	s_waitcnt lgkmcnt(0)
	s_barrier
	s_setprio 1
	s_waitcnt lgkmcnt(0)
	v_mfma_f32_16x16x32_bf16 v[60:63], v[128:131], v[190:193], v[60:63]
	v_mfma_f32_16x16x32_bf16 v[56:59], v[156:159], v[190:193], v[56:59]
	v_mfma_f32_16x16x32_bf16 v[44:47], v[128:131], v[198:201], v[44:47]
	v_mfma_f32_16x16x32_bf16 v[40:43], v[156:159], v[198:201], v[40:43]
	v_mfma_f32_16x16x32_bf16 v[28:31], v[128:131], v[210:213], v[28:31]
	v_mfma_f32_16x16x32_bf16 v[24:27], v[156:159], v[210:213], v[24:27]
	v_mfma_f32_16x16x32_bf16 v[12:15], v[128:131], v[222:225], v[12:15]
	v_mfma_f32_16x16x32_bf16 v[8:11], v[156:159], v[222:225], v[8:11]
	v_mfma_f32_16x16x32_bf16 v[60:63], v[132:135], v[194:197], v[60:63]
	v_mfma_f32_16x16x32_bf16 v[56:59], v[160:163], v[194:197], v[56:59]
	v_mfma_f32_16x16x32_bf16 v[44:47], v[132:135], v[206:209], v[44:47]
	v_mfma_f32_16x16x32_bf16 v[40:43], v[160:163], v[206:209], v[40:43]
	v_mfma_f32_16x16x32_bf16 v[28:31], v[132:135], v[214:217], v[28:31]
	v_mfma_f32_16x16x32_bf16 v[24:27], v[160:163], v[214:217], v[24:27]
	v_mfma_f32_16x16x32_bf16 v[12:15], v[132:135], v[226:229], v[12:15]
	v_mfma_f32_16x16x32_bf16 v[8:11], v[160:163], v[226:229], v[8:11]
	s_setprio 0
	s_setprio 1
	v_mfma_f32_16x16x32_bf16 v[52:55], v[164:167], v[190:193], v[52:55]
	v_mfma_f32_16x16x32_bf16 v[48:51], v[182:185], v[190:193], v[48:51]
	v_mfma_f32_16x16x32_bf16 v[36:39], v[164:167], v[198:201], v[36:39]
	v_mfma_f32_16x16x32_bf16 v[32:35], v[182:185], v[198:201], v[32:35]
	v_mfma_f32_16x16x32_bf16 v[20:23], v[164:167], v[210:213], v[20:23]
	v_mfma_f32_16x16x32_bf16 v[16:19], v[182:185], v[210:213], v[16:19]
	v_mfma_f32_16x16x32_bf16 v[4:7], v[164:167], v[222:225], v[4:7]
	v_mfma_f32_16x16x32_bf16 v[0:3], v[182:185], v[222:225], v[0:3]
	v_mfma_f32_16x16x32_bf16 v[52:55], v[178:181], v[194:197], v[52:55]
	v_mfma_f32_16x16x32_bf16 v[48:51], v[186:189], v[194:197], v[48:51]
	v_mfma_f32_16x16x32_bf16 v[36:39], v[178:181], v[206:209], v[36:39]
	v_mfma_f32_16x16x32_bf16 v[32:35], v[186:189], v[206:209], v[32:35]
	v_mfma_f32_16x16x32_bf16 v[20:23], v[178:181], v[214:217], v[20:23]
	v_mfma_f32_16x16x32_bf16 v[16:19], v[186:189], v[214:217], v[16:19]
	v_mfma_f32_16x16x32_bf16 v[4:7], v[178:181], v[226:229], v[4:7]
	v_mfma_f32_16x16x32_bf16 v[0:3], v[186:189], v[226:229], v[0:3]
	s_setprio 0
	s_barrier
	s_add_i32 s69, 0, 0x18000
	v_add_u32_e32 v144, s69, v171
	s_add_i32 s70, 0, 0x1c000
	ds_read_b128 v[128:131], v144
	ds_read_b128 v[132:135], v144 offset:1024
	ds_read_b128 v[156:159], v144 offset:2048
	ds_read_b128 v[160:163], v144 offset:3072
	v_add_u32_e32 v144, s70, v171
	ds_read_b128 v[164:167], v144
	ds_read_b128 v[178:181], v144 offset:1024
	ds_read_b128 v[182:185], v144 offset:2048
	ds_read_b128 v[186:189], v144 offset:3072
	s_add_u32 s42, s42, 0x80000
	s_addc_u32 s43, s43, 0
	s_mov_b32 m0, s37
	ds_read_b128 v[190:193], v175 offset:32768
	ds_read_b128 v[194:197], v175 offset:33792
	ds_read_b128 v[198:201], v175 offset:34816
	ds_read_b128 v[206:209], v175 offset:35840
	ds_read_b128 v[210:213], v175 offset:36864
	ds_read_b128 v[214:217], v175 offset:37888
	ds_read_b128 v[222:225], v175 offset:38912
	ds_read_b128 v[226:229], v175 offset:39936
	global_load_lds_dwordx4 v136, s[42:43]
	s_mov_b32 m0, s41
	s_nop 0
	global_load_lds_dwordx4 v140, s[42:43]
	s_cmp_lg_u32 s100, 0
	s_cbranch_scc1 .Lgr_p3_2
	s_waitcnt vmcnt(8)
; #define PG8_STAGE(bufoff, gbase, voff) do { _Pragma("unroll") for (int _i = 0; _i < 2; ++_i) \
;         __builtin_amdgcn_global_load_lds((const unsigned*)((const char*)(gbase) + (voff)[_i]), (PG8_LAS unsigned*)(lds + (bufoff) + ldsw + _i * 8192), 16, 0, 0); } while (0)
; #define PG8_LDA(dst, b, h) do { _Pragma("unroll") for (int m = 0; m < 4; ++m) _Pragma("unroll") for (int k = 0; k < 2; ++k) dst[m][k] = *(const PG8_LAS bf16x8*)(lds + PG8_SA(b, h) + aoff + m * 2048 + k * 1024); } while (0)
; #define PG8_MMA(ai, bj, At, Bt) do { __builtin_amdgcn_s_setprio(1); _Pragma("unroll") for (int m = 0; m < 4; ++m) _Pragma("unroll") for (int n = 0; n < 2; ++n) _Pragma("unroll") for (int k = 0; k < 2; ++k) \
;         acc[ai][bj][m][n] = __builtin_amdgcn_mfma_f32_16x16x32_bf16(Bt[n][k], At[m][k], acc[ai][bj][m][n], 0, 0, 0); __builtin_amdgcn_s_setprio(0); } while (0)
; #define PG8_WAIT_V(n) asm volatile("s_waitcnt vmcnt(" #n ")" ::: "memory")
; #define PG8_WAIT_L(n) asm volatile("s_waitcnt lgkmcnt(" #n ")" ::: "memory")
; #define PG8_BAR __builtin_amdgcn_s_barrier()
; #define PG8_SCHED __builtin_amdgcn_sched_barrier(0)
; template <class Epi, class Sched, bool ALIGN_EPI = false, bool SP2 = false>
; __device__ __forceinline__ void gemm_phase(PG8_LAS unsigned char* lds, const Gemm g, const Sched& S, const Epi& E) {
;     ...
;             PG8_WAIT_V(8); PG8_WAIT_L(0); PG8_BAR; PG8_MMA(0, 0, At, B0); PG8_MMA(0, 1, At, B1); PG8_BAR; PG8_SCHED;
;             PG8_LDA(At, 1, 1); PG8_STAGE(PG8_SB(1, 0), b3, voffB); PG8_STAGE(PG8_SB(1, 1), b3 + hstep, voffB); PG8_STAGE(PG8_SA(1, 0), a3, voffA);
;             PG8_WAIT_V(8); PG8_WAIT_L(0); PG8_BAR; PG8_MMA(1, 0, At, B0); PG8_MMA(1, 1, At, B1); PG8_BAR; PG8_SCHED;
.Lgr_p3_2:
	s_waitcnt lgkmcnt(0)
	s_barrier
	s_setprio 1
	s_waitcnt lgkmcnt(0)
	v_mfma_f32_16x16x32_bf16 v[124:127], v[128:131], v[190:193], v[124:127]
	v_mfma_f32_16x16x32_bf16 v[120:123], v[156:159], v[190:193], v[120:123]
	v_mfma_f32_16x16x32_bf16 v[108:111], v[128:131], v[198:201], v[108:111]
	v_mfma_f32_16x16x32_bf16 v[104:107], v[156:159], v[198:201], v[104:107]
	v_mfma_f32_16x16x32_bf16 v[92:95], v[128:131], v[210:213], v[92:95]
	v_mfma_f32_16x16x32_bf16 v[88:91], v[156:159], v[210:213], v[88:91]
	v_mfma_f32_16x16x32_bf16 v[76:79], v[128:131], v[222:225], v[76:79]
	v_mfma_f32_16x16x32_bf16 v[72:75], v[156:159], v[222:225], v[72:75]
	v_mfma_f32_16x16x32_bf16 v[124:127], v[132:135], v[194:197], v[124:127]
	v_mfma_f32_16x16x32_bf16 v[120:123], v[160:163], v[194:197], v[120:123]
	v_mfma_f32_16x16x32_bf16 v[108:111], v[132:135], v[206:209], v[108:111]
	v_mfma_f32_16x16x32_bf16 v[104:107], v[160:163], v[206:209], v[104:107]
	v_mfma_f32_16x16x32_bf16 v[92:95], v[132:135], v[214:217], v[92:95]
	v_mfma_f32_16x16x32_bf16 v[88:91], v[160:163], v[214:217], v[88:91]
	v_mfma_f32_16x16x32_bf16 v[76:79], v[132:135], v[226:229], v[76:79]
	v_mfma_f32_16x16x32_bf16 v[72:75], v[160:163], v[226:229], v[72:75]
	s_setprio 0
	s_setprio 1
	v_mfma_f32_16x16x32_bf16 v[116:119], v[164:167], v[190:193], v[116:119]
	v_mfma_f32_16x16x32_bf16 v[112:115], v[182:185], v[190:193], v[112:115]
	v_mfma_f32_16x16x32_bf16 v[100:103], v[164:167], v[198:201], v[100:103]
	v_mfma_f32_16x16x32_bf16 v[96:99], v[182:185], v[198:201], v[96:99]
	v_mfma_f32_16x16x32_bf16 v[84:87], v[164:167], v[210:213], v[84:87]
	v_mfma_f32_16x16x32_bf16 v[80:83], v[182:185], v[210:213], v[80:83]
	v_mfma_f32_16x16x32_bf16 v[68:71], v[164:167], v[222:225], v[68:71]
	v_mfma_f32_16x16x32_bf16 v[64:67], v[182:185], v[222:225], v[64:67]
	v_mfma_f32_16x16x32_bf16 v[116:119], v[178:181], v[194:197], v[116:119]
	v_mfma_f32_16x16x32_bf16 v[112:115], v[186:189], v[194:197], v[112:115]
	v_mfma_f32_16x16x32_bf16 v[100:103], v[178:181], v[206:209], v[100:103]
	v_mfma_f32_16x16x32_bf16 v[96:99], v[186:189], v[206:209], v[96:99]
	v_mfma_f32_16x16x32_bf16 v[84:87], v[178:181], v[214:217], v[84:87]
	v_mfma_f32_16x16x32_bf16 v[80:83], v[186:189], v[214:217], v[80:83]
	v_mfma_f32_16x16x32_bf16 v[68:71], v[178:181], v[226:229], v[68:71]
	v_mfma_f32_16x16x32_bf16 v[64:67], v[186:189], v[226:229], v[64:67]
	s_setprio 0
	s_barrier
	s_add_i32 s42, s69, s0
	s_mov_b32 m0, s42
	ds_read_b128 v[190:193], v175 offset:49152
	ds_read_b128 v[194:197], v175 offset:50176
	ds_read_b128 v[198:201], v175 offset:51200
	ds_read_b128 v[206:209], v175 offset:52224
	ds_read_b128 v[210:213], v175 offset:53248
	ds_read_b128 v[214:217], v175 offset:54272
	ds_read_b128 v[222:225], v175 offset:55296
	ds_read_b128 v[226:229], v175 offset:56320
	global_load_lds_dwordx4 v138, vcc
	s_add_i32 m0, s42, 0x2000
	s_add_u32 s6, s6, 0x80080
	s_addc_u32 s7, s7, 0
	s_add_i32 s42, s70, s0
	global_load_lds_dwordx4 v142, vcc
	s_mov_b32 m0, s42
	s_nop 0
	global_load_lds_dwordx4 v138, s[6:7]
	s_add_i32 m0, s42, 0x2000
	s_nop 0
	global_load_lds_dwordx4 v142, s[6:7]
	s_mov_b32 m0, s48
	s_nop 0
	global_load_lds_dwordx4 v136, s[98:99]
	s_mov_b32 m0, s49
	s_nop 0
	global_load_lds_dwordx4 v140, s[98:99]
	s_waitcnt vmcnt(8)
	s_waitcnt lgkmcnt(0)
	s_barrier
	s_setprio 1
	s_waitcnt lgkmcnt(0)
	v_mfma_f32_16x16x32_bf16 v[60:63], v[128:131], v[190:193], v[60:63]
	v_mfma_f32_16x16x32_bf16 v[56:59], v[156:159], v[190:193], v[56:59]
	v_mfma_f32_16x16x32_bf16 v[44:47], v[128:131], v[198:201], v[44:47]
	v_mfma_f32_16x16x32_bf16 v[40:43], v[156:159], v[198:201], v[40:43]
	v_mfma_f32_16x16x32_bf16 v[28:31], v[128:131], v[210:213], v[28:31]
	v_mfma_f32_16x16x32_bf16 v[24:27], v[156:159], v[210:213], v[24:27]
	v_mfma_f32_16x16x32_bf16 v[12:15], v[128:131], v[222:225], v[12:15]
	v_mfma_f32_16x16x32_bf16 v[8:11], v[156:159], v[222:225], v[8:11]
	v_mfma_f32_16x16x32_bf16 v[60:63], v[132:135], v[194:197], v[60:63]
	v_mfma_f32_16x16x32_bf16 v[56:59], v[160:163], v[194:197], v[56:59]
	v_mfma_f32_16x16x32_bf16 v[44:47], v[132:135], v[206:209], v[44:47]
	v_mfma_f32_16x16x32_bf16 v[40:43], v[160:163], v[206:209], v[40:43]
	v_mfma_f32_16x16x32_bf16 v[28:31], v[132:135], v[214:217], v[28:31]
	v_mfma_f32_16x16x32_bf16 v[24:27], v[160:163], v[214:217], v[24:27]
	v_mfma_f32_16x16x32_bf16 v[12:15], v[132:135], v[226:229], v[12:15]
	v_mfma_f32_16x16x32_bf16 v[8:11], v[160:163], v[226:229], v[8:11]
	s_setprio 0
	s_setprio 1
	v_mfma_f32_16x16x32_bf16 v[52:55], v[164:167], v[190:193], v[52:55]
	v_mfma_f32_16x16x32_bf16 v[48:51], v[182:185], v[190:193], v[48:51]
	v_mfma_f32_16x16x32_bf16 v[36:39], v[164:167], v[198:201], v[36:39]
	v_mfma_f32_16x16x32_bf16 v[32:35], v[182:185], v[198:201], v[32:35]
	v_mfma_f32_16x16x32_bf16 v[20:23], v[164:167], v[210:213], v[20:23]
	v_mfma_f32_16x16x32_bf16 v[16:19], v[182:185], v[210:213], v[16:19]
	v_mfma_f32_16x16x32_bf16 v[4:7], v[164:167], v[222:225], v[4:7]
	v_mfma_f32_16x16x32_bf16 v[0:3], v[182:185], v[222:225], v[0:3]
	v_mfma_f32_16x16x32_bf16 v[52:55], v[178:181], v[194:197], v[52:55]
	v_mfma_f32_16x16x32_bf16 v[48:51], v[186:189], v[194:197], v[48:51]
	v_mfma_f32_16x16x32_bf16 v[36:39], v[178:181], v[206:209], v[36:39]
	v_mfma_f32_16x16x32_bf16 v[32:35], v[186:189], v[206:209], v[32:35]
	v_mfma_f32_16x16x32_bf16 v[20:23], v[178:181], v[214:217], v[20:23]
	v_mfma_f32_16x16x32_bf16 v[16:19], v[186:189], v[214:217], v[16:19]
	v_mfma_f32_16x16x32_bf16 v[4:7], v[178:181], v[226:229], v[4:7]
	v_mfma_f32_16x16x32_bf16 v[0:3], v[186:189], v[226:229], v[0:3]
	s_setprio 0
	s_barrier
	s_mov_b32 s100, 0
	s_add_i32 s47, s47, 2
	s_add_u32 s4, s4, 0x100
	s_addc_u32 s5, s5, 0
	s_add_u32 s45, s45, 0x100
	s_addc_u32 s46, s46, 0
	s_cmp_gt_u32 s47, 29
	s_cbranch_scc0 .LBB0_370
	s_and_b64 vcc, exec, s[18:19]
	s_cbranch_vccnz .LBB0_375
	s_add_u32 s98, s29, 0x80080
	s_addc_u32 s99, s10, 0
	v_lshl_add_u64 v[252:253], s[98:99], 0, v[146:147]
	s_add_i32 m0, s1, 0xc000
	s_nop 0
	global_load_lds_dwordx4 v[252:253], off
	v_lshl_add_u64 v[252:253], s[98:99], 0, v[148:149]
	s_add_i32 m0, s1, 0xe000
	s_nop 0
	global_load_lds_dwordx4 v[252:253], off
	s_mov_b32 s100, 1
	s_cmp_gt_i32 s36, 7
	s_mov_b64 s[4:5], -1
	s_cbranch_scc1 .LBB0_376

; #define PG8_STAGE(bufoff, gbase, voff) do { _Pragma("unroll") for (int _i = 0; _i < 2; ++_i) \
;         __builtin_amdgcn_global_load_lds((const unsigned*)((const char*)(gbase) + (voff)[_i]), (PG8_LAS unsigned*)(lds + (bufoff) + ldsw + _i * 8192), 16, 0, 0); } while (0)
; #define PG8_LDA(dst, b, h) do { _Pragma("unroll") for (int m = 0; m < 4; ++m) _Pragma("unroll") for (int k = 0; k < 2; ++k) dst[m][k] = *(const PG8_LAS bf16x8*)(lds + PG8_SA(b, h) + aoff + m * 2048 + k * 1024); } while (0)
; #define PG8_LDB(dst, b, h) do { _Pragma("unroll") for (int n = 0; n < 2; ++n) _Pragma("unroll") for (int k = 0; k < 2; ++k) dst[n][k] = *(const PG8_LAS bf16x8*)(lds + PG8_SB(b, h) + boff + n * 2048 + k * 1024); } while (0)
; #define PG8_MMA(ai, bj, At, Bt) do { __builtin_amdgcn_s_setprio(1); _Pragma("unroll") for (int m = 0; m < 4; ++m) _Pragma("unroll") for (int n = 0; n < 2; ++n) _Pragma("unroll") for (int k = 0; k < 2; ++k) \
;         acc[ai][bj][m][n] = __builtin_amdgcn_mfma_f32_16x16x32_bf16(Bt[n][k], At[m][k], acc[ai][bj][m][n], 0, 0, 0); __builtin_amdgcn_s_setprio(0); } while (0)
; #define PG8_WAIT_V(n) asm volatile("s_waitcnt vmcnt(" #n ")" ::: "memory")
; #define PG8_WAIT_L(n) asm volatile("s_waitcnt lgkmcnt(" #n ")" ::: "memory")
; template <class Epi, class Sched, bool ALIGN_EPI = false, bool SP2 = false>
; __device__ __forceinline__ void gemm_phase(PG8_LAS unsigned char* lds, const Gemm g, const Sched& S, const Epi& E) {
;     ...
;             const bool last = (t == nt - 2);
;             const char* a1 = cA + (size_t)(t + 1) * kstep;
;             const char* a2 = last ? nA : cA + (size_t)(t + 2) * kstep; const char* b2 = last ? nB : cB + (size_t)(t + 2) * kstep;
;             const char* a3 = a2 + kstep; const char* b3 = b2 + kstep;
;             if (last && has_next) S.a_ready(nxt);
;             if constexpr (SP2) {
;             PG8_LDB(B0, 0, 0); PG8_LDB(B1, 0, 1); PG8_SCHED; PG8_LDA(At, 0, 0); PG8_STAGE(PG8_SA(1, 1), a1 + hstep, voffA);
;             PG8_WAIT_V(8); PG8_WAIT_L(0); PG8_BAR; PG8_MMA(0, 0, At, B0); PG8_MMA(0, 1, At, B1); PG8_BAR; PG8_SCHED;
;             PG8_LDA(At, 0, 1); PG8_STAGE(PG8_SB(0, 0), b2, voffB); PG8_STAGE(PG8_SB(0, 1), b2 + hstep, voffB); PG8_STAGE(PG8_SA(0, 0), a2, voffA);
;             PG8_WAIT_V(8); PG8_WAIT_L(0); PG8_BAR; PG8_MMA(1, 0, At, B0); PG8_MMA(1, 1, At, B1); PG8_BAR; PG8_SCHED;
.LBB0_884:
	ds_read_b128 v[128:131], v224
	ds_read_b128 v[132:135], v224 offset:1024
	ds_read_b128 v[136:139], v224 offset:2048
	ds_read_b128 v[140:143], v224 offset:3072
	ds_read_b128 v[144:147], v225
	ds_read_b128 v[148:151], v225 offset:1024
	ds_read_b128 v[152:155], v225 offset:2048
	ds_read_b128 v[156:159], v225 offset:3072
	s_add_u32 s24, s0, 0xfffc0080
	s_addc_u32 s25, s1, -1
	s_cmp_eq_u32 s46, 12
	s_cselect_b32 s27, s15, s25
	s_cselect_b32 s26, s23, s24
	s_cselect_b32 s25, s13, s45
	s_cselect_b32 s24, s43, s44
	s_add_i32 m0, s21, 0xc000
	ds_read_b128 v[160:163], v226
	ds_read_b128 v[164:167], v226 offset:1024
	ds_read_b128 v[168:171], v226 offset:2048
	ds_read_b128 v[172:175], v226 offset:3072
	ds_read_b128 v[176:179], v226 offset:4096
	ds_read_b128 v[180:183], v226 offset:5120
	ds_read_b128 v[184:187], v226 offset:6144
	ds_read_b128 v[188:191], v226 offset:7168
	s_cmp_lg_u32 s100, 0
	s_cbranch_scc1 .Lgr_p5_0
	global_load_lds_dwordx4 v200, s[0:1]
	s_add_i32 m0, s21, 0xe000
	s_nop 0
	global_load_lds_dwordx4 v202, s[0:1]
	s_waitcnt vmcnt(8)
.Lgr_p5_0:
	s_waitcnt lgkmcnt(0)
	s_barrier
	s_setprio 1
	s_waitcnt lgkmcnt(0)
	v_mfma_f32_16x16x32_bf16 v[124:127], v[128:131], v[160:163], v[124:127]
	v_mfma_f32_16x16x32_bf16 v[120:123], v[136:139], v[160:163], v[120:123]
	v_mfma_f32_16x16x32_bf16 v[108:111], v[128:131], v[168:171], v[108:111]
	v_mfma_f32_16x16x32_bf16 v[104:107], v[136:139], v[168:171], v[104:107]
	v_mfma_f32_16x16x32_bf16 v[92:95], v[128:131], v[176:179], v[92:95]
	v_mfma_f32_16x16x32_bf16 v[88:91], v[136:139], v[176:179], v[88:91]
	v_mfma_f32_16x16x32_bf16 v[76:79], v[128:131], v[184:187], v[76:79]
	v_mfma_f32_16x16x32_bf16 v[72:75], v[136:139], v[184:187], v[72:75]
	v_mfma_f32_16x16x32_bf16 v[124:127], v[132:135], v[164:167], v[124:127]
	v_mfma_f32_16x16x32_bf16 v[120:123], v[140:143], v[164:167], v[120:123]
	v_mfma_f32_16x16x32_bf16 v[108:111], v[132:135], v[172:175], v[108:111]
	v_mfma_f32_16x16x32_bf16 v[104:107], v[140:143], v[172:175], v[104:107]
	v_mfma_f32_16x16x32_bf16 v[92:95], v[132:135], v[180:183], v[92:95]
	v_mfma_f32_16x16x32_bf16 v[88:91], v[140:143], v[180:183], v[88:91]
	v_mfma_f32_16x16x32_bf16 v[76:79], v[132:135], v[188:191], v[76:79]
	v_mfma_f32_16x16x32_bf16 v[72:75], v[140:143], v[188:191], v[72:75]
	s_setprio 0
	s_setprio 1
	v_mfma_f32_16x16x32_bf16 v[116:119], v[144:147], v[160:163], v[116:119]
	v_mfma_f32_16x16x32_bf16 v[112:115], v[152:155], v[160:163], v[112:115]
	v_mfma_f32_16x16x32_bf16 v[100:103], v[144:147], v[168:171], v[100:103]
	v_mfma_f32_16x16x32_bf16 v[96:99], v[152:155], v[168:171], v[96:99]
	v_mfma_f32_16x16x32_bf16 v[84:87], v[144:147], v[176:179], v[84:87]
	v_mfma_f32_16x16x32_bf16 v[80:83], v[152:155], v[176:179], v[80:83]
	v_mfma_f32_16x16x32_bf16 v[68:71], v[144:147], v[184:187], v[68:71]
	v_mfma_f32_16x16x32_bf16 v[64:67], v[152:155], v[184:187], v[64:67]
	v_mfma_f32_16x16x32_bf16 v[116:119], v[148:151], v[164:167], v[116:119]
	v_mfma_f32_16x16x32_bf16 v[112:115], v[156:159], v[164:167], v[112:115]
	v_mfma_f32_16x16x32_bf16 v[100:103], v[148:151], v[172:175], v[100:103]
	v_mfma_f32_16x16x32_bf16 v[96:99], v[156:159], v[172:175], v[96:99]
	v_mfma_f32_16x16x32_bf16 v[84:87], v[148:151], v[180:183], v[84:87]
	v_mfma_f32_16x16x32_bf16 v[80:83], v[156:159], v[180:183], v[80:83]
	v_mfma_f32_16x16x32_bf16 v[68:71], v[148:151], v[188:191], v[68:71]
	v_mfma_f32_16x16x32_bf16 v[64:67], v[156:159], v[188:191], v[64:67]
	s_setprio 0
	s_barrier
	s_add_i32 s47, s41, s29
	s_add_u32 vcc_lo, s24, 0x80
	s_addc_u32 vcc_hi, s25, 0
	s_mov_b32 m0, s47
	ds_read_b128 v[160:163], v226 offset:16384
	ds_read_b128 v[164:167], v226 offset:17408
	ds_read_b128 v[168:171], v226 offset:18432
	ds_read_b128 v[172:175], v226 offset:19456
	ds_read_b128 v[176:179], v226 offset:20480
	ds_read_b128 v[180:183], v226 offset:21504
	ds_read_b128 v[184:187], v226 offset:22528
	ds_read_b128 v[188:191], v226 offset:23552
	global_load_lds_dwordx4 v194, s[24:25]
	s_add_i32 m0, s47, 0x2000
	s_add_u32 s48, s24, 0x40000
	s_addc_u32 s49, s25, 0
	s_add_i32 s47, s42, s29
	global_load_lds_dwordx4 v198, s[24:25]
	s_mov_b32 m0, s47
	s_nop 0
	global_load_lds_dwordx4 v194, s[48:49]
	s_add_i32 m0, s47, 0x2000
	s_nop 0
	global_load_lds_dwordx4 v198, s[48:49]
	s_add_u32 s98, s26, 0x80
	s_addc_u32 s99, s27, 0
	s_mov_b32 m0, s21
	s_nop 0
	global_load_lds_dwordx4 v192, s[26:27]
	s_mov_b32 m0, s30
	s_nop 0
	global_load_lds_dwordx4 v196, s[26:27]
	s_cmp_lg_u32 s100, 0
	s_cbranch_scc1 .Lgr_p5_1
	s_waitcnt vmcnt(8)
; #define PG8_STAGE(bufoff, gbase, voff) do { _Pragma("unroll") for (int _i = 0; _i < 2; ++_i) \
;         __builtin_amdgcn_global_load_lds((const unsigned*)((const char*)(gbase) + (voff)[_i]), (PG8_LAS unsigned*)(lds + (bufoff) + ldsw + _i * 8192), 16, 0, 0); } while (0)
; #define PG8_LDA(dst, b, h) do { _Pragma("unroll") for (int m = 0; m < 4; ++m) _Pragma("unroll") for (int k = 0; k < 2; ++k) dst[m][k] = *(const PG8_LAS bf16x8*)(lds + PG8_SA(b, h) + aoff + m * 2048 + k * 1024); } while (0)
; #define PG8_LDB(dst, b, h) do { _Pragma("unroll") for (int n = 0; n < 2; ++n) _Pragma("unroll") for (int k = 0; k < 2; ++k) dst[n][k] = *(const PG8_LAS bf16x8*)(lds + PG8_SB(b, h) + boff + n * 2048 + k * 1024); } while (0)
; #define PG8_MMA(ai, bj, At, Bt) do { __builtin_amdgcn_s_setprio(1); _Pragma("unroll") for (int m = 0; m < 4; ++m) _Pragma("unroll") for (int n = 0; n < 2; ++n) _Pragma("unroll") for (int k = 0; k < 2; ++k) \
;         acc[ai][bj][m][n] = __builtin_amdgcn_mfma_f32_16x16x32_bf16(Bt[n][k], At[m][k], acc[ai][bj][m][n], 0, 0, 0); __builtin_amdgcn_s_setprio(0); } while (0)
; #define PG8_WAIT_V(n) asm volatile("s_waitcnt vmcnt(" #n ")" ::: "memory")
; #define PG8_WAIT_L(n) asm volatile("s_waitcnt lgkmcnt(" #n ")" ::: "memory")
; #define PG8_BAR __builtin_amdgcn_s_barrier()
; #define PG8_SCHED __builtin_amdgcn_sched_barrier(0)
; template <class Epi, class Sched, bool ALIGN_EPI = false, bool SP2 = false>
; __device__ __forceinline__ void gemm_phase(PG8_LAS unsigned char* lds, const Gemm g, const Sched& S, const Epi& E) {
;     ...
;             PG8_WAIT_V(8); PG8_WAIT_L(0); PG8_BAR; PG8_MMA(1, 0, At, B0); PG8_MMA(1, 1, At, B1); PG8_BAR; PG8_SCHED;
;             PG8_LDB(B0, 1, 0); PG8_LDB(B1, 1, 1); PG8_SCHED; PG8_LDA(At, 1, 0); PG8_STAGE(PG8_SA(0, 1), a2 + hstep, voffA);
;             PG8_WAIT_V(8); PG8_WAIT_L(0); PG8_BAR; PG8_MMA(0, 0, At, B0); PG8_MMA(0, 1, At, B1); PG8_BAR; PG8_SCHED;
.Lgr_p5_1:
	s_waitcnt lgkmcnt(0)
	s_barrier
	s_setprio 1
	s_waitcnt lgkmcnt(0)
	v_mfma_f32_16x16x32_bf16 v[60:63], v[128:131], v[160:163], v[60:63]
	v_mfma_f32_16x16x32_bf16 v[56:59], v[136:139], v[160:163], v[56:59]
	v_mfma_f32_16x16x32_bf16 v[44:47], v[128:131], v[168:171], v[44:47]
	v_mfma_f32_16x16x32_bf16 v[40:43], v[136:139], v[168:171], v[40:43]
	v_mfma_f32_16x16x32_bf16 v[28:31], v[128:131], v[176:179], v[28:31]
	v_mfma_f32_16x16x32_bf16 v[24:27], v[136:139], v[176:179], v[24:27]
	v_mfma_f32_16x16x32_bf16 v[12:15], v[128:131], v[184:187], v[12:15]
	v_mfma_f32_16x16x32_bf16 v[8:11], v[136:139], v[184:187], v[8:11]
	v_mfma_f32_16x16x32_bf16 v[60:63], v[132:135], v[164:167], v[60:63]
	v_mfma_f32_16x16x32_bf16 v[56:59], v[140:143], v[164:167], v[56:59]
	v_mfma_f32_16x16x32_bf16 v[44:47], v[132:135], v[172:175], v[44:47]
	v_mfma_f32_16x16x32_bf16 v[40:43], v[140:143], v[172:175], v[40:43]
	v_mfma_f32_16x16x32_bf16 v[28:31], v[132:135], v[180:183], v[28:31]
	v_mfma_f32_16x16x32_bf16 v[24:27], v[140:143], v[180:183], v[24:27]
	v_mfma_f32_16x16x32_bf16 v[12:15], v[132:135], v[188:191], v[12:15]
	v_mfma_f32_16x16x32_bf16 v[8:11], v[140:143], v[188:191], v[8:11]
	s_setprio 0
	s_setprio 1
	v_mfma_f32_16x16x32_bf16 v[52:55], v[144:147], v[160:163], v[52:55]
	v_mfma_f32_16x16x32_bf16 v[48:51], v[152:155], v[160:163], v[48:51]
	v_mfma_f32_16x16x32_bf16 v[36:39], v[144:147], v[168:171], v[36:39]
	v_mfma_f32_16x16x32_bf16 v[32:35], v[152:155], v[168:171], v[32:35]
	v_mfma_f32_16x16x32_bf16 v[20:23], v[144:147], v[176:179], v[20:23]
	v_mfma_f32_16x16x32_bf16 v[16:19], v[152:155], v[176:179], v[16:19]
	v_mfma_f32_16x16x32_bf16 v[4:7], v[144:147], v[184:187], v[4:7]
	v_mfma_f32_16x16x32_bf16 v[0:3], v[152:155], v[184:187], v[0:3]
	v_mfma_f32_16x16x32_bf16 v[52:55], v[148:151], v[164:167], v[52:55]
	v_mfma_f32_16x16x32_bf16 v[48:51], v[156:159], v[164:167], v[48:51]
	v_mfma_f32_16x16x32_bf16 v[36:39], v[148:151], v[172:175], v[36:39]
	v_mfma_f32_16x16x32_bf16 v[32:35], v[156:159], v[172:175], v[32:35]
	v_mfma_f32_16x16x32_bf16 v[20:23], v[148:151], v[180:183], v[20:23]
	v_mfma_f32_16x16x32_bf16 v[16:19], v[156:159], v[180:183], v[16:19]
	v_mfma_f32_16x16x32_bf16 v[4:7], v[148:151], v[188:191], v[4:7]
	v_mfma_f32_16x16x32_bf16 v[0:3], v[156:159], v[188:191], v[0:3]
	s_setprio 0
	s_barrier
	s_add_i32 s47, 0, 0x18000
	s_add_i32 s48, 0, 0x1c000
	v_add_u32_e32 v140, s47, v222
	v_add_u32_e32 v156, s48, v222
	ds_read_b128 v[128:131], v140
	ds_read_b128 v[132:135], v140 offset:1024
	ds_read_b128 v[136:139], v140 offset:2048
	ds_read_b128 v[140:143], v140 offset:3072
	ds_read_b128 v[144:147], v156
	ds_read_b128 v[148:151], v156 offset:1024
	ds_read_b128 v[152:155], v156 offset:2048
	ds_read_b128 v[156:159], v156 offset:3072
	s_add_u32 s26, s26, 0x40000
	s_addc_u32 s27, s27, 0
	s_mov_b32 m0, s31
	ds_read_b128 v[160:163], v226 offset:32768
	ds_read_b128 v[164:167], v226 offset:33792
	ds_read_b128 v[168:171], v226 offset:34816
	ds_read_b128 v[172:175], v226 offset:35840
	ds_read_b128 v[176:179], v226 offset:36864
	ds_read_b128 v[180:183], v226 offset:37888
	ds_read_b128 v[184:187], v226 offset:38912
	ds_read_b128 v[188:191], v226 offset:39936
	global_load_lds_dwordx4 v192, s[26:27]
	s_mov_b32 m0, s33
	s_nop 0
	global_load_lds_dwordx4 v196, s[26:27]
	s_cmp_lg_u32 s100, 0
	s_cbranch_scc1 .Lgr_p5_2
	s_waitcnt vmcnt(8)
; #define PG8_STAGE(bufoff, gbase, voff) do { _Pragma("unroll") for (int _i = 0; _i < 2; ++_i) \
;         __builtin_amdgcn_global_load_lds((const unsigned*)((const char*)(gbase) + (voff)[_i]), (PG8_LAS unsigned*)(lds + (bufoff) + ldsw + _i * 8192), 16, 0, 0); } while (0)
; #define PG8_LDA(dst, b, h) do { _Pragma("unroll") for (int m = 0; m < 4; ++m) _Pragma("unroll") for (int k = 0; k < 2; ++k) dst[m][k] = *(const PG8_LAS bf16x8*)(lds + PG8_SA(b, h) + aoff + m * 2048 + k * 1024); } while (0)
; #define PG8_MMA(ai, bj, At, Bt) do { __builtin_amdgcn_s_setprio(1); _Pragma("unroll") for (int m = 0; m < 4; ++m) _Pragma("unroll") for (int n = 0; n < 2; ++n) _Pragma("unroll") for (int k = 0; k < 2; ++k) \
;         acc[ai][bj][m][n] = __builtin_amdgcn_mfma_f32_16x16x32_bf16(Bt[n][k], At[m][k], acc[ai][bj][m][n], 0, 0, 0); __builtin_amdgcn_s_setprio(0); } while (0)
; #define PG8_WAIT_V(n) asm volatile("s_waitcnt vmcnt(" #n ")" ::: "memory")
; #define PG8_WAIT_L(n) asm volatile("s_waitcnt lgkmcnt(" #n ")" ::: "memory")
; #define PG8_BAR __builtin_amdgcn_s_barrier()
; #define PG8_SCHED __builtin_amdgcn_sched_barrier(0)
; template <class Epi, class Sched, bool ALIGN_EPI = false, bool SP2 = false>
; __device__ __forceinline__ void gemm_phase(PG8_LAS unsigned char* lds, const Gemm g, const Sched& S, const Epi& E) {
;     ...
;             PG8_WAIT_V(8); PG8_WAIT_L(0); PG8_BAR; PG8_MMA(0, 0, At, B0); PG8_MMA(0, 1, At, B1); PG8_BAR; PG8_SCHED;
;             PG8_LDA(At, 1, 1); PG8_STAGE(PG8_SB(1, 0), b3, voffB); PG8_STAGE(PG8_SB(1, 1), b3 + hstep, voffB); PG8_STAGE(PG8_SA(1, 0), a3, voffA);
;             PG8_WAIT_V(8); PG8_WAIT_L(0); PG8_BAR; PG8_MMA(1, 0, At, B0); PG8_MMA(1, 1, At, B1); PG8_BAR; PG8_SCHED;
.Lgr_p5_2:
	s_waitcnt lgkmcnt(0)
	s_barrier
	s_setprio 1
	s_waitcnt lgkmcnt(0)
	v_mfma_f32_16x16x32_bf16 v[124:127], v[128:131], v[160:163], v[124:127]
	v_mfma_f32_16x16x32_bf16 v[120:123], v[136:139], v[160:163], v[120:123]
	v_mfma_f32_16x16x32_bf16 v[108:111], v[128:131], v[168:171], v[108:111]
	v_mfma_f32_16x16x32_bf16 v[104:107], v[136:139], v[168:171], v[104:107]
	v_mfma_f32_16x16x32_bf16 v[92:95], v[128:131], v[176:179], v[92:95]
	v_mfma_f32_16x16x32_bf16 v[88:91], v[136:139], v[176:179], v[88:91]
	v_mfma_f32_16x16x32_bf16 v[76:79], v[128:131], v[184:187], v[76:79]
	v_mfma_f32_16x16x32_bf16 v[72:75], v[136:139], v[184:187], v[72:75]
	v_mfma_f32_16x16x32_bf16 v[124:127], v[132:135], v[164:167], v[124:127]
	v_mfma_f32_16x16x32_bf16 v[120:123], v[140:143], v[164:167], v[120:123]
	v_mfma_f32_16x16x32_bf16 v[108:111], v[132:135], v[172:175], v[108:111]
	v_mfma_f32_16x16x32_bf16 v[104:107], v[140:143], v[172:175], v[104:107]
	v_mfma_f32_16x16x32_bf16 v[92:95], v[132:135], v[180:183], v[92:95]
	v_mfma_f32_16x16x32_bf16 v[88:91], v[140:143], v[180:183], v[88:91]
	v_mfma_f32_16x16x32_bf16 v[76:79], v[132:135], v[188:191], v[76:79]
	v_mfma_f32_16x16x32_bf16 v[72:75], v[140:143], v[188:191], v[72:75]
	s_setprio 0
	s_setprio 1
	v_mfma_f32_16x16x32_bf16 v[116:119], v[144:147], v[160:163], v[116:119]
	v_mfma_f32_16x16x32_bf16 v[112:115], v[152:155], v[160:163], v[112:115]
	v_mfma_f32_16x16x32_bf16 v[100:103], v[144:147], v[168:171], v[100:103]
	v_mfma_f32_16x16x32_bf16 v[96:99], v[152:155], v[168:171], v[96:99]
	v_mfma_f32_16x16x32_bf16 v[84:87], v[144:147], v[176:179], v[84:87]
	v_mfma_f32_16x16x32_bf16 v[80:83], v[152:155], v[176:179], v[80:83]
	v_mfma_f32_16x16x32_bf16 v[68:71], v[144:147], v[184:187], v[68:71]
	v_mfma_f32_16x16x32_bf16 v[64:67], v[152:155], v[184:187], v[64:67]
	v_mfma_f32_16x16x32_bf16 v[116:119], v[148:151], v[164:167], v[116:119]
	v_mfma_f32_16x16x32_bf16 v[112:115], v[156:159], v[164:167], v[112:115]
	v_mfma_f32_16x16x32_bf16 v[100:103], v[148:151], v[172:175], v[100:103]
	v_mfma_f32_16x16x32_bf16 v[96:99], v[156:159], v[172:175], v[96:99]
	v_mfma_f32_16x16x32_bf16 v[84:87], v[148:151], v[180:183], v[84:87]
	v_mfma_f32_16x16x32_bf16 v[80:83], v[156:159], v[180:183], v[80:83]
	v_mfma_f32_16x16x32_bf16 v[68:71], v[148:151], v[188:191], v[68:71]
	v_mfma_f32_16x16x32_bf16 v[64:67], v[156:159], v[188:191], v[64:67]
	s_setprio 0
	s_barrier
	s_add_i32 s26, s47, s29
	s_mov_b32 m0, s26
	ds_read_b128 v[160:163], v226 offset:49152
	ds_read_b128 v[164:167], v226 offset:50176
	ds_read_b128 v[168:171], v226 offset:51200
	ds_read_b128 v[172:175], v226 offset:52224
	ds_read_b128 v[176:179], v226 offset:53248
	ds_read_b128 v[180:183], v226 offset:54272
	ds_read_b128 v[184:187], v226 offset:55296
	ds_read_b128 v[188:191], v226 offset:56320
	global_load_lds_dwordx4 v194, vcc
	s_add_i32 m0, s26, 0x2000
	s_add_u32 s24, s24, 0x40080
	s_addc_u32 s25, s25, 0
	s_add_i32 s26, s48, s29
	global_load_lds_dwordx4 v198, vcc
	s_mov_b32 m0, s26
	s_nop 0
	global_load_lds_dwordx4 v194, s[24:25]
	s_add_i32 m0, s26, 0x2000
	s_nop 0
	global_load_lds_dwordx4 v198, s[24:25]
	s_mov_b32 m0, s37
	s_nop 0
	global_load_lds_dwordx4 v192, s[98:99]
	s_mov_b32 m0, s38
	s_nop 0
	global_load_lds_dwordx4 v196, s[98:99]
	s_waitcnt vmcnt(8)
	s_waitcnt lgkmcnt(0)
	s_barrier
	s_setprio 1
	s_waitcnt lgkmcnt(0)
	v_mfma_f32_16x16x32_bf16 v[60:63], v[128:131], v[160:163], v[60:63]
	v_mfma_f32_16x16x32_bf16 v[56:59], v[136:139], v[160:163], v[56:59]
	v_mfma_f32_16x16x32_bf16 v[44:47], v[128:131], v[168:171], v[44:47]
	v_mfma_f32_16x16x32_bf16 v[40:43], v[136:139], v[168:171], v[40:43]
	v_mfma_f32_16x16x32_bf16 v[28:31], v[128:131], v[176:179], v[28:31]
	v_mfma_f32_16x16x32_bf16 v[24:27], v[136:139], v[176:179], v[24:27]
	v_mfma_f32_16x16x32_bf16 v[12:15], v[128:131], v[184:187], v[12:15]
	v_mfma_f32_16x16x32_bf16 v[8:11], v[136:139], v[184:187], v[8:11]
	v_mfma_f32_16x16x32_bf16 v[60:63], v[132:135], v[164:167], v[60:63]
	v_mfma_f32_16x16x32_bf16 v[56:59], v[140:143], v[164:167], v[56:59]
	v_mfma_f32_16x16x32_bf16 v[44:47], v[132:135], v[172:175], v[44:47]
	v_mfma_f32_16x16x32_bf16 v[40:43], v[140:143], v[172:175], v[40:43]
	v_mfma_f32_16x16x32_bf16 v[28:31], v[132:135], v[180:183], v[28:31]
	v_mfma_f32_16x16x32_bf16 v[24:27], v[140:143], v[180:183], v[24:27]
	v_mfma_f32_16x16x32_bf16 v[12:15], v[132:135], v[188:191], v[12:15]
	v_mfma_f32_16x16x32_bf16 v[8:11], v[140:143], v[188:191], v[8:11]
	s_setprio 0
	s_setprio 1
	v_mfma_f32_16x16x32_bf16 v[52:55], v[144:147], v[160:163], v[52:55]
	v_mfma_f32_16x16x32_bf16 v[48:51], v[152:155], v[160:163], v[48:51]
	v_mfma_f32_16x16x32_bf16 v[36:39], v[144:147], v[168:171], v[36:39]
	v_mfma_f32_16x16x32_bf16 v[32:35], v[152:155], v[168:171], v[32:35]
	v_mfma_f32_16x16x32_bf16 v[20:23], v[144:147], v[176:179], v[20:23]
	v_mfma_f32_16x16x32_bf16 v[16:19], v[152:155], v[176:179], v[16:19]
	v_mfma_f32_16x16x32_bf16 v[4:7], v[144:147], v[184:187], v[4:7]
	v_mfma_f32_16x16x32_bf16 v[0:3], v[152:155], v[184:187], v[0:3]
	v_mfma_f32_16x16x32_bf16 v[52:55], v[148:151], v[164:167], v[52:55]
	v_mfma_f32_16x16x32_bf16 v[48:51], v[156:159], v[164:167], v[48:51]
	v_mfma_f32_16x16x32_bf16 v[36:39], v[148:151], v[172:175], v[36:39]
	v_mfma_f32_16x16x32_bf16 v[32:35], v[156:159], v[172:175], v[32:35]
	v_mfma_f32_16x16x32_bf16 v[20:23], v[148:151], v[180:183], v[20:23]
	v_mfma_f32_16x16x32_bf16 v[16:19], v[156:159], v[180:183], v[16:19]
	v_mfma_f32_16x16x32_bf16 v[4:7], v[148:151], v[188:191], v[4:7]
	v_mfma_f32_16x16x32_bf16 v[0:3], v[156:159], v[188:191], v[0:3]
	s_setprio 0
	s_barrier
	s_mov_b32 s100, 0
	s_add_i32 s46, s46, 2
	s_add_u32 s0, s0, 0x100
	s_addc_u32 s1, s1, 0
	s_add_u32 s44, s44, 0x100
	s_addc_u32 s45, s45, 0
	s_cmp_gt_u32 s46, 13
	s_cbranch_scc0 .LBB0_884
	s_and_b64 vcc, exec, s[8:9]
	s_cbranch_vccz .LBB0_887
	s_barrier

; #define PG8_STAGE(bufoff, gbase, voff) do { _Pragma("unroll") for (int _i = 0; _i < 2; ++_i) \
;         __builtin_amdgcn_global_load_lds((const unsigned*)((const char*)(gbase) + (voff)[_i]), (PG8_LAS unsigned*)(lds + (bufoff) + ldsw + _i * 8192), 16, 0, 0); } while (0)
; #define PG8_LDA(dst, b, h) do { _Pragma("unroll") for (int m = 0; m < 4; ++m) _Pragma("unroll") for (int k = 0; k < 2; ++k) dst[m][k] = *(const PG8_LAS bf16x8*)(lds + PG8_SA(b, h) + aoff + m * 2048 + k * 1024); } while (0)
; #define PG8_LDB(dst, b, h) do { _Pragma("unroll") for (int n = 0; n < 2; ++n) _Pragma("unroll") for (int k = 0; k < 2; ++k) dst[n][k] = *(const PG8_LAS bf16x8*)(lds + PG8_SB(b, h) + boff + n * 2048 + k * 1024); } while (0)
; #define PG8_MMA(ai, bj, At, Bt) do { __builtin_amdgcn_s_setprio(1); _Pragma("unroll") for (int m = 0; m < 4; ++m) _Pragma("unroll") for (int n = 0; n < 2; ++n) _Pragma("unroll") for (int k = 0; k < 2; ++k) \
;         acc[ai][bj][m][n] = __builtin_amdgcn_mfma_f32_16x16x32_bf16(Bt[n][k], At[m][k], acc[ai][bj][m][n], 0, 0, 0); __builtin_amdgcn_s_setprio(0); } while (0)
; #define PG8_WAIT_V(n) asm volatile("s_waitcnt vmcnt(" #n ")" ::: "memory")
; #define PG8_WAIT_L(n) asm volatile("s_waitcnt lgkmcnt(" #n ")" ::: "memory")
; template <class Epi, class Sched, bool ALIGN_EPI = false, bool SP2 = false>
; __device__ __forceinline__ void gemm_phase(PG8_LAS unsigned char* lds, const Gemm g, const Sched& S, const Epi& E) {
;     ...
;             const bool last = (t == nt - 2);
;             const char* a1 = cA + (size_t)(t + 1) * kstep;
;             const char* a2 = last ? nA : cA + (size_t)(t + 2) * kstep; const char* b2 = last ? nB : cB + (size_t)(t + 2) * kstep;
;             const char* a3 = a2 + kstep; const char* b3 = b2 + kstep;
;             if (last && has_next) S.a_ready(nxt);
;             if constexpr (SP2) {
;             PG8_LDB(B0, 0, 0); PG8_LDB(B1, 0, 1); PG8_SCHED; PG8_LDA(At, 0, 0); PG8_STAGE(PG8_SA(1, 1), a1 + hstep, voffA);
;             PG8_WAIT_V(8); PG8_WAIT_L(0); PG8_BAR; PG8_MMA(0, 0, At, B0); PG8_MMA(0, 1, At, B1); PG8_BAR; PG8_SCHED;
;             PG8_LDA(At, 0, 1); PG8_STAGE(PG8_SB(0, 0), b2, voffB); PG8_STAGE(PG8_SB(0, 1), b2 + hstep, voffB); PG8_STAGE(PG8_SA(0, 0), a2, voffA);
;             PG8_WAIT_V(8); PG8_WAIT_L(0); PG8_BAR; PG8_MMA(1, 0, At, B0); PG8_MMA(1, 1, At, B1); PG8_BAR; PG8_SCHED;
.LBB0_993:
	ds_read_b128 v[128:131], v213
	ds_read_b128 v[132:135], v213 offset:1024
	ds_read_b128 v[136:139], v213 offset:2048
	ds_read_b128 v[140:143], v213 offset:3072
	ds_read_b128 v[144:147], v214
	ds_read_b128 v[148:151], v214 offset:1024
	ds_read_b128 v[152:155], v214 offset:2048
	ds_read_b128 v[156:159], v214 offset:3072
	s_add_u32 s28, s26, 0xfff80080
	s_addc_u32 s29, s27, -1
	s_cmp_eq_u32 s48, 28
	s_cselect_b32 s31, s17, s29
	s_cselect_b32 s30, s23, s28
	s_cselect_b32 s29, s15, s47
	s_cselect_b32 s28, s45, s46
	s_add_i32 m0, s25, 0xc000
	ds_read_b128 v[160:163], v215
	ds_read_b128 v[164:167], v215 offset:1024
	ds_read_b128 v[168:171], v215 offset:2048
	ds_read_b128 v[172:175], v215 offset:3072
	ds_read_b128 v[192:195], v215 offset:4096
	ds_read_b128 v[196:199], v215 offset:5120
	ds_read_b128 v[200:203], v215 offset:6144
	ds_read_b128 v[204:207], v215 offset:7168
	global_load_lds_dwordx4 v184, s[26:27]
	s_add_i32 m0, s25, 0xe000
	s_nop 0
	global_load_lds_dwordx4 v186, s[26:27]
	s_waitcnt vmcnt(8)
	s_waitcnt lgkmcnt(0)
	s_barrier
	s_setprio 1
	s_waitcnt lgkmcnt(0)
	v_mfma_f32_16x16x32_bf16 v[124:127], v[128:131], v[160:163], v[124:127]
	v_mfma_f32_16x16x32_bf16 v[120:123], v[136:139], v[160:163], v[120:123]
	v_mfma_f32_16x16x32_bf16 v[108:111], v[128:131], v[168:171], v[108:111]
	v_mfma_f32_16x16x32_bf16 v[104:107], v[136:139], v[168:171], v[104:107]
	v_mfma_f32_16x16x32_bf16 v[92:95], v[128:131], v[192:195], v[92:95]
	v_mfma_f32_16x16x32_bf16 v[88:91], v[136:139], v[192:195], v[88:91]
	v_mfma_f32_16x16x32_bf16 v[76:79], v[128:131], v[200:203], v[76:79]
	v_mfma_f32_16x16x32_bf16 v[72:75], v[136:139], v[200:203], v[72:75]
	v_mfma_f32_16x16x32_bf16 v[124:127], v[132:135], v[164:167], v[124:127]
	v_mfma_f32_16x16x32_bf16 v[120:123], v[140:143], v[164:167], v[120:123]
	v_mfma_f32_16x16x32_bf16 v[108:111], v[132:135], v[172:175], v[108:111]
	v_mfma_f32_16x16x32_bf16 v[104:107], v[140:143], v[172:175], v[104:107]
	v_mfma_f32_16x16x32_bf16 v[92:95], v[132:135], v[196:199], v[92:95]
	v_mfma_f32_16x16x32_bf16 v[88:91], v[140:143], v[196:199], v[88:91]
	v_mfma_f32_16x16x32_bf16 v[76:79], v[132:135], v[204:207], v[76:79]
	v_mfma_f32_16x16x32_bf16 v[72:75], v[140:143], v[204:207], v[72:75]
	s_setprio 0
	s_setprio 1
	v_mfma_f32_16x16x32_bf16 v[116:119], v[144:147], v[160:163], v[116:119]
	v_mfma_f32_16x16x32_bf16 v[112:115], v[152:155], v[160:163], v[112:115]
	v_mfma_f32_16x16x32_bf16 v[100:103], v[144:147], v[168:171], v[100:103]
	v_mfma_f32_16x16x32_bf16 v[96:99], v[152:155], v[168:171], v[96:99]
	v_mfma_f32_16x16x32_bf16 v[84:87], v[144:147], v[192:195], v[84:87]
	v_mfma_f32_16x16x32_bf16 v[80:83], v[152:155], v[192:195], v[80:83]
	v_mfma_f32_16x16x32_bf16 v[68:71], v[144:147], v[200:203], v[68:71]
	v_mfma_f32_16x16x32_bf16 v[64:67], v[152:155], v[200:203], v[64:67]
	v_mfma_f32_16x16x32_bf16 v[116:119], v[148:151], v[164:167], v[116:119]
	v_mfma_f32_16x16x32_bf16 v[112:115], v[156:159], v[164:167], v[112:115]
	v_mfma_f32_16x16x32_bf16 v[100:103], v[148:151], v[172:175], v[100:103]
	v_mfma_f32_16x16x32_bf16 v[96:99], v[156:159], v[172:175], v[96:99]
	v_mfma_f32_16x16x32_bf16 v[84:87], v[148:151], v[196:199], v[84:87]
	v_mfma_f32_16x16x32_bf16 v[80:83], v[156:159], v[196:199], v[80:83]
	v_mfma_f32_16x16x32_bf16 v[68:71], v[148:151], v[204:207], v[68:71]
	v_mfma_f32_16x16x32_bf16 v[64:67], v[156:159], v[204:207], v[64:67]
	s_setprio 0
	s_barrier
	s_add_i32 s49, s43, s33
	s_add_u32 vcc_lo, s28, 0x80
	s_addc_u32 vcc_hi, s29, 0
	s_mov_b32 m0, s49
	ds_read_b128 v[160:163], v215 offset:16384
	ds_read_b128 v[164:167], v215 offset:17408
	ds_read_b128 v[168:171], v215 offset:18432
	ds_read_b128 v[172:175], v215 offset:19456
	ds_read_b128 v[192:195], v215 offset:20480
	ds_read_b128 v[196:199], v215 offset:21504
	ds_read_b128 v[200:203], v215 offset:22528
	ds_read_b128 v[204:207], v215 offset:23552
	global_load_lds_dwordx4 v178, s[28:29]
	s_add_i32 m0, s49, 0x2000
	s_add_u32 s50, s28, 0x80000
	s_addc_u32 s51, s29, 0
	s_add_i32 s49, s44, s33
	global_load_lds_dwordx4 v182, s[28:29]
	s_mov_b32 m0, s49
	s_nop 0
	global_load_lds_dwordx4 v178, s[50:51]
	s_add_i32 m0, s49, 0x2000
	s_nop 0
	global_load_lds_dwordx4 v182, s[50:51]
	s_add_u32 s98, s30, 0x80
	s_addc_u32 s99, s31, 0
	s_mov_b32 m0, s25
	s_nop 0
	global_load_lds_dwordx4 v176, s[30:31]
	s_mov_b32 m0, s34
	s_nop 0
	global_load_lds_dwordx4 v180, s[30:31]
	s_waitcnt vmcnt(8)
	s_waitcnt lgkmcnt(0)
	s_barrier
	s_setprio 1
	s_waitcnt lgkmcnt(0)
	v_mfma_f32_16x16x32_bf16 v[60:63], v[128:131], v[160:163], v[60:63]
	v_mfma_f32_16x16x32_bf16 v[56:59], v[136:139], v[160:163], v[56:59]
	v_mfma_f32_16x16x32_bf16 v[44:47], v[128:131], v[168:171], v[44:47]
	v_mfma_f32_16x16x32_bf16 v[40:43], v[136:139], v[168:171], v[40:43]
	v_mfma_f32_16x16x32_bf16 v[28:31], v[128:131], v[192:195], v[28:31]
	v_mfma_f32_16x16x32_bf16 v[24:27], v[136:139], v[192:195], v[24:27]
	v_mfma_f32_16x16x32_bf16 v[12:15], v[128:131], v[200:203], v[12:15]
	v_mfma_f32_16x16x32_bf16 v[8:11], v[136:139], v[200:203], v[8:11]
	v_mfma_f32_16x16x32_bf16 v[60:63], v[132:135], v[164:167], v[60:63]
	v_mfma_f32_16x16x32_bf16 v[56:59], v[140:143], v[164:167], v[56:59]
	v_mfma_f32_16x16x32_bf16 v[44:47], v[132:135], v[172:175], v[44:47]
	v_mfma_f32_16x16x32_bf16 v[40:43], v[140:143], v[172:175], v[40:43]
	v_mfma_f32_16x16x32_bf16 v[28:31], v[132:135], v[196:199], v[28:31]
	v_mfma_f32_16x16x32_bf16 v[24:27], v[140:143], v[196:199], v[24:27]
	v_mfma_f32_16x16x32_bf16 v[12:15], v[132:135], v[204:207], v[12:15]
	v_mfma_f32_16x16x32_bf16 v[8:11], v[140:143], v[204:207], v[8:11]
	s_setprio 0
	s_setprio 1
	v_mfma_f32_16x16x32_bf16 v[52:55], v[144:147], v[160:163], v[52:55]
	v_mfma_f32_16x16x32_bf16 v[48:51], v[152:155], v[160:163], v[48:51]
	v_mfma_f32_16x16x32_bf16 v[36:39], v[144:147], v[168:171], v[36:39]
	v_mfma_f32_16x16x32_bf16 v[32:35], v[152:155], v[168:171], v[32:35]
	v_mfma_f32_16x16x32_bf16 v[20:23], v[144:147], v[192:195], v[20:23]
	v_mfma_f32_16x16x32_bf16 v[16:19], v[152:155], v[192:195], v[16:19]
	v_mfma_f32_16x16x32_bf16 v[4:7], v[144:147], v[200:203], v[4:7]
	v_mfma_f32_16x16x32_bf16 v[0:3], v[152:155], v[200:203], v[0:3]
	v_mfma_f32_16x16x32_bf16 v[52:55], v[148:151], v[164:167], v[52:55]
	v_mfma_f32_16x16x32_bf16 v[48:51], v[156:159], v[164:167], v[48:51]
	v_mfma_f32_16x16x32_bf16 v[36:39], v[148:151], v[172:175], v[36:39]
	v_mfma_f32_16x16x32_bf16 v[32:35], v[156:159], v[172:175], v[32:35]
	v_mfma_f32_16x16x32_bf16 v[20:23], v[148:151], v[196:199], v[20:23]
	v_mfma_f32_16x16x32_bf16 v[16:19], v[156:159], v[196:199], v[16:19]
	v_mfma_f32_16x16x32_bf16 v[4:7], v[148:151], v[204:207], v[4:7]
	v_mfma_f32_16x16x32_bf16 v[0:3], v[156:159], v[204:207], v[0:3]
	s_setprio 0
	s_barrier
; #define PG8_STAGE(bufoff, gbase, voff) do { _Pragma("unroll") for (int _i = 0; _i < 2; ++_i) \
;         __builtin_amdgcn_global_load_lds((const unsigned*)((const char*)(gbase) + (voff)[_i]), (PG8_LAS unsigned*)(lds + (bufoff) + ldsw + _i * 8192), 16, 0, 0); } while (0)
; #define PG8_LDA(dst, b, h) do { _Pragma("unroll") for (int m = 0; m < 4; ++m) _Pragma("unroll") for (int k = 0; k < 2; ++k) dst[m][k] = *(const PG8_LAS bf16x8*)(lds + PG8_SA(b, h) + aoff + m * 2048 + k * 1024); } while (0)
; #define PG8_LDB(dst, b, h) do { _Pragma("unroll") for (int n = 0; n < 2; ++n) _Pragma("unroll") for (int k = 0; k < 2; ++k) dst[n][k] = *(const PG8_LAS bf16x8*)(lds + PG8_SB(b, h) + boff + n * 2048 + k * 1024); } while (0)
; #define PG8_MMA(ai, bj, At, Bt) do { __builtin_amdgcn_s_setprio(1); _Pragma("unroll") for (int m = 0; m < 4; ++m) _Pragma("unroll") for (int n = 0; n < 2; ++n) _Pragma("unroll") for (int k = 0; k < 2; ++k) \
;         acc[ai][bj][m][n] = __builtin_amdgcn_mfma_f32_16x16x32_bf16(Bt[n][k], At[m][k], acc[ai][bj][m][n], 0, 0, 0); __builtin_amdgcn_s_setprio(0); } while (0)
; #define PG8_WAIT_V(n) asm volatile("s_waitcnt vmcnt(" #n ")" ::: "memory")
; #define PG8_WAIT_L(n) asm volatile("s_waitcnt lgkmcnt(" #n ")" ::: "memory")
; #define PG8_BAR __builtin_amdgcn_s_barrier()
; #define PG8_SCHED __builtin_amdgcn_sched_barrier(0)
; template <class Epi, class Sched, bool ALIGN_EPI = false, bool SP2 = false>
; __device__ __forceinline__ void gemm_phase(PG8_LAS unsigned char* lds, const Gemm g, const Sched& S, const Epi& E) {
;     ...
;             PG8_LDB(B0, 1, 0); PG8_LDB(B1, 1, 1); PG8_SCHED; PG8_LDA(At, 1, 0); PG8_STAGE(PG8_SA(0, 1), a2 + hstep, voffA);
;             PG8_WAIT_V(8); PG8_WAIT_L(0); PG8_BAR; PG8_MMA(0, 0, At, B0); PG8_MMA(0, 1, At, B1); PG8_BAR; PG8_SCHED;
;             PG8_LDA(At, 1, 1); PG8_STAGE(PG8_SB(1, 0), b3, voffB); PG8_STAGE(PG8_SB(1, 1), b3 + hstep, voffB); PG8_STAGE(PG8_SA(1, 0), a3, voffA);
;             PG8_WAIT_V(8); PG8_WAIT_L(0); PG8_BAR; PG8_MMA(1, 0, At, B0); PG8_MMA(1, 1, At, B1); PG8_BAR; PG8_SCHED;
	s_add_i32 s49, 0, 0x18000
	s_add_i32 s50, 0, 0x1c000
	v_add_u32_e32 v140, s49, v211
	v_add_u32_e32 v156, s50, v211
	ds_read_b128 v[128:131], v140
	ds_read_b128 v[132:135], v140 offset:1024
	ds_read_b128 v[136:139], v140 offset:2048
	ds_read_b128 v[140:143], v140 offset:3072
	ds_read_b128 v[144:147], v156
	ds_read_b128 v[148:151], v156 offset:1024
	ds_read_b128 v[152:155], v156 offset:2048
	ds_read_b128 v[156:159], v156 offset:3072
	s_add_u32 s30, s30, 0x80000
	s_addc_u32 s31, s31, 0
	s_mov_b32 m0, s35
	ds_read_b128 v[160:163], v215 offset:32768
	ds_read_b128 v[164:167], v215 offset:33792
	ds_read_b128 v[168:171], v215 offset:34816
	ds_read_b128 v[172:175], v215 offset:35840
	ds_read_b128 v[192:195], v215 offset:36864
	ds_read_b128 v[196:199], v215 offset:37888
	ds_read_b128 v[200:203], v215 offset:38912
	ds_read_b128 v[204:207], v215 offset:39936
	global_load_lds_dwordx4 v176, s[30:31]
	s_mov_b32 m0, s36
	s_nop 0
	global_load_lds_dwordx4 v180, s[30:31]
	s_waitcnt vmcnt(8)
	s_waitcnt lgkmcnt(0)
	s_barrier
	s_setprio 1
	s_waitcnt lgkmcnt(0)
	v_mfma_f32_16x16x32_bf16 v[124:127], v[128:131], v[160:163], v[124:127]
	v_mfma_f32_16x16x32_bf16 v[120:123], v[136:139], v[160:163], v[120:123]
	v_mfma_f32_16x16x32_bf16 v[108:111], v[128:131], v[168:171], v[108:111]
	v_mfma_f32_16x16x32_bf16 v[104:107], v[136:139], v[168:171], v[104:107]
	v_mfma_f32_16x16x32_bf16 v[92:95], v[128:131], v[192:195], v[92:95]
	v_mfma_f32_16x16x32_bf16 v[88:91], v[136:139], v[192:195], v[88:91]
	v_mfma_f32_16x16x32_bf16 v[76:79], v[128:131], v[200:203], v[76:79]
	v_mfma_f32_16x16x32_bf16 v[72:75], v[136:139], v[200:203], v[72:75]
	v_mfma_f32_16x16x32_bf16 v[124:127], v[132:135], v[164:167], v[124:127]
	v_mfma_f32_16x16x32_bf16 v[120:123], v[140:143], v[164:167], v[120:123]
	v_mfma_f32_16x16x32_bf16 v[108:111], v[132:135], v[172:175], v[108:111]
	v_mfma_f32_16x16x32_bf16 v[104:107], v[140:143], v[172:175], v[104:107]
	v_mfma_f32_16x16x32_bf16 v[92:95], v[132:135], v[196:199], v[92:95]
	v_mfma_f32_16x16x32_bf16 v[88:91], v[140:143], v[196:199], v[88:91]
	v_mfma_f32_16x16x32_bf16 v[76:79], v[132:135], v[204:207], v[76:79]
	v_mfma_f32_16x16x32_bf16 v[72:75], v[140:143], v[204:207], v[72:75]
	s_setprio 0
	s_setprio 1
	v_mfma_f32_16x16x32_bf16 v[116:119], v[144:147], v[160:163], v[116:119]
	v_mfma_f32_16x16x32_bf16 v[112:115], v[152:155], v[160:163], v[112:115]
	v_mfma_f32_16x16x32_bf16 v[100:103], v[144:147], v[168:171], v[100:103]
	v_mfma_f32_16x16x32_bf16 v[96:99], v[152:155], v[168:171], v[96:99]
	v_mfma_f32_16x16x32_bf16 v[84:87], v[144:147], v[192:195], v[84:87]
	v_mfma_f32_16x16x32_bf16 v[80:83], v[152:155], v[192:195], v[80:83]
	v_mfma_f32_16x16x32_bf16 v[68:71], v[144:147], v[200:203], v[68:71]
	v_mfma_f32_16x16x32_bf16 v[64:67], v[152:155], v[200:203], v[64:67]
	v_mfma_f32_16x16x32_bf16 v[116:119], v[148:151], v[164:167], v[116:119]
	v_mfma_f32_16x16x32_bf16 v[112:115], v[156:159], v[164:167], v[112:115]
	v_mfma_f32_16x16x32_bf16 v[100:103], v[148:151], v[172:175], v[100:103]
	v_mfma_f32_16x16x32_bf16 v[96:99], v[156:159], v[172:175], v[96:99]
	v_mfma_f32_16x16x32_bf16 v[84:87], v[148:151], v[196:199], v[84:87]
	v_mfma_f32_16x16x32_bf16 v[80:83], v[156:159], v[196:199], v[80:83]
	v_mfma_f32_16x16x32_bf16 v[68:71], v[148:151], v[204:207], v[68:71]
	v_mfma_f32_16x16x32_bf16 v[64:67], v[156:159], v[204:207], v[64:67]
	s_setprio 0
	s_barrier
	s_add_i32 s30, s49, s33
	s_mov_b32 m0, s30
	ds_read_b128 v[160:163], v215 offset:49152
	ds_read_b128 v[164:167], v215 offset:50176
	ds_read_b128 v[168:171], v215 offset:51200
	ds_read_b128 v[172:175], v215 offset:52224
	ds_read_b128 v[192:195], v215 offset:53248
	ds_read_b128 v[196:199], v215 offset:54272
	ds_read_b128 v[200:203], v215 offset:55296
	ds_read_b128 v[204:207], v215 offset:56320
	global_load_lds_dwordx4 v178, vcc
	s_add_i32 m0, s30, 0x2000
	s_add_u32 s28, s28, 0x80080
	s_addc_u32 s29, s29, 0
	s_add_i32 s30, s50, s33
	global_load_lds_dwordx4 v182, vcc
	s_mov_b32 m0, s30
	s_nop 0
	global_load_lds_dwordx4 v178, s[28:29]
	s_add_i32 m0, s30, 0x2000
	s_nop 0
	global_load_lds_dwordx4 v182, s[28:29]
	s_mov_b32 m0, s38
	s_nop 0
	global_load_lds_dwordx4 v176, s[98:99]
	s_mov_b32 m0, s39
	s_nop 0
	global_load_lds_dwordx4 v180, s[98:99]
	s_waitcnt vmcnt(8)
	s_waitcnt lgkmcnt(0)
	s_barrier
	s_setprio 1
	s_waitcnt lgkmcnt(0)
	v_mfma_f32_16x16x32_bf16 v[60:63], v[128:131], v[160:163], v[60:63]
	v_mfma_f32_16x16x32_bf16 v[56:59], v[136:139], v[160:163], v[56:59]
	v_mfma_f32_16x16x32_bf16 v[44:47], v[128:131], v[168:171], v[44:47]
	v_mfma_f32_16x16x32_bf16 v[40:43], v[136:139], v[168:171], v[40:43]
	v_mfma_f32_16x16x32_bf16 v[28:31], v[128:131], v[192:195], v[28:31]
	v_mfma_f32_16x16x32_bf16 v[24:27], v[136:139], v[192:195], v[24:27]
	v_mfma_f32_16x16x32_bf16 v[12:15], v[128:131], v[200:203], v[12:15]
	v_mfma_f32_16x16x32_bf16 v[8:11], v[136:139], v[200:203], v[8:11]
	v_mfma_f32_16x16x32_bf16 v[60:63], v[132:135], v[164:167], v[60:63]
	v_mfma_f32_16x16x32_bf16 v[56:59], v[140:143], v[164:167], v[56:59]
	v_mfma_f32_16x16x32_bf16 v[44:47], v[132:135], v[172:175], v[44:47]
	v_mfma_f32_16x16x32_bf16 v[40:43], v[140:143], v[172:175], v[40:43]
	v_mfma_f32_16x16x32_bf16 v[28:31], v[132:135], v[196:199], v[28:31]
	v_mfma_f32_16x16x32_bf16 v[24:27], v[140:143], v[196:199], v[24:27]
	v_mfma_f32_16x16x32_bf16 v[12:15], v[132:135], v[204:207], v[12:15]
	v_mfma_f32_16x16x32_bf16 v[8:11], v[140:143], v[204:207], v[8:11]
	s_setprio 0
	s_setprio 1
	v_mfma_f32_16x16x32_bf16 v[52:55], v[144:147], v[160:163], v[52:55]
	v_mfma_f32_16x16x32_bf16 v[48:51], v[152:155], v[160:163], v[48:51]
	v_mfma_f32_16x16x32_bf16 v[36:39], v[144:147], v[168:171], v[36:39]
	v_mfma_f32_16x16x32_bf16 v[32:35], v[152:155], v[168:171], v[32:35]
	v_mfma_f32_16x16x32_bf16 v[20:23], v[144:147], v[192:195], v[20:23]
	v_mfma_f32_16x16x32_bf16 v[16:19], v[152:155], v[192:195], v[16:19]
	v_mfma_f32_16x16x32_bf16 v[4:7], v[144:147], v[200:203], v[4:7]
	v_mfma_f32_16x16x32_bf16 v[0:3], v[152:155], v[200:203], v[0:3]
	v_mfma_f32_16x16x32_bf16 v[52:55], v[148:151], v[164:167], v[52:55]
	v_mfma_f32_16x16x32_bf16 v[48:51], v[156:159], v[164:167], v[48:51]
	v_mfma_f32_16x16x32_bf16 v[36:39], v[148:151], v[172:175], v[36:39]
	v_mfma_f32_16x16x32_bf16 v[32:35], v[156:159], v[172:175], v[32:35]
	v_mfma_f32_16x16x32_bf16 v[20:23], v[148:151], v[196:199], v[20:23]
	v_mfma_f32_16x16x32_bf16 v[16:19], v[156:159], v[196:199], v[16:19]
	v_mfma_f32_16x16x32_bf16 v[4:7], v[148:151], v[204:207], v[4:7]
	v_mfma_f32_16x16x32_bf16 v[0:3], v[156:159], v[204:207], v[0:3]
	s_setprio 0
	s_barrier
	s_add_i32 s48, s48, 2
	s_add_u32 s26, s26, 0x100
	s_addc_u32 s27, s27, 0
	s_add_u32 s46, s46, 0x100
	s_addc_u32 s47, s47, 0
	s_cmp_gt_u32 s48, 29
	s_cbranch_scc0 .LBB0_993
	s_and_b64 vcc, exec, s[12:13]
	s_cbranch_vccz .LBB0_996
	s_barrier

; #define PG8_STAGE(bufoff, gbase, voff) do { _Pragma("unroll") for (int _i = 0; _i < 2; ++_i) \
;         __builtin_amdgcn_global_load_lds((const unsigned*)((const char*)(gbase) + (voff)[_i]), (PG8_LAS unsigned*)(lds + (bufoff) + ldsw + _i * 8192), 16, 0, 0); } while (0)
; #define PG8_LDA(dst, b, h) do { _Pragma("unroll") for (int m = 0; m < 4; ++m) _Pragma("unroll") for (int k = 0; k < 2; ++k) dst[m][k] = *(const PG8_LAS bf16x8*)(lds + PG8_SA(b, h) + aoff + m * 2048 + k * 1024); } while (0)
; #define PG8_LDB(dst, b, h) do { _Pragma("unroll") for (int n = 0; n < 2; ++n) _Pragma("unroll") for (int k = 0; k < 2; ++k) dst[n][k] = *(const PG8_LAS bf16x8*)(lds + PG8_SB(b, h) + boff + n * 2048 + k * 1024); } while (0)
; #define PG8_MMA(ai, bj, At, Bt) do { __builtin_amdgcn_s_setprio(1); _Pragma("unroll") for (int m = 0; m < 4; ++m) _Pragma("unroll") for (int n = 0; n < 2; ++n) _Pragma("unroll") for (int k = 0; k < 2; ++k) \
;         acc[ai][bj][m][n] = __builtin_amdgcn_mfma_f32_16x16x32_bf16(Bt[n][k], At[m][k], acc[ai][bj][m][n], 0, 0, 0); __builtin_amdgcn_s_setprio(0); } while (0)
; #define PG8_WAIT_V(n) asm volatile("s_waitcnt vmcnt(" #n ")" ::: "memory")
; #define PG8_WAIT_L(n) asm volatile("s_waitcnt lgkmcnt(" #n ")" ::: "memory")
; #define PG8_BAR __builtin_amdgcn_s_barrier()
; #define PG8_SCHED __builtin_amdgcn_sched_barrier(0)
; template <class Epi, class Sched, bool ALIGN_EPI = false, bool SP2 = false>
; __device__ __forceinline__ void gemm_phase(PG8_LAS unsigned char* lds, const Gemm g, const Sched& S, const Epi& E) {
;     ...
;             const bool last = (t == nt - 2);
;             const char* a1 = cA + (size_t)(t + 1) * kstep;
;             const char* a2 = last ? nA : cA + (size_t)(t + 2) * kstep; const char* b2 = last ? nB : cB + (size_t)(t + 2) * kstep;
;             const char* a3 = a2 + kstep; const char* b3 = b2 + kstep;
;             if (last && has_next) S.a_ready(nxt);
;             if constexpr (SP2) {
;             PG8_LDB(B0, 0, 0); PG8_LDB(B1, 0, 1); PG8_SCHED; PG8_LDA(At, 0, 0); PG8_STAGE(PG8_SA(1, 1), a1 + hstep, voffA);
;             PG8_WAIT_V(8); PG8_WAIT_L(0); PG8_BAR; PG8_MMA(0, 0, At, B0); PG8_MMA(0, 1, At, B1); PG8_BAR; PG8_SCHED;
;             PG8_LDA(At, 0, 1); PG8_STAGE(PG8_SB(0, 0), b2, voffB); PG8_STAGE(PG8_SB(0, 1), b2 + hstep, voffB); PG8_STAGE(PG8_SA(0, 0), a2, voffA);
.LBB0_1076:
	ds_read_b128 v[166:169], v162
	ds_read_b128 v[170:173], v162 offset:1024
	ds_read_b128 v[174:177], v162 offset:2048
	ds_read_b128 v[178:181], v162 offset:3072
	ds_read_b128 v[182:185], v163
	ds_read_b128 v[186:189], v163 offset:1024
	ds_read_b128 v[190:193], v163 offset:2048
	ds_read_b128 v[194:197], v163 offset:3072
	s_add_u32 s26, s24, 0xfff80080
	s_addc_u32 s27, s25, -1
	s_cmp_eq_u32 s51, 28
	s_cselect_b32 s29, s19, s27
	s_cselect_b32 s28, s47, s26
	s_cselect_b32 s27, s17, s50
	s_cselect_b32 s26, s48, s49
	s_add_i32 m0, s34, 0xc000
	ds_read_b128 v[198:201], v164
	ds_read_b128 v[202:205], v164 offset:1024
	ds_read_b128 v[206:209], v164 offset:2048
	ds_read_b128 v[210:213], v164 offset:3072
	ds_read_b128 v[214:217], v164 offset:4096
	ds_read_b128 v[222:225], v164 offset:5120
	ds_read_b128 v[226:229], v164 offset:6144
	ds_read_b128 v[230:233], v164 offset:7168
	s_cmp_lg_u32 s100, 0
	s_cbranch_scc1 .Lgr_p7_0
	global_load_lds_dwordx4 v136, s[24:25]
	s_add_i32 m0, s34, 0xe000
	s_nop 0
	global_load_lds_dwordx4 v138, s[24:25]
	s_waitcnt vmcnt(8)
.Lgr_p7_0:
	s_waitcnt lgkmcnt(0)
	s_barrier
	s_setprio 1
	s_waitcnt lgkmcnt(0)
	v_mfma_f32_16x16x32_bf16 v[116:119], v[166:169], v[198:201], v[116:119]
	v_mfma_f32_16x16x32_bf16 v[112:115], v[174:177], v[198:201], v[112:115]
	v_mfma_f32_16x16x32_bf16 v[108:111], v[166:169], v[206:209], v[108:111]
	v_mfma_f32_16x16x32_bf16 v[100:103], v[174:177], v[206:209], v[100:103]
	v_mfma_f32_16x16x32_bf16 v[92:95], v[166:169], v[214:217], v[92:95]
	v_mfma_f32_16x16x32_bf16 v[84:87], v[174:177], v[214:217], v[84:87]
	v_mfma_f32_16x16x32_bf16 v[76:79], v[166:169], v[226:229], v[76:79]
	v_mfma_f32_16x16x32_bf16 v[68:71], v[174:177], v[226:229], v[68:71]
	v_mfma_f32_16x16x32_bf16 v[116:119], v[170:173], v[202:205], v[116:119]
	v_mfma_f32_16x16x32_bf16 v[112:115], v[178:181], v[202:205], v[112:115]
	v_mfma_f32_16x16x32_bf16 v[108:111], v[170:173], v[210:213], v[108:111]
	v_mfma_f32_16x16x32_bf16 v[100:103], v[178:181], v[210:213], v[100:103]
	v_mfma_f32_16x16x32_bf16 v[92:95], v[170:173], v[222:225], v[92:95]
	v_mfma_f32_16x16x32_bf16 v[84:87], v[178:181], v[222:225], v[84:87]
	v_mfma_f32_16x16x32_bf16 v[76:79], v[170:173], v[230:233], v[76:79]
	v_mfma_f32_16x16x32_bf16 v[68:71], v[178:181], v[230:233], v[68:71]
	s_setprio 0
	s_setprio 1
	v_mfma_f32_16x16x32_bf16 v[124:127], v[182:185], v[198:201], v[124:127]
	v_mfma_f32_16x16x32_bf16 v[120:123], v[190:193], v[198:201], v[120:123]
	v_mfma_f32_16x16x32_bf16 v[104:107], v[182:185], v[206:209], v[104:107]
	v_mfma_f32_16x16x32_bf16 v[96:99], v[190:193], v[206:209], v[96:99]
	v_mfma_f32_16x16x32_bf16 v[88:91], v[182:185], v[214:217], v[88:91]
	v_mfma_f32_16x16x32_bf16 v[80:83], v[190:193], v[214:217], v[80:83]
	v_mfma_f32_16x16x32_bf16 v[72:75], v[182:185], v[226:229], v[72:75]
	v_mfma_f32_16x16x32_bf16 v[64:67], v[190:193], v[226:229], v[64:67]
	v_mfma_f32_16x16x32_bf16 v[124:127], v[186:189], v[202:205], v[124:127]
	v_mfma_f32_16x16x32_bf16 v[120:123], v[194:197], v[202:205], v[120:123]
	v_mfma_f32_16x16x32_bf16 v[104:107], v[186:189], v[210:213], v[104:107]
	v_mfma_f32_16x16x32_bf16 v[96:99], v[194:197], v[210:213], v[96:99]
	v_mfma_f32_16x16x32_bf16 v[88:91], v[186:189], v[222:225], v[88:91]
	v_mfma_f32_16x16x32_bf16 v[80:83], v[194:197], v[222:225], v[80:83]
	v_mfma_f32_16x16x32_bf16 v[72:75], v[186:189], v[230:233], v[72:75]
	v_mfma_f32_16x16x32_bf16 v[64:67], v[194:197], v[230:233], v[64:67]
	s_setprio 0
	s_barrier
	s_add_i32 s52, s43, s30
	s_add_u32 vcc_lo, s26, 0x80
	s_addc_u32 vcc_hi, s27, 0
	s_mov_b32 m0, s52
	ds_read_b128 v[198:201], v164 offset:16384
	ds_read_b128 v[202:205], v164 offset:17408
	ds_read_b128 v[206:209], v164 offset:18432
	ds_read_b128 v[210:213], v164 offset:19456
	ds_read_b128 v[214:217], v164 offset:20480
	ds_read_b128 v[222:225], v164 offset:21504
	ds_read_b128 v[226:229], v164 offset:22528
	ds_read_b128 v[230:233], v164 offset:23552
	global_load_lds_dwordx4 v132, s[26:27]
	s_add_i32 m0, s52, 0x2000
	s_add_u32 s52, s26, 0x80000
	s_addc_u32 s53, s27, 0
	s_add_i32 s54, s44, s30
	global_load_lds_dwordx4 v128, s[26:27]
	s_mov_b32 m0, s54
	s_nop 0
	global_load_lds_dwordx4 v132, s[52:53]
	s_add_i32 m0, s54, 0x2000
	s_nop 0
	global_load_lds_dwordx4 v128, s[52:53]
	s_add_u32 s98, s28, 0x80
	s_addc_u32 s99, s29, 0
	s_mov_b32 m0, s34
	s_nop 0
	global_load_lds_dwordx4 v134, s[28:29]
	s_mov_b32 m0, s35
	s_nop 0
	global_load_lds_dwordx4 v130, s[28:29]
	s_cmp_lg_u32 s100, 0
	s_cbranch_scc1 .Lgr_p7_1
	s_waitcnt vmcnt(8)
; #define PG8_STAGE(bufoff, gbase, voff) do { _Pragma("unroll") for (int _i = 0; _i < 2; ++_i) \
;         __builtin_amdgcn_global_load_lds((const unsigned*)((const char*)(gbase) + (voff)[_i]), (PG8_LAS unsigned*)(lds + (bufoff) + ldsw + _i * 8192), 16, 0, 0); } while (0)
; #define PG8_LDA(dst, b, h) do { _Pragma("unroll") for (int m = 0; m < 4; ++m) _Pragma("unroll") for (int k = 0; k < 2; ++k) dst[m][k] = *(const PG8_LAS bf16x8*)(lds + PG8_SA(b, h) + aoff + m * 2048 + k * 1024); } while (0)
; #define PG8_LDB(dst, b, h) do { _Pragma("unroll") for (int n = 0; n < 2; ++n) _Pragma("unroll") for (int k = 0; k < 2; ++k) dst[n][k] = *(const PG8_LAS bf16x8*)(lds + PG8_SB(b, h) + boff + n * 2048 + k * 1024); } while (0)
; #define PG8_MMA(ai, bj, At, Bt) do { __builtin_amdgcn_s_setprio(1); _Pragma("unroll") for (int m = 0; m < 4; ++m) _Pragma("unroll") for (int n = 0; n < 2; ++n) _Pragma("unroll") for (int k = 0; k < 2; ++k) \
;         acc[ai][bj][m][n] = __builtin_amdgcn_mfma_f32_16x16x32_bf16(Bt[n][k], At[m][k], acc[ai][bj][m][n], 0, 0, 0); __builtin_amdgcn_s_setprio(0); } while (0)
; #define PG8_WAIT_V(n) asm volatile("s_waitcnt vmcnt(" #n ")" ::: "memory")
; #define PG8_WAIT_L(n) asm volatile("s_waitcnt lgkmcnt(" #n ")" ::: "memory")
; #define PG8_BAR __builtin_amdgcn_s_barrier()
; #define PG8_SCHED __builtin_amdgcn_sched_barrier(0)
; template <class Epi, class Sched, bool ALIGN_EPI = false, bool SP2 = false>
; __device__ __forceinline__ void gemm_phase(PG8_LAS unsigned char* lds, const Gemm g, const Sched& S, const Epi& E) {
;     ...
;             PG8_WAIT_V(8); PG8_WAIT_L(0); PG8_BAR; PG8_MMA(1, 0, At, B0); PG8_MMA(1, 1, At, B1); PG8_BAR; PG8_SCHED;
;             PG8_LDB(B0, 1, 0); PG8_LDB(B1, 1, 1); PG8_SCHED; PG8_LDA(At, 1, 0); PG8_STAGE(PG8_SA(0, 1), a2 + hstep, voffA);
.Lgr_p7_1:
	s_waitcnt lgkmcnt(0)
	s_barrier
	s_setprio 1
	s_waitcnt lgkmcnt(0)
	v_mfma_f32_16x16x32_bf16 v[60:63], v[166:169], v[198:201], v[60:63]
	v_mfma_f32_16x16x32_bf16 v[52:55], v[174:177], v[198:201], v[52:55]
	v_mfma_f32_16x16x32_bf16 v[44:47], v[166:169], v[206:209], v[44:47]
	v_mfma_f32_16x16x32_bf16 v[36:39], v[174:177], v[206:209], v[36:39]
	v_mfma_f32_16x16x32_bf16 v[28:31], v[166:169], v[214:217], v[28:31]
	v_mfma_f32_16x16x32_bf16 v[20:23], v[174:177], v[214:217], v[20:23]
	v_mfma_f32_16x16x32_bf16 v[12:15], v[166:169], v[226:229], v[12:15]
	v_mfma_f32_16x16x32_bf16 v[4:7], v[174:177], v[226:229], v[4:7]
	v_mfma_f32_16x16x32_bf16 v[60:63], v[170:173], v[202:205], v[60:63]
	v_mfma_f32_16x16x32_bf16 v[52:55], v[178:181], v[202:205], v[52:55]
	v_mfma_f32_16x16x32_bf16 v[44:47], v[170:173], v[210:213], v[44:47]
	v_mfma_f32_16x16x32_bf16 v[36:39], v[178:181], v[210:213], v[36:39]
	v_mfma_f32_16x16x32_bf16 v[28:31], v[170:173], v[222:225], v[28:31]
	v_mfma_f32_16x16x32_bf16 v[20:23], v[178:181], v[222:225], v[20:23]
	v_mfma_f32_16x16x32_bf16 v[12:15], v[170:173], v[230:233], v[12:15]
	v_mfma_f32_16x16x32_bf16 v[4:7], v[178:181], v[230:233], v[4:7]
	s_setprio 0
	s_setprio 1
	v_mfma_f32_16x16x32_bf16 v[56:59], v[182:185], v[198:201], v[56:59]
	v_mfma_f32_16x16x32_bf16 v[48:51], v[190:193], v[198:201], v[48:51]
	v_mfma_f32_16x16x32_bf16 v[40:43], v[182:185], v[206:209], v[40:43]
	v_mfma_f32_16x16x32_bf16 v[32:35], v[190:193], v[206:209], v[32:35]
	v_mfma_f32_16x16x32_bf16 v[24:27], v[182:185], v[214:217], v[24:27]
	v_mfma_f32_16x16x32_bf16 v[16:19], v[190:193], v[214:217], v[16:19]
	v_mfma_f32_16x16x32_bf16 v[8:11], v[182:185], v[226:229], v[8:11]
	v_mfma_f32_16x16x32_bf16 v[0:3], v[190:193], v[226:229], v[0:3]
	v_mfma_f32_16x16x32_bf16 v[56:59], v[186:189], v[202:205], v[56:59]
	v_mfma_f32_16x16x32_bf16 v[48:51], v[194:197], v[202:205], v[48:51]
	v_mfma_f32_16x16x32_bf16 v[40:43], v[186:189], v[210:213], v[40:43]
	v_mfma_f32_16x16x32_bf16 v[32:35], v[194:197], v[210:213], v[32:35]
	v_mfma_f32_16x16x32_bf16 v[24:27], v[186:189], v[222:225], v[24:27]
	v_mfma_f32_16x16x32_bf16 v[16:19], v[194:197], v[222:225], v[16:19]
	v_mfma_f32_16x16x32_bf16 v[8:11], v[186:189], v[230:233], v[8:11]
	v_mfma_f32_16x16x32_bf16 v[0:3], v[194:197], v[230:233], v[0:3]
	s_setprio 0
	s_barrier
	s_add_i32 s52, 0, 0x18000
	s_add_i32 s53, 0, 0x1c000
	v_add_u32_e32 v178, s52, v160
	v_add_u32_e32 v194, s53, v160
	ds_read_b128 v[166:169], v178
	ds_read_b128 v[170:173], v178 offset:1024
	ds_read_b128 v[174:177], v178 offset:2048
	ds_read_b128 v[178:181], v178 offset:3072
	ds_read_b128 v[182:185], v194
	ds_read_b128 v[186:189], v194 offset:1024
	ds_read_b128 v[190:193], v194 offset:2048
	ds_read_b128 v[194:197], v194 offset:3072
	s_add_u32 s28, s28, 0x80000
	s_addc_u32 s29, s29, 0
	s_mov_b32 m0, s36
	ds_read_b128 v[198:201], v164 offset:32768
	ds_read_b128 v[202:205], v164 offset:33792
	ds_read_b128 v[206:209], v164 offset:34816
	ds_read_b128 v[210:213], v164 offset:35840
	ds_read_b128 v[214:217], v164 offset:36864
	ds_read_b128 v[222:225], v164 offset:37888
	ds_read_b128 v[226:229], v164 offset:38912
	ds_read_b128 v[230:233], v164 offset:39936
	global_load_lds_dwordx4 v134, s[28:29]
	s_mov_b32 m0, s37
	s_nop 0
	global_load_lds_dwordx4 v130, s[28:29]
	s_cmp_lg_u32 s100, 0
	s_cbranch_scc1 .Lgr_p7_2
	s_waitcnt vmcnt(8)
; #define PG8_STAGE(bufoff, gbase, voff) do { _Pragma("unroll") for (int _i = 0; _i < 2; ++_i) \
;         __builtin_amdgcn_global_load_lds((const unsigned*)((const char*)(gbase) + (voff)[_i]), (PG8_LAS unsigned*)(lds + (bufoff) + ldsw + _i * 8192), 16, 0, 0); } while (0)
; #define PG8_LDA(dst, b, h) do { _Pragma("unroll") for (int m = 0; m < 4; ++m) _Pragma("unroll") for (int k = 0; k < 2; ++k) dst[m][k] = *(const PG8_LAS bf16x8*)(lds + PG8_SA(b, h) + aoff + m * 2048 + k * 1024); } while (0)
; #define PG8_MMA(ai, bj, At, Bt) do { __builtin_amdgcn_s_setprio(1); _Pragma("unroll") for (int m = 0; m < 4; ++m) _Pragma("unroll") for (int n = 0; n < 2; ++n) _Pragma("unroll") for (int k = 0; k < 2; ++k) \
;         acc[ai][bj][m][n] = __builtin_amdgcn_mfma_f32_16x16x32_bf16(Bt[n][k], At[m][k], acc[ai][bj][m][n], 0, 0, 0); __builtin_amdgcn_s_setprio(0); } while (0)
; #define PG8_WAIT_V(n) asm volatile("s_waitcnt vmcnt(" #n ")" ::: "memory")
; #define PG8_WAIT_L(n) asm volatile("s_waitcnt lgkmcnt(" #n ")" ::: "memory")
; #define PG8_BAR __builtin_amdgcn_s_barrier()
; #define PG8_SCHED __builtin_amdgcn_sched_barrier(0)
; template <class Epi, class Sched, bool ALIGN_EPI = false, bool SP2 = false>
; __device__ __forceinline__ void gemm_phase(PG8_LAS unsigned char* lds, const Gemm g, const Sched& S, const Epi& E) {
;     ...
;             PG8_WAIT_V(8); PG8_WAIT_L(0); PG8_BAR; PG8_MMA(0, 0, At, B0); PG8_MMA(0, 1, At, B1); PG8_BAR; PG8_SCHED;
;             PG8_LDA(At, 1, 1); PG8_STAGE(PG8_SB(1, 0), b3, voffB); PG8_STAGE(PG8_SB(1, 1), b3 + hstep, voffB); PG8_STAGE(PG8_SA(1, 0), a3, voffA);
;             PG8_WAIT_V(8); PG8_WAIT_L(0); PG8_BAR; PG8_MMA(1, 0, At, B0); PG8_MMA(1, 1, At, B1); PG8_BAR; PG8_SCHED;
.Lgr_p7_2:
	s_waitcnt lgkmcnt(0)
	s_barrier
	s_setprio 1
	s_waitcnt lgkmcnt(0)
	v_mfma_f32_16x16x32_bf16 v[116:119], v[166:169], v[198:201], v[116:119]
	v_mfma_f32_16x16x32_bf16 v[112:115], v[174:177], v[198:201], v[112:115]
	v_mfma_f32_16x16x32_bf16 v[108:111], v[166:169], v[206:209], v[108:111]
	v_mfma_f32_16x16x32_bf16 v[100:103], v[174:177], v[206:209], v[100:103]
	v_mfma_f32_16x16x32_bf16 v[92:95], v[166:169], v[214:217], v[92:95]
	v_mfma_f32_16x16x32_bf16 v[84:87], v[174:177], v[214:217], v[84:87]
	v_mfma_f32_16x16x32_bf16 v[76:79], v[166:169], v[226:229], v[76:79]
	v_mfma_f32_16x16x32_bf16 v[68:71], v[174:177], v[226:229], v[68:71]
	v_mfma_f32_16x16x32_bf16 v[116:119], v[170:173], v[202:205], v[116:119]
	v_mfma_f32_16x16x32_bf16 v[112:115], v[178:181], v[202:205], v[112:115]
	v_mfma_f32_16x16x32_bf16 v[108:111], v[170:173], v[210:213], v[108:111]
	v_mfma_f32_16x16x32_bf16 v[100:103], v[178:181], v[210:213], v[100:103]
	v_mfma_f32_16x16x32_bf16 v[92:95], v[170:173], v[222:225], v[92:95]
	v_mfma_f32_16x16x32_bf16 v[84:87], v[178:181], v[222:225], v[84:87]
	v_mfma_f32_16x16x32_bf16 v[76:79], v[170:173], v[230:233], v[76:79]
	v_mfma_f32_16x16x32_bf16 v[68:71], v[178:181], v[230:233], v[68:71]
	s_setprio 0
	s_setprio 1
	v_mfma_f32_16x16x32_bf16 v[124:127], v[182:185], v[198:201], v[124:127]
	v_mfma_f32_16x16x32_bf16 v[120:123], v[190:193], v[198:201], v[120:123]
	v_mfma_f32_16x16x32_bf16 v[104:107], v[182:185], v[206:209], v[104:107]
	v_mfma_f32_16x16x32_bf16 v[96:99], v[190:193], v[206:209], v[96:99]
	v_mfma_f32_16x16x32_bf16 v[88:91], v[182:185], v[214:217], v[88:91]
	v_mfma_f32_16x16x32_bf16 v[80:83], v[190:193], v[214:217], v[80:83]
	v_mfma_f32_16x16x32_bf16 v[72:75], v[182:185], v[226:229], v[72:75]
	v_mfma_f32_16x16x32_bf16 v[64:67], v[190:193], v[226:229], v[64:67]
	v_mfma_f32_16x16x32_bf16 v[124:127], v[186:189], v[202:205], v[124:127]
	v_mfma_f32_16x16x32_bf16 v[120:123], v[194:197], v[202:205], v[120:123]
	v_mfma_f32_16x16x32_bf16 v[104:107], v[186:189], v[210:213], v[104:107]
	v_mfma_f32_16x16x32_bf16 v[96:99], v[194:197], v[210:213], v[96:99]
	v_mfma_f32_16x16x32_bf16 v[88:91], v[186:189], v[222:225], v[88:91]
	v_mfma_f32_16x16x32_bf16 v[80:83], v[194:197], v[222:225], v[80:83]
	v_mfma_f32_16x16x32_bf16 v[72:75], v[186:189], v[230:233], v[72:75]
	v_mfma_f32_16x16x32_bf16 v[64:67], v[194:197], v[230:233], v[64:67]
	s_setprio 0
	s_barrier
	s_add_i32 s28, s52, s30
	s_mov_b32 m0, s28
	ds_read_b128 v[198:201], v164 offset:49152
	ds_read_b128 v[202:205], v164 offset:50176
	ds_read_b128 v[206:209], v164 offset:51200
	ds_read_b128 v[210:213], v164 offset:52224
	ds_read_b128 v[214:217], v164 offset:53248
	ds_read_b128 v[222:225], v164 offset:54272
	ds_read_b128 v[226:229], v164 offset:55296
	ds_read_b128 v[230:233], v164 offset:56320
	global_load_lds_dwordx4 v132, vcc
	s_add_i32 m0, s28, 0x2000
	s_add_u32 s26, s26, 0x80080
	s_addc_u32 s27, s27, 0
	s_add_i32 s28, s53, s30
	global_load_lds_dwordx4 v128, vcc
	s_mov_b32 m0, s28
	s_nop 0
	global_load_lds_dwordx4 v132, s[26:27]
	s_add_i32 m0, s28, 0x2000
	s_nop 0
	global_load_lds_dwordx4 v128, s[26:27]
	s_mov_b32 m0, s39
	s_nop 0
	global_load_lds_dwordx4 v134, s[98:99]
	s_mov_b32 m0, s40
	s_nop 0
	global_load_lds_dwordx4 v130, s[98:99]
	s_waitcnt vmcnt(8)
	s_waitcnt lgkmcnt(0)
	s_barrier
	s_setprio 1
	s_waitcnt lgkmcnt(0)
	v_mfma_f32_16x16x32_bf16 v[60:63], v[166:169], v[198:201], v[60:63]
	v_mfma_f32_16x16x32_bf16 v[52:55], v[174:177], v[198:201], v[52:55]
	v_mfma_f32_16x16x32_bf16 v[44:47], v[166:169], v[206:209], v[44:47]
	v_mfma_f32_16x16x32_bf16 v[36:39], v[174:177], v[206:209], v[36:39]
	v_mfma_f32_16x16x32_bf16 v[28:31], v[166:169], v[214:217], v[28:31]
	v_mfma_f32_16x16x32_bf16 v[20:23], v[174:177], v[214:217], v[20:23]
	v_mfma_f32_16x16x32_bf16 v[12:15], v[166:169], v[226:229], v[12:15]
	v_mfma_f32_16x16x32_bf16 v[4:7], v[174:177], v[226:229], v[4:7]
	v_mfma_f32_16x16x32_bf16 v[60:63], v[170:173], v[202:205], v[60:63]
	v_mfma_f32_16x16x32_bf16 v[52:55], v[178:181], v[202:205], v[52:55]
	v_mfma_f32_16x16x32_bf16 v[44:47], v[170:173], v[210:213], v[44:47]
	v_mfma_f32_16x16x32_bf16 v[36:39], v[178:181], v[210:213], v[36:39]
	v_mfma_f32_16x16x32_bf16 v[28:31], v[170:173], v[222:225], v[28:31]
	v_mfma_f32_16x16x32_bf16 v[20:23], v[178:181], v[222:225], v[20:23]
	v_mfma_f32_16x16x32_bf16 v[12:15], v[170:173], v[230:233], v[12:15]
	v_mfma_f32_16x16x32_bf16 v[4:7], v[178:181], v[230:233], v[4:7]
	s_setprio 0
	s_setprio 1
	v_mfma_f32_16x16x32_bf16 v[56:59], v[182:185], v[198:201], v[56:59]
	v_mfma_f32_16x16x32_bf16 v[48:51], v[190:193], v[198:201], v[48:51]
	v_mfma_f32_16x16x32_bf16 v[40:43], v[182:185], v[206:209], v[40:43]
	v_mfma_f32_16x16x32_bf16 v[32:35], v[190:193], v[206:209], v[32:35]
	v_mfma_f32_16x16x32_bf16 v[24:27], v[182:185], v[214:217], v[24:27]
	v_mfma_f32_16x16x32_bf16 v[16:19], v[190:193], v[214:217], v[16:19]
	v_mfma_f32_16x16x32_bf16 v[8:11], v[182:185], v[226:229], v[8:11]
	v_mfma_f32_16x16x32_bf16 v[0:3], v[190:193], v[226:229], v[0:3]
	v_mfma_f32_16x16x32_bf16 v[56:59], v[186:189], v[202:205], v[56:59]
	v_mfma_f32_16x16x32_bf16 v[48:51], v[194:197], v[202:205], v[48:51]
	v_mfma_f32_16x16x32_bf16 v[40:43], v[186:189], v[210:213], v[40:43]
	v_mfma_f32_16x16x32_bf16 v[32:35], v[194:197], v[210:213], v[32:35]
	v_mfma_f32_16x16x32_bf16 v[24:27], v[186:189], v[222:225], v[24:27]
	v_mfma_f32_16x16x32_bf16 v[16:19], v[194:197], v[222:225], v[16:19]
	v_mfma_f32_16x16x32_bf16 v[8:11], v[186:189], v[230:233], v[8:11]
	v_mfma_f32_16x16x32_bf16 v[0:3], v[194:197], v[230:233], v[0:3]
	s_setprio 0
	s_barrier
	s_mov_b32 s100, 0
	s_add_i32 s51, s51, 2
	s_add_u32 s24, s24, 0x100
	s_addc_u32 s25, s25, 0
	s_add_u32 s49, s49, 0x100
	s_addc_u32 s50, s50, 0
	s_cmp_gt_u32 s51, 29
	s_cbranch_scc0 .LBB0_1076
	s_and_b64 vcc, exec, s[14:15]
	s_cbranch_vccz .LBB0_1079
	s_barrier

; #define PG8_STAGE(bufoff, gbase, voff) do { _Pragma("unroll") for (int _i = 0; _i < 2; ++_i) \
;         __builtin_amdgcn_global_load_lds((const unsigned*)((const char*)(gbase) + (voff)[_i]), (PG8_LAS unsigned*)(lds + (bufoff) + ldsw + _i * 8192), 16, 0, 0); } while (0)
; #define PG8_LDA(dst, b, h) do { _Pragma("unroll") for (int m = 0; m < 4; ++m) _Pragma("unroll") for (int k = 0; k < 2; ++k) dst[m][k] = *(const PG8_LAS bf16x8*)(lds + PG8_SA(b, h) + aoff + m * 2048 + k * 1024); } while (0)
; #define PG8_LDB(dst, b, h) do { _Pragma("unroll") for (int n = 0; n < 2; ++n) _Pragma("unroll") for (int k = 0; k < 2; ++k) dst[n][k] = *(const PG8_LAS bf16x8*)(lds + PG8_SB(b, h) + boff + n * 2048 + k * 1024); } while (0)
; #define PG8_MMA(ai, bj, At, Bt) do { __builtin_amdgcn_s_setprio(1); _Pragma("unroll") for (int m = 0; m < 4; ++m) _Pragma("unroll") for (int n = 0; n < 2; ++n) _Pragma("unroll") for (int k = 0; k < 2; ++k) \
;         acc[ai][bj][m][n] = __builtin_amdgcn_mfma_f32_16x16x32_bf16(Bt[n][k], At[m][k], acc[ai][bj][m][n], 0, 0, 0); __builtin_amdgcn_s_setprio(0); } while (0)
; #define PG8_WAIT_V(n) asm volatile("s_waitcnt vmcnt(" #n ")" ::: "memory")
; #define PG8_WAIT_L(n) asm volatile("s_waitcnt lgkmcnt(" #n ")" ::: "memory")
; template <class Epi, class Sched, bool ALIGN_EPI = false, bool SP2 = false>
; __device__ __forceinline__ void gemm_phase(PG8_LAS unsigned char* lds, const Gemm g, const Sched& S, const Epi& E) {
;     ...
;             const bool last = (t == nt - 2);
;             const char* a1 = cA + (size_t)(t + 1) * kstep;
;             const char* a2 = last ? nA : cA + (size_t)(t + 2) * kstep; const char* b2 = last ? nB : cB + (size_t)(t + 2) * kstep;
;             const char* a3 = a2 + kstep; const char* b3 = b2 + kstep;
;             if (last && has_next) S.a_ready(nxt);
;             if constexpr (SP2) {
;             PG8_LDB(B0, 0, 0); PG8_LDB(B1, 0, 1); PG8_SCHED; PG8_LDA(At, 0, 0); PG8_STAGE(PG8_SA(1, 1), a1 + hstep, voffA);
;             PG8_WAIT_V(8); PG8_WAIT_L(0); PG8_BAR; PG8_MMA(0, 0, At, B0); PG8_MMA(0, 1, At, B1); PG8_BAR; PG8_SCHED;
;             PG8_LDA(At, 0, 1); PG8_STAGE(PG8_SB(0, 0), b2, voffB); PG8_STAGE(PG8_SB(0, 1), b2 + hstep, voffB); PG8_STAGE(PG8_SA(0, 0), a2, voffA);
;             PG8_WAIT_V(8); PG8_WAIT_L(0); PG8_BAR; PG8_MMA(1, 0, At, B0); PG8_MMA(1, 1, At, B1); PG8_BAR; PG8_SCHED;
.LBB0_1204:
	ds_read_b128 v[128:131], v213
	ds_read_b128 v[132:135], v213 offset:1024
	ds_read_b128 v[136:139], v213 offset:2048
	ds_read_b128 v[140:143], v213 offset:3072
	ds_read_b128 v[144:147], v214
	ds_read_b128 v[148:151], v214 offset:1024
	ds_read_b128 v[152:155], v214 offset:2048
	ds_read_b128 v[156:159], v214 offset:3072
	s_add_u32 s22, s20, 0xffea0080
	s_addc_u32 s23, s21, -1
	s_cmpk_eq_i32 s46, 0x54
	s_cselect_b32 s25, s5, s23
	s_cselect_b32 s24, s4, s22
	s_cselect_b32 s23, s19, s45
	s_cselect_b32 s22, s18, s44
	s_add_i32 m0, s27, 0xc000
	ds_read_b128 v[160:163], v215
	ds_read_b128 v[164:167], v215 offset:1024
	ds_read_b128 v[168:171], v215 offset:2048
	ds_read_b128 v[172:175], v215 offset:3072
	ds_read_b128 v[192:195], v215 offset:4096
	ds_read_b128 v[196:199], v215 offset:5120
	ds_read_b128 v[200:203], v215 offset:6144
	ds_read_b128 v[204:207], v215 offset:7168
	global_load_lds_dwordx4 v184, s[20:21]
	s_add_i32 m0, s27, 0xe000
	s_nop 0
	global_load_lds_dwordx4 v186, s[20:21]
	s_waitcnt vmcnt(8)
	s_waitcnt lgkmcnt(0)
	s_barrier
	s_setprio 1
	s_waitcnt lgkmcnt(0)
	v_mfma_f32_16x16x32_bf16 v[124:127], v[128:131], v[160:163], v[124:127]
	v_mfma_f32_16x16x32_bf16 v[120:123], v[136:139], v[160:163], v[120:123]
	v_mfma_f32_16x16x32_bf16 v[108:111], v[128:131], v[168:171], v[108:111]
	v_mfma_f32_16x16x32_bf16 v[104:107], v[136:139], v[168:171], v[104:107]
	v_mfma_f32_16x16x32_bf16 v[92:95], v[128:131], v[192:195], v[92:95]
	v_mfma_f32_16x16x32_bf16 v[88:91], v[136:139], v[192:195], v[88:91]
	v_mfma_f32_16x16x32_bf16 v[76:79], v[128:131], v[200:203], v[76:79]
	v_mfma_f32_16x16x32_bf16 v[72:75], v[136:139], v[200:203], v[72:75]
	v_mfma_f32_16x16x32_bf16 v[124:127], v[132:135], v[164:167], v[124:127]
	v_mfma_f32_16x16x32_bf16 v[120:123], v[140:143], v[164:167], v[120:123]
	v_mfma_f32_16x16x32_bf16 v[108:111], v[132:135], v[172:175], v[108:111]
	v_mfma_f32_16x16x32_bf16 v[104:107], v[140:143], v[172:175], v[104:107]
	v_mfma_f32_16x16x32_bf16 v[92:95], v[132:135], v[196:199], v[92:95]
	v_mfma_f32_16x16x32_bf16 v[88:91], v[140:143], v[196:199], v[88:91]
	v_mfma_f32_16x16x32_bf16 v[76:79], v[132:135], v[204:207], v[76:79]
	v_mfma_f32_16x16x32_bf16 v[72:75], v[140:143], v[204:207], v[72:75]
	s_setprio 0
	s_setprio 1
	v_mfma_f32_16x16x32_bf16 v[116:119], v[144:147], v[160:163], v[116:119]
	v_mfma_f32_16x16x32_bf16 v[112:115], v[152:155], v[160:163], v[112:115]
	v_mfma_f32_16x16x32_bf16 v[100:103], v[144:147], v[168:171], v[100:103]
	v_mfma_f32_16x16x32_bf16 v[96:99], v[152:155], v[168:171], v[96:99]
	v_mfma_f32_16x16x32_bf16 v[84:87], v[144:147], v[192:195], v[84:87]
	v_mfma_f32_16x16x32_bf16 v[80:83], v[152:155], v[192:195], v[80:83]
	v_mfma_f32_16x16x32_bf16 v[68:71], v[144:147], v[200:203], v[68:71]
	v_mfma_f32_16x16x32_bf16 v[64:67], v[152:155], v[200:203], v[64:67]
	v_mfma_f32_16x16x32_bf16 v[116:119], v[148:151], v[164:167], v[116:119]
	v_mfma_f32_16x16x32_bf16 v[112:115], v[156:159], v[164:167], v[112:115]
	v_mfma_f32_16x16x32_bf16 v[100:103], v[148:151], v[172:175], v[100:103]
	v_mfma_f32_16x16x32_bf16 v[96:99], v[156:159], v[172:175], v[96:99]
	v_mfma_f32_16x16x32_bf16 v[84:87], v[148:151], v[196:199], v[84:87]
	v_mfma_f32_16x16x32_bf16 v[80:83], v[156:159], v[196:199], v[80:83]
	v_mfma_f32_16x16x32_bf16 v[68:71], v[148:151], v[204:207], v[68:71]
	v_mfma_f32_16x16x32_bf16 v[64:67], v[156:159], v[204:207], v[64:67]
	s_setprio 0
	s_barrier
	s_add_i32 s47, s38, s26
	s_add_u32 vcc_lo, s22, 0x80
	s_addc_u32 vcc_hi, s23, 0
	s_mov_b32 m0, s47
	ds_read_b128 v[160:163], v215 offset:16384
	ds_read_b128 v[164:167], v215 offset:17408
	ds_read_b128 v[168:171], v215 offset:18432
	ds_read_b128 v[172:175], v215 offset:19456
	ds_read_b128 v[192:195], v215 offset:20480
	ds_read_b128 v[196:199], v215 offset:21504
	ds_read_b128 v[200:203], v215 offset:22528
	ds_read_b128 v[204:207], v215 offset:23552
	global_load_lds_dwordx4 v178, s[22:23]
	s_add_i32 m0, s47, 0x2000
	s_add_u32 s48, s22, 0x160000
	s_addc_u32 s49, s23, 0
	s_add_i32 s47, s39, s26
	global_load_lds_dwordx4 v182, s[22:23]
	s_mov_b32 m0, s47
	s_nop 0
	global_load_lds_dwordx4 v178, s[48:49]
	s_add_i32 m0, s47, 0x2000
	s_nop 0
	global_load_lds_dwordx4 v182, s[48:49]
	s_add_u32 s98, s24, 0x80
	s_addc_u32 s99, s25, 0
	s_mov_b32 m0, s27
	s_nop 0
	global_load_lds_dwordx4 v176, s[24:25]
	s_mov_b32 m0, s28
	s_nop 0
	global_load_lds_dwordx4 v180, s[24:25]
	s_waitcnt vmcnt(8)
	s_waitcnt lgkmcnt(0)
	s_barrier
	s_setprio 1
	s_waitcnt lgkmcnt(0)
	v_mfma_f32_16x16x32_bf16 v[60:63], v[128:131], v[160:163], v[60:63]
	v_mfma_f32_16x16x32_bf16 v[56:59], v[136:139], v[160:163], v[56:59]
	v_mfma_f32_16x16x32_bf16 v[44:47], v[128:131], v[168:171], v[44:47]
	v_mfma_f32_16x16x32_bf16 v[40:43], v[136:139], v[168:171], v[40:43]
	v_mfma_f32_16x16x32_bf16 v[28:31], v[128:131], v[192:195], v[28:31]
	v_mfma_f32_16x16x32_bf16 v[24:27], v[136:139], v[192:195], v[24:27]
	v_mfma_f32_16x16x32_bf16 v[12:15], v[128:131], v[200:203], v[12:15]
	v_mfma_f32_16x16x32_bf16 v[8:11], v[136:139], v[200:203], v[8:11]
	v_mfma_f32_16x16x32_bf16 v[60:63], v[132:135], v[164:167], v[60:63]
	v_mfma_f32_16x16x32_bf16 v[56:59], v[140:143], v[164:167], v[56:59]
	v_mfma_f32_16x16x32_bf16 v[44:47], v[132:135], v[172:175], v[44:47]
	v_mfma_f32_16x16x32_bf16 v[40:43], v[140:143], v[172:175], v[40:43]
	v_mfma_f32_16x16x32_bf16 v[28:31], v[132:135], v[196:199], v[28:31]
	v_mfma_f32_16x16x32_bf16 v[24:27], v[140:143], v[196:199], v[24:27]
	v_mfma_f32_16x16x32_bf16 v[12:15], v[132:135], v[204:207], v[12:15]
	v_mfma_f32_16x16x32_bf16 v[8:11], v[140:143], v[204:207], v[8:11]
	s_setprio 0
	s_setprio 1
	v_mfma_f32_16x16x32_bf16 v[52:55], v[144:147], v[160:163], v[52:55]
	v_mfma_f32_16x16x32_bf16 v[48:51], v[152:155], v[160:163], v[48:51]
	v_mfma_f32_16x16x32_bf16 v[36:39], v[144:147], v[168:171], v[36:39]
	v_mfma_f32_16x16x32_bf16 v[32:35], v[152:155], v[168:171], v[32:35]
	v_mfma_f32_16x16x32_bf16 v[20:23], v[144:147], v[192:195], v[20:23]
	v_mfma_f32_16x16x32_bf16 v[16:19], v[152:155], v[192:195], v[16:19]
	v_mfma_f32_16x16x32_bf16 v[4:7], v[144:147], v[200:203], v[4:7]
	v_mfma_f32_16x16x32_bf16 v[0:3], v[152:155], v[200:203], v[0:3]
	v_mfma_f32_16x16x32_bf16 v[52:55], v[148:151], v[164:167], v[52:55]
	v_mfma_f32_16x16x32_bf16 v[48:51], v[156:159], v[164:167], v[48:51]
	v_mfma_f32_16x16x32_bf16 v[36:39], v[148:151], v[172:175], v[36:39]
	v_mfma_f32_16x16x32_bf16 v[32:35], v[156:159], v[172:175], v[32:35]
	v_mfma_f32_16x16x32_bf16 v[20:23], v[148:151], v[196:199], v[20:23]
	v_mfma_f32_16x16x32_bf16 v[16:19], v[156:159], v[196:199], v[16:19]
	v_mfma_f32_16x16x32_bf16 v[4:7], v[148:151], v[204:207], v[4:7]
	v_mfma_f32_16x16x32_bf16 v[0:3], v[156:159], v[204:207], v[0:3]
	s_setprio 0
	s_barrier
; #define PG8_STAGE(bufoff, gbase, voff) do { _Pragma("unroll") for (int _i = 0; _i < 2; ++_i) \
;         __builtin_amdgcn_global_load_lds((const unsigned*)((const char*)(gbase) + (voff)[_i]), (PG8_LAS unsigned*)(lds + (bufoff) + ldsw + _i * 8192), 16, 0, 0); } while (0)
; #define PG8_LDA(dst, b, h) do { _Pragma("unroll") for (int m = 0; m < 4; ++m) _Pragma("unroll") for (int k = 0; k < 2; ++k) dst[m][k] = *(const PG8_LAS bf16x8*)(lds + PG8_SA(b, h) + aoff + m * 2048 + k * 1024); } while (0)
; #define PG8_LDB(dst, b, h) do { _Pragma("unroll") for (int n = 0; n < 2; ++n) _Pragma("unroll") for (int k = 0; k < 2; ++k) dst[n][k] = *(const PG8_LAS bf16x8*)(lds + PG8_SB(b, h) + boff + n * 2048 + k * 1024); } while (0)
; #define PG8_MMA(ai, bj, At, Bt) do { __builtin_amdgcn_s_setprio(1); _Pragma("unroll") for (int m = 0; m < 4; ++m) _Pragma("unroll") for (int n = 0; n < 2; ++n) _Pragma("unroll") for (int k = 0; k < 2; ++k) \
;         acc[ai][bj][m][n] = __builtin_amdgcn_mfma_f32_16x16x32_bf16(Bt[n][k], At[m][k], acc[ai][bj][m][n], 0, 0, 0); __builtin_amdgcn_s_setprio(0); } while (0)
; #define PG8_WAIT_V(n) asm volatile("s_waitcnt vmcnt(" #n ")" ::: "memory")
; #define PG8_WAIT_L(n) asm volatile("s_waitcnt lgkmcnt(" #n ")" ::: "memory")
; #define PG8_BAR __builtin_amdgcn_s_barrier()
; #define PG8_SCHED __builtin_amdgcn_sched_barrier(0)
; template <class Epi, class Sched, bool ALIGN_EPI = false, bool SP2 = false>
; __device__ __forceinline__ void gemm_phase(PG8_LAS unsigned char* lds, const Gemm g, const Sched& S, const Epi& E) {
;     ...
;             PG8_LDB(B0, 1, 0); PG8_LDB(B1, 1, 1); PG8_SCHED; PG8_LDA(At, 1, 0); PG8_STAGE(PG8_SA(0, 1), a2 + hstep, voffA);
;             PG8_WAIT_V(8); PG8_WAIT_L(0); PG8_BAR; PG8_MMA(0, 0, At, B0); PG8_MMA(0, 1, At, B1); PG8_BAR; PG8_SCHED;
;             PG8_LDA(At, 1, 1); PG8_STAGE(PG8_SB(1, 0), b3, voffB); PG8_STAGE(PG8_SB(1, 1), b3 + hstep, voffB); PG8_STAGE(PG8_SA(1, 0), a3, voffA);
;             PG8_WAIT_V(8); PG8_WAIT_L(0); PG8_BAR; PG8_MMA(1, 0, At, B0); PG8_MMA(1, 1, At, B1); PG8_BAR; PG8_SCHED;
	s_add_i32 s47, 0, 0x18000
	s_add_i32 s48, 0, 0x1c000
	v_add_u32_e32 v140, s47, v211
	v_add_u32_e32 v156, s48, v211
	ds_read_b128 v[128:131], v140
	ds_read_b128 v[132:135], v140 offset:1024
	ds_read_b128 v[136:139], v140 offset:2048
	ds_read_b128 v[140:143], v140 offset:3072
	ds_read_b128 v[144:147], v156
	ds_read_b128 v[148:151], v156 offset:1024
	ds_read_b128 v[152:155], v156 offset:2048
	ds_read_b128 v[156:159], v156 offset:3072
	s_add_u32 s24, s24, 0x160000
	s_addc_u32 s25, s25, 0
	s_mov_b32 m0, s29
	ds_read_b128 v[160:163], v215 offset:32768
	ds_read_b128 v[164:167], v215 offset:33792
	ds_read_b128 v[168:171], v215 offset:34816
	ds_read_b128 v[172:175], v215 offset:35840
	ds_read_b128 v[192:195], v215 offset:36864
	ds_read_b128 v[196:199], v215 offset:37888
	ds_read_b128 v[200:203], v215 offset:38912
	ds_read_b128 v[204:207], v215 offset:39936
	global_load_lds_dwordx4 v176, s[24:25]
	s_mov_b32 m0, s30
	s_nop 0
	global_load_lds_dwordx4 v180, s[24:25]
	s_waitcnt vmcnt(8)
	s_waitcnt lgkmcnt(0)
	s_barrier
	s_setprio 1
	s_waitcnt lgkmcnt(0)
	v_mfma_f32_16x16x32_bf16 v[124:127], v[128:131], v[160:163], v[124:127]
	v_mfma_f32_16x16x32_bf16 v[120:123], v[136:139], v[160:163], v[120:123]
	v_mfma_f32_16x16x32_bf16 v[108:111], v[128:131], v[168:171], v[108:111]
	v_mfma_f32_16x16x32_bf16 v[104:107], v[136:139], v[168:171], v[104:107]
	v_mfma_f32_16x16x32_bf16 v[92:95], v[128:131], v[192:195], v[92:95]
	v_mfma_f32_16x16x32_bf16 v[88:91], v[136:139], v[192:195], v[88:91]
	v_mfma_f32_16x16x32_bf16 v[76:79], v[128:131], v[200:203], v[76:79]
	v_mfma_f32_16x16x32_bf16 v[72:75], v[136:139], v[200:203], v[72:75]
	v_mfma_f32_16x16x32_bf16 v[124:127], v[132:135], v[164:167], v[124:127]
	v_mfma_f32_16x16x32_bf16 v[120:123], v[140:143], v[164:167], v[120:123]
	v_mfma_f32_16x16x32_bf16 v[108:111], v[132:135], v[172:175], v[108:111]
	v_mfma_f32_16x16x32_bf16 v[104:107], v[140:143], v[172:175], v[104:107]
	v_mfma_f32_16x16x32_bf16 v[92:95], v[132:135], v[196:199], v[92:95]
	v_mfma_f32_16x16x32_bf16 v[88:91], v[140:143], v[196:199], v[88:91]
	v_mfma_f32_16x16x32_bf16 v[76:79], v[132:135], v[204:207], v[76:79]
	v_mfma_f32_16x16x32_bf16 v[72:75], v[140:143], v[204:207], v[72:75]
	s_setprio 0
	s_setprio 1
	v_mfma_f32_16x16x32_bf16 v[116:119], v[144:147], v[160:163], v[116:119]
	v_mfma_f32_16x16x32_bf16 v[112:115], v[152:155], v[160:163], v[112:115]
	v_mfma_f32_16x16x32_bf16 v[100:103], v[144:147], v[168:171], v[100:103]
	v_mfma_f32_16x16x32_bf16 v[96:99], v[152:155], v[168:171], v[96:99]
	v_mfma_f32_16x16x32_bf16 v[84:87], v[144:147], v[192:195], v[84:87]
	v_mfma_f32_16x16x32_bf16 v[80:83], v[152:155], v[192:195], v[80:83]
	v_mfma_f32_16x16x32_bf16 v[68:71], v[144:147], v[200:203], v[68:71]
	v_mfma_f32_16x16x32_bf16 v[64:67], v[152:155], v[200:203], v[64:67]
	v_mfma_f32_16x16x32_bf16 v[116:119], v[148:151], v[164:167], v[116:119]
	v_mfma_f32_16x16x32_bf16 v[112:115], v[156:159], v[164:167], v[112:115]
	v_mfma_f32_16x16x32_bf16 v[100:103], v[148:151], v[172:175], v[100:103]
	v_mfma_f32_16x16x32_bf16 v[96:99], v[156:159], v[172:175], v[96:99]
	v_mfma_f32_16x16x32_bf16 v[84:87], v[148:151], v[196:199], v[84:87]
	v_mfma_f32_16x16x32_bf16 v[80:83], v[156:159], v[196:199], v[80:83]
	v_mfma_f32_16x16x32_bf16 v[68:71], v[148:151], v[204:207], v[68:71]
	v_mfma_f32_16x16x32_bf16 v[64:67], v[156:159], v[204:207], v[64:67]
	s_setprio 0
	s_barrier
	s_add_i32 s24, s47, s26
	s_mov_b32 m0, s24
	ds_read_b128 v[160:163], v215 offset:49152
	ds_read_b128 v[164:167], v215 offset:50176
	ds_read_b128 v[168:171], v215 offset:51200
	ds_read_b128 v[172:175], v215 offset:52224
	ds_read_b128 v[192:195], v215 offset:53248
	ds_read_b128 v[196:199], v215 offset:54272
	ds_read_b128 v[200:203], v215 offset:55296
	ds_read_b128 v[204:207], v215 offset:56320
	global_load_lds_dwordx4 v178, vcc
	s_add_i32 m0, s24, 0x2000
	s_add_u32 s22, s22, 0x160080
	s_addc_u32 s23, s23, 0
	s_add_i32 s24, s48, s26
	global_load_lds_dwordx4 v182, vcc
	s_mov_b32 m0, s24
	s_nop 0
	global_load_lds_dwordx4 v178, s[22:23]
	s_add_i32 m0, s24, 0x2000
	s_nop 0
	global_load_lds_dwordx4 v182, s[22:23]
	s_mov_b32 m0, s33
	s_nop 0
	global_load_lds_dwordx4 v176, s[98:99]
	s_mov_b32 m0, s34
	s_nop 0
	global_load_lds_dwordx4 v180, s[98:99]
	s_waitcnt vmcnt(8)
	s_waitcnt lgkmcnt(0)
	s_barrier
	s_setprio 1
	s_waitcnt lgkmcnt(0)
	v_mfma_f32_16x16x32_bf16 v[60:63], v[128:131], v[160:163], v[60:63]
	v_mfma_f32_16x16x32_bf16 v[56:59], v[136:139], v[160:163], v[56:59]
	v_mfma_f32_16x16x32_bf16 v[44:47], v[128:131], v[168:171], v[44:47]
	v_mfma_f32_16x16x32_bf16 v[40:43], v[136:139], v[168:171], v[40:43]
	v_mfma_f32_16x16x32_bf16 v[28:31], v[128:131], v[192:195], v[28:31]
	v_mfma_f32_16x16x32_bf16 v[24:27], v[136:139], v[192:195], v[24:27]
	v_mfma_f32_16x16x32_bf16 v[12:15], v[128:131], v[200:203], v[12:15]
	v_mfma_f32_16x16x32_bf16 v[8:11], v[136:139], v[200:203], v[8:11]
	v_mfma_f32_16x16x32_bf16 v[60:63], v[132:135], v[164:167], v[60:63]
	v_mfma_f32_16x16x32_bf16 v[56:59], v[140:143], v[164:167], v[56:59]
	v_mfma_f32_16x16x32_bf16 v[44:47], v[132:135], v[172:175], v[44:47]
	v_mfma_f32_16x16x32_bf16 v[40:43], v[140:143], v[172:175], v[40:43]
	v_mfma_f32_16x16x32_bf16 v[28:31], v[132:135], v[196:199], v[28:31]
	v_mfma_f32_16x16x32_bf16 v[24:27], v[140:143], v[196:199], v[24:27]
	v_mfma_f32_16x16x32_bf16 v[12:15], v[132:135], v[204:207], v[12:15]
	v_mfma_f32_16x16x32_bf16 v[8:11], v[140:143], v[204:207], v[8:11]
	s_setprio 0
	s_setprio 1
	v_mfma_f32_16x16x32_bf16 v[52:55], v[144:147], v[160:163], v[52:55]
	v_mfma_f32_16x16x32_bf16 v[48:51], v[152:155], v[160:163], v[48:51]
	v_mfma_f32_16x16x32_bf16 v[36:39], v[144:147], v[168:171], v[36:39]
	v_mfma_f32_16x16x32_bf16 v[32:35], v[152:155], v[168:171], v[32:35]
	v_mfma_f32_16x16x32_bf16 v[20:23], v[144:147], v[192:195], v[20:23]
	v_mfma_f32_16x16x32_bf16 v[16:19], v[152:155], v[192:195], v[16:19]
	v_mfma_f32_16x16x32_bf16 v[4:7], v[144:147], v[200:203], v[4:7]
	v_mfma_f32_16x16x32_bf16 v[0:3], v[152:155], v[200:203], v[0:3]
	v_mfma_f32_16x16x32_bf16 v[52:55], v[148:151], v[164:167], v[52:55]
	v_mfma_f32_16x16x32_bf16 v[48:51], v[156:159], v[164:167], v[48:51]
	v_mfma_f32_16x16x32_bf16 v[36:39], v[148:151], v[172:175], v[36:39]
	v_mfma_f32_16x16x32_bf16 v[32:35], v[156:159], v[172:175], v[32:35]
	v_mfma_f32_16x16x32_bf16 v[20:23], v[148:151], v[196:199], v[20:23]
	v_mfma_f32_16x16x32_bf16 v[16:19], v[156:159], v[196:199], v[16:19]
	v_mfma_f32_16x16x32_bf16 v[4:7], v[148:151], v[204:207], v[4:7]
	v_mfma_f32_16x16x32_bf16 v[0:3], v[156:159], v[204:207], v[0:3]
	s_setprio 0
	s_barrier
	s_add_i32 s46, s46, 2
	s_add_u32 s20, s20, 0x100
	s_addc_u32 s21, s21, 0
	s_add_u32 s44, s44, 0x100
	s_addc_u32 s45, s45, 0
	s_cmpk_gt_u32 s46, 0x55
	s_cbranch_scc0 .LBB0_1204
	s_and_b64 vcc, exec, s[16:17]
	s_cbranch_vccz .LBB0_1207
	s_barrier

; #define PG8_STAGE(bufoff, gbase, voff) do { _Pragma("unroll") for (int _i = 0; _i < 2; ++_i) \
;         __builtin_amdgcn_global_load_lds((const unsigned*)((const char*)(gbase) + (voff)[_i]), (PG8_LAS unsigned*)(lds + (bufoff) + ldsw + _i * 8192), 16, 0, 0); } while (0)
; #define PG8_LDA(dst, b, h) do { _Pragma("unroll") for (int m = 0; m < 4; ++m) _Pragma("unroll") for (int k = 0; k < 2; ++k) dst[m][k] = *(const PG8_LAS bf16x8*)(lds + PG8_SA(b, h) + aoff + m * 2048 + k * 1024); } while (0)
; #define PG8_LDB(dst, b, h) do { _Pragma("unroll") for (int n = 0; n < 2; ++n) _Pragma("unroll") for (int k = 0; k < 2; ++k) dst[n][k] = *(const PG8_LAS bf16x8*)(lds + PG8_SB(b, h) + boff + n * 2048 + k * 1024); } while (0)
; #define PG8_MMA(ai, bj, At, Bt) do { __builtin_amdgcn_s_setprio(1); _Pragma("unroll") for (int m = 0; m < 4; ++m) _Pragma("unroll") for (int n = 0; n < 2; ++n) _Pragma("unroll") for (int k = 0; k < 2; ++k) \
;         acc[ai][bj][m][n] = __builtin_amdgcn_mfma_f32_16x16x32_bf16(Bt[n][k], At[m][k], acc[ai][bj][m][n], 0, 0, 0); __builtin_amdgcn_s_setprio(0); } while (0)
; #define PG8_WAIT_V(n) asm volatile("s_waitcnt vmcnt(" #n ")" ::: "memory")
; #define PG8_WAIT_L(n) asm volatile("s_waitcnt lgkmcnt(" #n ")" ::: "memory")
; template <class Epi, class Sched, bool ALIGN_EPI = false, bool SP2 = false>
; __device__ __forceinline__ void gemm_phase(PG8_LAS unsigned char* lds, const Gemm g, const Sched& S, const Epi& E) {
;     ...
;             const bool last = (t == nt - 2);
;             const char* a1 = cA + (size_t)(t + 1) * kstep;
;             const char* a2 = last ? nA : cA + (size_t)(t + 2) * kstep; const char* b2 = last ? nB : cB + (size_t)(t + 2) * kstep;
;             const char* a3 = a2 + kstep; const char* b3 = b2 + kstep;
;             if (last && has_next) S.a_ready(nxt);
;             if constexpr (SP2) {
;             PG8_LDB(B0, 0, 0); PG8_LDB(B1, 0, 1); PG8_SCHED; PG8_LDA(At, 0, 0); PG8_STAGE(PG8_SA(1, 1), a1 + hstep, voffA);
;             PG8_WAIT_V(8); PG8_WAIT_L(0); PG8_BAR; PG8_MMA(0, 0, At, B0); PG8_MMA(0, 1, At, B1); PG8_BAR; PG8_SCHED;
;             PG8_LDA(At, 0, 1); PG8_STAGE(PG8_SB(0, 0), b2, voffB); PG8_STAGE(PG8_SB(0, 1), b2 + hstep, voffB); PG8_STAGE(PG8_SA(0, 0), a2, voffA);
;             PG8_WAIT_V(8); PG8_WAIT_L(0); PG8_BAR; PG8_MMA(1, 0, At, B0); PG8_MMA(1, 1, At, B1); PG8_BAR; PG8_SCHED;
.LBB0_1295:
	ds_read_b128 v[56:59], v203
	ds_read_b128 v[64:67], v203 offset:1024
	ds_read_b128 v[72:75], v203 offset:2048
	ds_read_b128 v[76:79], v203 offset:3072
	ds_read_b128 v[144:147], v204
	ds_read_b128 v[148:151], v204 offset:1024
	ds_read_b128 v[152:155], v204 offset:2048
	ds_read_b128 v[156:159], v204 offset:3072
	s_add_u32 s36, s34, 0xfff80080
	s_addc_u32 s37, s35, -1
	s_cmp_eq_u32 s56, 28
	s_cselect_b32 s39, s27, s37
	s_cselect_b32 s38, s52, s36
	s_cselect_b32 s37, s25, s55
	s_cselect_b32 s36, s53, s54
	s_add_i32 m0, s41, 0xc000
	ds_read_b128 v[160:163], v205
	ds_read_b128 v[164:167], v205 offset:1024
	ds_read_b128 v[168:171], v205 offset:2048
	ds_read_b128 v[188:191], v205 offset:3072
	ds_read_b128 v[192:195], v205 offset:4096
	ds_read_b128 v[196:199], v205 offset:5120
	ds_read_b128 v[208:211], v205 offset:6144
	ds_read_b128 v[212:215], v205 offset:7168
	global_load_lds_dwordx4 v180, s[34:35]
	s_add_i32 m0, s41, 0xe000
	s_nop 0
	global_load_lds_dwordx4 v182, s[34:35]
	s_waitcnt vmcnt(8)
	s_waitcnt lgkmcnt(0)
	s_barrier
	s_setprio 1
	s_waitcnt lgkmcnt(0)
	v_mfma_f32_16x16x32_bf16 v[140:143], v[56:59], v[160:163], v[140:143]
	v_mfma_f32_16x16x32_bf16 v[136:139], v[72:75], v[160:163], v[136:139]
	v_mfma_f32_16x16x32_bf16 v[124:127], v[56:59], v[168:171], v[124:127]
	v_mfma_f32_16x16x32_bf16 v[120:123], v[72:75], v[168:171], v[120:123]
	v_mfma_f32_16x16x32_bf16 v[108:111], v[56:59], v[192:195], v[108:111]
	v_mfma_f32_16x16x32_bf16 v[104:107], v[72:75], v[192:195], v[104:107]
	v_mfma_f32_16x16x32_bf16 v[92:95], v[56:59], v[208:211], v[92:95]
	v_mfma_f32_16x16x32_bf16 v[88:91], v[72:75], v[208:211], v[88:91]
	v_mfma_f32_16x16x32_bf16 v[140:143], v[64:67], v[164:167], v[140:143]
	v_mfma_f32_16x16x32_bf16 v[136:139], v[76:79], v[164:167], v[136:139]
	v_mfma_f32_16x16x32_bf16 v[124:127], v[64:67], v[188:191], v[124:127]
	v_mfma_f32_16x16x32_bf16 v[120:123], v[76:79], v[188:191], v[120:123]
	v_mfma_f32_16x16x32_bf16 v[108:111], v[64:67], v[196:199], v[108:111]
	v_mfma_f32_16x16x32_bf16 v[104:107], v[76:79], v[196:199], v[104:107]
	v_mfma_f32_16x16x32_bf16 v[92:95], v[64:67], v[212:215], v[92:95]
	v_mfma_f32_16x16x32_bf16 v[88:91], v[76:79], v[212:215], v[88:91]
	s_setprio 0
	s_setprio 1
	v_mfma_f32_16x16x32_bf16 v[132:135], v[144:147], v[160:163], v[132:135]
	v_mfma_f32_16x16x32_bf16 v[128:131], v[152:155], v[160:163], v[128:131]
	v_mfma_f32_16x16x32_bf16 v[116:119], v[144:147], v[168:171], v[116:119]
	v_mfma_f32_16x16x32_bf16 v[112:115], v[152:155], v[168:171], v[112:115]
	v_mfma_f32_16x16x32_bf16 v[100:103], v[144:147], v[192:195], v[100:103]
	v_mfma_f32_16x16x32_bf16 v[96:99], v[152:155], v[192:195], v[96:99]
	v_mfma_f32_16x16x32_bf16 v[84:87], v[144:147], v[208:211], v[84:87]
	v_mfma_f32_16x16x32_bf16 v[80:83], v[152:155], v[208:211], v[80:83]
	v_mfma_f32_16x16x32_bf16 v[132:135], v[148:151], v[164:167], v[132:135]
	v_mfma_f32_16x16x32_bf16 v[128:131], v[156:159], v[164:167], v[128:131]
	v_mfma_f32_16x16x32_bf16 v[116:119], v[148:151], v[188:191], v[116:119]
	v_mfma_f32_16x16x32_bf16 v[112:115], v[156:159], v[188:191], v[112:115]
	v_mfma_f32_16x16x32_bf16 v[100:103], v[148:151], v[196:199], v[100:103]
	v_mfma_f32_16x16x32_bf16 v[96:99], v[156:159], v[196:199], v[96:99]
	v_mfma_f32_16x16x32_bf16 v[84:87], v[148:151], v[212:215], v[84:87]
	v_mfma_f32_16x16x32_bf16 v[80:83], v[156:159], v[212:215], v[80:83]
	s_setprio 0
	s_barrier
	s_add_i32 s57, s49, s40
	s_add_u32 vcc_lo, s36, 0x80
	s_addc_u32 vcc_hi, s37, 0
	s_mov_b32 m0, s57
	ds_read_b128 v[160:163], v205 offset:16384
	ds_read_b128 v[164:167], v205 offset:17408
	ds_read_b128 v[168:171], v205 offset:18432
	ds_read_b128 v[188:191], v205 offset:19456
	ds_read_b128 v[192:195], v205 offset:20480
	ds_read_b128 v[196:199], v205 offset:21504
	ds_read_b128 v[208:211], v205 offset:22528
	ds_read_b128 v[212:215], v205 offset:23552
	global_load_lds_dwordx4 v174, s[36:37]
	s_add_i32 m0, s57, 0x2000
	s_add_u32 s58, s36, 0x80000
	s_addc_u32 s59, s37, 0
	s_add_i32 s57, s50, s40
	global_load_lds_dwordx4 v178, s[36:37]
	s_mov_b32 m0, s57
	s_nop 0
	global_load_lds_dwordx4 v174, s[58:59]
	s_add_i32 m0, s57, 0x2000
	s_nop 0
	global_load_lds_dwordx4 v178, s[58:59]
	s_add_u32 s98, s38, 0x80
	s_addc_u32 s99, s39, 0
	s_mov_b32 m0, s41
	s_nop 0
	global_load_lds_dwordx4 v172, s[38:39]
	s_mov_b32 m0, s42
	s_nop 0
	global_load_lds_dwordx4 v176, s[38:39]
	s_waitcnt vmcnt(8)
	s_waitcnt lgkmcnt(0)
	s_barrier
	s_setprio 1
	s_waitcnt lgkmcnt(0)
	v_mfma_f32_16x16x32_bf16 v[68:71], v[56:59], v[160:163], v[68:71]
	v_mfma_f32_16x16x32_bf16 v[60:63], v[72:75], v[160:163], v[60:63]
	v_mfma_f32_16x16x32_bf16 v[44:47], v[56:59], v[168:171], v[44:47]
	v_mfma_f32_16x16x32_bf16 v[40:43], v[72:75], v[168:171], v[40:43]
	v_mfma_f32_16x16x32_bf16 v[28:31], v[56:59], v[192:195], v[28:31]
	v_mfma_f32_16x16x32_bf16 v[24:27], v[72:75], v[192:195], v[24:27]
	v_mfma_f32_16x16x32_bf16 v[12:15], v[56:59], v[208:211], v[12:15]
	v_mfma_f32_16x16x32_bf16 v[8:11], v[72:75], v[208:211], v[8:11]
	v_mfma_f32_16x16x32_bf16 v[68:71], v[64:67], v[164:167], v[68:71]
	v_mfma_f32_16x16x32_bf16 v[60:63], v[76:79], v[164:167], v[60:63]
	v_mfma_f32_16x16x32_bf16 v[44:47], v[64:67], v[188:191], v[44:47]
	v_mfma_f32_16x16x32_bf16 v[40:43], v[76:79], v[188:191], v[40:43]
	v_mfma_f32_16x16x32_bf16 v[28:31], v[64:67], v[196:199], v[28:31]
	v_mfma_f32_16x16x32_bf16 v[24:27], v[76:79], v[196:199], v[24:27]
	v_mfma_f32_16x16x32_bf16 v[12:15], v[64:67], v[212:215], v[12:15]
	v_mfma_f32_16x16x32_bf16 v[8:11], v[76:79], v[212:215], v[8:11]
	s_setprio 0
	s_setprio 1
	v_mfma_f32_16x16x32_bf16 v[52:55], v[144:147], v[160:163], v[52:55]
	v_mfma_f32_16x16x32_bf16 v[48:51], v[152:155], v[160:163], v[48:51]
	v_mfma_f32_16x16x32_bf16 v[36:39], v[144:147], v[168:171], v[36:39]
	v_mfma_f32_16x16x32_bf16 v[32:35], v[152:155], v[168:171], v[32:35]
	v_mfma_f32_16x16x32_bf16 v[20:23], v[144:147], v[192:195], v[20:23]
	v_mfma_f32_16x16x32_bf16 v[16:19], v[152:155], v[192:195], v[16:19]
	v_mfma_f32_16x16x32_bf16 v[4:7], v[144:147], v[208:211], v[4:7]
	v_mfma_f32_16x16x32_bf16 v[0:3], v[152:155], v[208:211], v[0:3]
	v_mfma_f32_16x16x32_bf16 v[52:55], v[148:151], v[164:167], v[52:55]
	v_mfma_f32_16x16x32_bf16 v[48:51], v[156:159], v[164:167], v[48:51]
	v_mfma_f32_16x16x32_bf16 v[36:39], v[148:151], v[188:191], v[36:39]
	v_mfma_f32_16x16x32_bf16 v[32:35], v[156:159], v[188:191], v[32:35]
	v_mfma_f32_16x16x32_bf16 v[20:23], v[148:151], v[196:199], v[20:23]
	v_mfma_f32_16x16x32_bf16 v[16:19], v[156:159], v[196:199], v[16:19]
	v_mfma_f32_16x16x32_bf16 v[4:7], v[148:151], v[212:215], v[4:7]
	v_mfma_f32_16x16x32_bf16 v[0:3], v[156:159], v[212:215], v[0:3]
	s_setprio 0
	s_barrier
; #define PG8_STAGE(bufoff, gbase, voff) do { _Pragma("unroll") for (int _i = 0; _i < 2; ++_i) \
;         __builtin_amdgcn_global_load_lds((const unsigned*)((const char*)(gbase) + (voff)[_i]), (PG8_LAS unsigned*)(lds + (bufoff) + ldsw + _i * 8192), 16, 0, 0); } while (0)
; #define PG8_LDA(dst, b, h) do { _Pragma("unroll") for (int m = 0; m < 4; ++m) _Pragma("unroll") for (int k = 0; k < 2; ++k) dst[m][k] = *(const PG8_LAS bf16x8*)(lds + PG8_SA(b, h) + aoff + m * 2048 + k * 1024); } while (0)
; #define PG8_LDB(dst, b, h) do { _Pragma("unroll") for (int n = 0; n < 2; ++n) _Pragma("unroll") for (int k = 0; k < 2; ++k) dst[n][k] = *(const PG8_LAS bf16x8*)(lds + PG8_SB(b, h) + boff + n * 2048 + k * 1024); } while (0)
; #define PG8_MMA(ai, bj, At, Bt) do { __builtin_amdgcn_s_setprio(1); _Pragma("unroll") for (int m = 0; m < 4; ++m) _Pragma("unroll") for (int n = 0; n < 2; ++n) _Pragma("unroll") for (int k = 0; k < 2; ++k) \
;         acc[ai][bj][m][n] = __builtin_amdgcn_mfma_f32_16x16x32_bf16(Bt[n][k], At[m][k], acc[ai][bj][m][n], 0, 0, 0); __builtin_amdgcn_s_setprio(0); } while (0)
; #define PG8_WAIT_V(n) asm volatile("s_waitcnt vmcnt(" #n ")" ::: "memory")
; #define PG8_WAIT_L(n) asm volatile("s_waitcnt lgkmcnt(" #n ")" ::: "memory")
; #define PG8_BAR __builtin_amdgcn_s_barrier()
; #define PG8_SCHED __builtin_amdgcn_sched_barrier(0)
; template <class Epi, class Sched, bool ALIGN_EPI = false, bool SP2 = false>
; __device__ __forceinline__ void gemm_phase(PG8_LAS unsigned char* lds, const Gemm g, const Sched& S, const Epi& E) {
;     ...
;             PG8_LDB(B0, 1, 0); PG8_LDB(B1, 1, 1); PG8_SCHED; PG8_LDA(At, 1, 0); PG8_STAGE(PG8_SA(0, 1), a2 + hstep, voffA);
;             PG8_WAIT_V(8); PG8_WAIT_L(0); PG8_BAR; PG8_MMA(0, 0, At, B0); PG8_MMA(0, 1, At, B1); PG8_BAR; PG8_SCHED;
;             PG8_LDA(At, 1, 1); PG8_STAGE(PG8_SB(1, 0), b3, voffB); PG8_STAGE(PG8_SB(1, 1), b3 + hstep, voffB); PG8_STAGE(PG8_SA(1, 0), a3, voffA);
;             PG8_WAIT_V(8); PG8_WAIT_L(0); PG8_BAR; PG8_MMA(1, 0, At, B0); PG8_MMA(1, 1, At, B1); PG8_BAR; PG8_SCHED;
	s_add_i32 s57, 0, 0x18000
	s_add_i32 s58, 0, 0x1c000
	v_add_u32_e32 v76, s57, v201
	v_add_u32_e32 v156, s58, v201
	ds_read_b128 v[56:59], v76
	ds_read_b128 v[64:67], v76 offset:1024
	ds_read_b128 v[72:75], v76 offset:2048
	ds_read_b128 v[76:79], v76 offset:3072
	ds_read_b128 v[144:147], v156
	ds_read_b128 v[148:151], v156 offset:1024
	ds_read_b128 v[152:155], v156 offset:2048
	ds_read_b128 v[156:159], v156 offset:3072
	s_add_u32 s38, s38, 0x80000
	s_addc_u32 s39, s39, 0
	s_mov_b32 m0, s43
	ds_read_b128 v[160:163], v205 offset:32768
	ds_read_b128 v[164:167], v205 offset:33792
	ds_read_b128 v[168:171], v205 offset:34816
	ds_read_b128 v[188:191], v205 offset:35840
	ds_read_b128 v[192:195], v205 offset:36864
	ds_read_b128 v[196:199], v205 offset:37888
	ds_read_b128 v[208:211], v205 offset:38912
	ds_read_b128 v[212:215], v205 offset:39936
	global_load_lds_dwordx4 v172, s[38:39]
	s_mov_b32 m0, s44
	s_nop 0
	global_load_lds_dwordx4 v176, s[38:39]
	s_waitcnt vmcnt(8)
	s_waitcnt lgkmcnt(0)
	s_barrier
	s_setprio 1
	s_waitcnt lgkmcnt(0)
	v_mfma_f32_16x16x32_bf16 v[140:143], v[56:59], v[160:163], v[140:143]
	v_mfma_f32_16x16x32_bf16 v[136:139], v[72:75], v[160:163], v[136:139]
	v_mfma_f32_16x16x32_bf16 v[124:127], v[56:59], v[168:171], v[124:127]
	v_mfma_f32_16x16x32_bf16 v[120:123], v[72:75], v[168:171], v[120:123]
	v_mfma_f32_16x16x32_bf16 v[108:111], v[56:59], v[192:195], v[108:111]
	v_mfma_f32_16x16x32_bf16 v[104:107], v[72:75], v[192:195], v[104:107]
	v_mfma_f32_16x16x32_bf16 v[92:95], v[56:59], v[208:211], v[92:95]
	v_mfma_f32_16x16x32_bf16 v[88:91], v[72:75], v[208:211], v[88:91]
	v_mfma_f32_16x16x32_bf16 v[140:143], v[64:67], v[164:167], v[140:143]
	v_mfma_f32_16x16x32_bf16 v[136:139], v[76:79], v[164:167], v[136:139]
	v_mfma_f32_16x16x32_bf16 v[124:127], v[64:67], v[188:191], v[124:127]
	v_mfma_f32_16x16x32_bf16 v[120:123], v[76:79], v[188:191], v[120:123]
	v_mfma_f32_16x16x32_bf16 v[108:111], v[64:67], v[196:199], v[108:111]
	v_mfma_f32_16x16x32_bf16 v[104:107], v[76:79], v[196:199], v[104:107]
	v_mfma_f32_16x16x32_bf16 v[92:95], v[64:67], v[212:215], v[92:95]
	v_mfma_f32_16x16x32_bf16 v[88:91], v[76:79], v[212:215], v[88:91]
	s_setprio 0
	s_setprio 1
	v_mfma_f32_16x16x32_bf16 v[132:135], v[144:147], v[160:163], v[132:135]
	v_mfma_f32_16x16x32_bf16 v[128:131], v[152:155], v[160:163], v[128:131]
	v_mfma_f32_16x16x32_bf16 v[116:119], v[144:147], v[168:171], v[116:119]
	v_mfma_f32_16x16x32_bf16 v[112:115], v[152:155], v[168:171], v[112:115]
	v_mfma_f32_16x16x32_bf16 v[100:103], v[144:147], v[192:195], v[100:103]
	v_mfma_f32_16x16x32_bf16 v[96:99], v[152:155], v[192:195], v[96:99]
	v_mfma_f32_16x16x32_bf16 v[84:87], v[144:147], v[208:211], v[84:87]
	v_mfma_f32_16x16x32_bf16 v[80:83], v[152:155], v[208:211], v[80:83]
	v_mfma_f32_16x16x32_bf16 v[132:135], v[148:151], v[164:167], v[132:135]
	v_mfma_f32_16x16x32_bf16 v[128:131], v[156:159], v[164:167], v[128:131]
	v_mfma_f32_16x16x32_bf16 v[116:119], v[148:151], v[188:191], v[116:119]
	v_mfma_f32_16x16x32_bf16 v[112:115], v[156:159], v[188:191], v[112:115]
	v_mfma_f32_16x16x32_bf16 v[100:103], v[148:151], v[196:199], v[100:103]
	v_mfma_f32_16x16x32_bf16 v[96:99], v[156:159], v[196:199], v[96:99]
	v_mfma_f32_16x16x32_bf16 v[84:87], v[148:151], v[212:215], v[84:87]
	v_mfma_f32_16x16x32_bf16 v[80:83], v[156:159], v[212:215], v[80:83]
	s_setprio 0
	s_barrier
	s_add_i32 s38, s57, s40
	s_mov_b32 m0, s38
	ds_read_b128 v[160:163], v205 offset:49152
	ds_read_b128 v[164:167], v205 offset:50176
	ds_read_b128 v[168:171], v205 offset:51200
	ds_read_b128 v[188:191], v205 offset:52224
	ds_read_b128 v[192:195], v205 offset:53248
	ds_read_b128 v[196:199], v205 offset:54272
	ds_read_b128 v[208:211], v205 offset:55296
	ds_read_b128 v[212:215], v205 offset:56320
	global_load_lds_dwordx4 v174, vcc
	s_add_i32 m0, s38, 0x2000
	s_add_u32 s36, s36, 0x80080
	s_addc_u32 s37, s37, 0
	s_add_i32 s38, s58, s40
	global_load_lds_dwordx4 v178, vcc
	s_mov_b32 m0, s38
	s_nop 0
	global_load_lds_dwordx4 v174, s[36:37]
	s_add_i32 m0, s38, 0x2000
	s_nop 0
	global_load_lds_dwordx4 v178, s[36:37]
	s_mov_b32 m0, s46
	s_nop 0
	global_load_lds_dwordx4 v172, s[98:99]
	s_mov_b32 m0, s47
	s_nop 0
	global_load_lds_dwordx4 v176, s[98:99]
	s_waitcnt vmcnt(8)
	s_waitcnt lgkmcnt(0)
	s_barrier
	s_setprio 1
	s_waitcnt lgkmcnt(0)
	v_mfma_f32_16x16x32_bf16 v[68:71], v[56:59], v[160:163], v[68:71]
	v_mfma_f32_16x16x32_bf16 v[60:63], v[72:75], v[160:163], v[60:63]
	v_mfma_f32_16x16x32_bf16 v[44:47], v[56:59], v[168:171], v[44:47]
	v_mfma_f32_16x16x32_bf16 v[40:43], v[72:75], v[168:171], v[40:43]
	v_mfma_f32_16x16x32_bf16 v[28:31], v[56:59], v[192:195], v[28:31]
	v_mfma_f32_16x16x32_bf16 v[24:27], v[72:75], v[192:195], v[24:27]
	v_mfma_f32_16x16x32_bf16 v[12:15], v[56:59], v[208:211], v[12:15]
	v_mfma_f32_16x16x32_bf16 v[8:11], v[72:75], v[208:211], v[8:11]
	v_mfma_f32_16x16x32_bf16 v[68:71], v[64:67], v[164:167], v[68:71]
	v_mfma_f32_16x16x32_bf16 v[60:63], v[76:79], v[164:167], v[60:63]
	v_mfma_f32_16x16x32_bf16 v[44:47], v[64:67], v[188:191], v[44:47]
	v_mfma_f32_16x16x32_bf16 v[40:43], v[76:79], v[188:191], v[40:43]
	v_mfma_f32_16x16x32_bf16 v[28:31], v[64:67], v[196:199], v[28:31]
	v_mfma_f32_16x16x32_bf16 v[24:27], v[76:79], v[196:199], v[24:27]
	v_mfma_f32_16x16x32_bf16 v[12:15], v[64:67], v[212:215], v[12:15]
	v_mfma_f32_16x16x32_bf16 v[8:11], v[76:79], v[212:215], v[8:11]
	s_setprio 0
	s_setprio 1
	v_mfma_f32_16x16x32_bf16 v[52:55], v[144:147], v[160:163], v[52:55]
	v_mfma_f32_16x16x32_bf16 v[48:51], v[152:155], v[160:163], v[48:51]
	v_mfma_f32_16x16x32_bf16 v[36:39], v[144:147], v[168:171], v[36:39]
	v_mfma_f32_16x16x32_bf16 v[32:35], v[152:155], v[168:171], v[32:35]
	v_mfma_f32_16x16x32_bf16 v[20:23], v[144:147], v[192:195], v[20:23]
	v_mfma_f32_16x16x32_bf16 v[16:19], v[152:155], v[192:195], v[16:19]
	v_mfma_f32_16x16x32_bf16 v[4:7], v[144:147], v[208:211], v[4:7]
	v_mfma_f32_16x16x32_bf16 v[0:3], v[152:155], v[208:211], v[0:3]
	v_mfma_f32_16x16x32_bf16 v[52:55], v[148:151], v[164:167], v[52:55]
	v_mfma_f32_16x16x32_bf16 v[48:51], v[156:159], v[164:167], v[48:51]
	v_mfma_f32_16x16x32_bf16 v[36:39], v[148:151], v[188:191], v[36:39]
	v_mfma_f32_16x16x32_bf16 v[32:35], v[156:159], v[188:191], v[32:35]
	v_mfma_f32_16x16x32_bf16 v[20:23], v[148:151], v[196:199], v[20:23]
	v_mfma_f32_16x16x32_bf16 v[16:19], v[156:159], v[196:199], v[16:19]
	v_mfma_f32_16x16x32_bf16 v[4:7], v[148:151], v[212:215], v[4:7]
	v_mfma_f32_16x16x32_bf16 v[0:3], v[156:159], v[212:215], v[0:3]
	s_setprio 0
	s_barrier
	s_add_i32 s56, s56, 2
	s_add_u32 s34, s34, 0x100
	s_addc_u32 s35, s35, 0
	s_add_u32 s54, s54, 0x100
	s_addc_u32 s55, s55, 0
	s_cmp_gt_u32 s56, 29
	s_cbranch_scc0 .LBB0_1295
	s_and_b64 vcc, exec, s[16:17]
	s_cbranch_vccz .LBB0_1298
	s_barrier
